# code placement pin: every 32-MFMA block of the K-loops on an 8-byte boundary (one s_nop in the preceding load segment where needed), on top of the accumulate-chain MFMA order
# speedup vs baseline: 1.0023x; 1.0023x over previous
; #define PG8_STAGE(bufoff, gbase, voff) do { _Pragma("unroll") for (int _i = 0; _i < 2; ++_i) \
;         __builtin_amdgcn_global_load_lds((const unsigned*)((const char*)(gbase) + (voff)[_i]), (PG8_LAS unsigned*)(lds + (bufoff) + ldsw + _i * 8192), 16, 0, 0); } while (0)
; #define PG8_LDA(dst, b, h) do { _Pragma("unroll") for (int m = 0; m < 4; ++m) _Pragma("unroll") for (int k = 0; k < 2; ++k) dst[m][k] = *(const PG8_LAS bf16x8*)(lds + PG8_SA(b, h) + aoff + m * 2048 + k * 1024); } while (0)
; #define PG8_LDB(dst, b, h) do { _Pragma("unroll") for (int n = 0; n < 2; ++n) _Pragma("unroll") for (int k = 0; k < 2; ++k) dst[n][k] = *(const PG8_LAS bf16x8*)(lds + PG8_SB(b, h) + boff + n * 2048 + k * 1024); } while (0)
; #define PG8_WAIT_V(n) asm volatile("s_waitcnt vmcnt(" #n ")" ::: "memory")
; #define PG8_WAIT_L(n) asm volatile("s_waitcnt lgkmcnt(" #n ")" ::: "memory")
; #define PG8_BAR __builtin_amdgcn_s_barrier()
; #define PG8_SCHED __builtin_amdgcn_sched_barrier(0)
; template <class Epi, class Sched, bool ALIGN_EPI = false, bool SP2 = false>
; __device__ __forceinline__ void gemm_phase(PG8_LAS unsigned char* lds, const Gemm g, const Sched& S, const Epi& E) {
;     ...
;         const bool has_next = S.next(ui + 1, nxt);
;         const char* nA = has_next ? (const char*)g.A + (size_t)nxt.pm * tstep : cA; const char* nB = has_next ? (const char*)g.Bt + (size_t)nxt.pn * tstep : cB;
;         for (int t = 0; t < nt; t += 2) {
;             const bool last = (t == nt - 2);
;             const char* a1 = cA + (size_t)(t + 1) * kstep;
;             const char* a2 = last ? nA : cA + (size_t)(t + 2) * kstep; const char* b2 = last ? nB : cB + (size_t)(t + 2) * kstep;
;             const char* a3 = a2 + kstep; const char* b3 = b2 + kstep;
;             if (last && has_next) S.a_ready(nxt);
;             if constexpr (SP2) {
;             PG8_LDB(B0, 0, 0); PG8_LDB(B1, 0, 1); PG8_SCHED; PG8_LDA(At, 0, 0); PG8_STAGE(PG8_SA(1, 1), a1 + hstep, voffA);
;             PG8_WAIT_V(8); PG8_WAIT_L(0); PG8_BAR; PG8_MMA(0, 0, At, B0); PG8_MMA(0, 1, At, B1); PG8_BAR; PG8_SCHED;
;             PG8_LDA(At, 0, 1); PG8_STAGE(PG8_SB(0, 0), b2, voffB); PG8_STAGE(PG8_SB(0, 1), b2 + hstepB, voffB); PG8_STAGE(PG8_SA(0, 0), a2, voffA);
;             PG8_WAIT_V(8); PG8_WAIT_L(0); PG8_BAR; PG8_MMA(1, 0, At, B0); PG8_MMA(1, 1, At, B1); PG8_BAR; PG8_SCHED;
.LBB0_169:
	s_add_u32 s93, s46, 0x100
	s_addc_u32 s94, s47, 0
	s_ashr_i32 s69, s68, 31
	s_lshl_b64 s[4:5], s[68:69], 20
	s_add_u32 s76, s52, s4
	s_addc_u32 s77, s53, s5
	s_and_b64 s[4:5], s[38:39], exec
	s_cselect_b32 s4, s77, s71
	s_cselect_b32 s5, s76, s70
	s_ashr_i32 s63, s62, 31
	s_lshl_b64 s[6:7], s[62:63], 20
	v_readlane_b32 s8, v249, 19
	v_readlane_b32 s9, v249, 20
	s_add_u32 s72, s8, s6
	s_addc_u32 s73, s9, s7
	s_and_b64 s[6:7], s[38:39], exec
	s_cselect_b32 s6, s73, s47
	s_cselect_b32 s7, s72, s46
	s_add_u32 s8, s70, 0x80080
	s_addc_u32 s9, s71, 0
	v_lshl_add_u64 v[144:145], s[8:9], 0, v[140:141]
	v_lshl_add_u64 v[146:147], s[8:9], 0, v[142:143]
	s_mov_b32 s8, -2
	s_mov_b64 s[46:47], 0
	v_add_u32_e32 v186, 0x10000, v139
	v_add_u32_e32 v187, 0x14000, v139
	v_add_u32_e32 v198, 0x18000, v139
	v_add_u32_e32 v199, 0x1c000, v139
	s_add_u32 s9, s70, s46
	s_addc_u32 s10, s71, s47
	s_add_u32 s9, s9, 0x100
	s_addc_u32 s10, s10, 0
	s_add_u32 s100, s9, 0x7ff80
	s_addc_u32 s101, s10, 0
	s_add_u32 s11, s93, s46
	s_addc_u32 s12, s94, s47
	s_add_i32 s13, 0, 0x10000
	s_cmpk_eq_i32 s46, 0xf00
	s_cselect_b32 s85, s4, s10
	s_cselect_b32 s84, s5, s9
	s_cselect_b32 s81, s6, s12
	s_cselect_b32 s80, s7, s11
	s_add_i32 s9, 0, 0x14000
	ds_read_b128 v[148:151], v186
	ds_read_b128 v[152:155], v186 offset:1024
	ds_read_b128 v[156:159], v186 offset:2048
	ds_read_b128 v[160:163], v186 offset:3072
	ds_read_b128 v[166:169], v187
	ds_read_b128 v[170:173], v187 offset:1024
	ds_read_b128 v[174:177], v187 offset:2048
	ds_read_b128 v[178:181], v187 offset:3072
	s_add_i32 m0, s1, 0xc000
	ds_read_b128 v[182:185], v165
	ds_read_b128 v[206:209], v165 offset:1024
	ds_read_b128 v[210:213], v165 offset:2048
	ds_read_b128 v[214:217], v165 offset:3072
	ds_read_b128 v[218:221], v165 offset:4096
	ds_read_b128 v[236:239], v165 offset:5120
	ds_read_b128 v[240:243], v165 offset:6144
	ds_read_b128 v[244:247], v165 offset:7168
	global_load_lds_dwordx4 v140, s[100:101]
	s_add_i32 m0, s1, 0xe000
	s_nop 0
	global_load_lds_dwordx4 v142, s[100:101]
	s_waitcnt vmcnt(8)
	s_waitcnt lgkmcnt(0)
	s_barrier
	v_mfma_f32_16x16x32_bf16 v[126:129], v[148:151], v[182:185], 0
	v_mfma_f32_16x16x32_bf16 v[126:129], v[152:155], v[206:209], v[126:129]
	v_mfma_f32_16x16x32_bf16 v[118:121], v[148:151], v[210:213], 0
	v_mfma_f32_16x16x32_bf16 v[118:121], v[152:155], v[214:217], v[118:121]
	v_mfma_f32_16x16x32_bf16 v[114:117], v[156:159], v[210:213], 0
	v_mfma_f32_16x16x32_bf16 v[114:117], v[160:163], v[214:217], v[114:117]
	v_mfma_f32_16x16x32_bf16 v[122:125], v[156:159], v[182:185], 0
	v_mfma_f32_16x16x32_bf16 v[122:125], v[160:163], v[206:209], v[122:125]
	v_mfma_f32_16x16x32_bf16 v[106:109], v[156:159], v[218:221], 0
	v_mfma_f32_16x16x32_bf16 v[106:109], v[160:163], v[236:239], v[106:109]
	v_mfma_f32_16x16x32_bf16 v[98:101], v[156:159], v[240:243], 0
	v_mfma_f32_16x16x32_bf16 v[98:101], v[160:163], v[244:247], v[98:101]
	v_mfma_f32_16x16x32_bf16 v[102:105], v[148:151], v[240:243], 0
	v_mfma_f32_16x16x32_bf16 v[102:105], v[152:155], v[244:247], v[102:105]
	v_mfma_f32_16x16x32_bf16 v[110:113], v[148:151], v[218:221], 0
	v_mfma_f32_16x16x32_bf16 v[110:113], v[152:155], v[236:239], v[110:113]
	v_mfma_f32_16x16x32_bf16 v[94:97], v[166:169], v[182:185], 0
	v_mfma_f32_16x16x32_bf16 v[94:97], v[170:173], v[206:209], v[94:97]
	v_mfma_f32_16x16x32_bf16 v[86:89], v[166:169], v[210:213], 0
	v_mfma_f32_16x16x32_bf16 v[86:89], v[170:173], v[214:217], v[86:89]
	v_mfma_f32_16x16x32_bf16 v[82:85], v[174:177], v[210:213], 0
	v_mfma_f32_16x16x32_bf16 v[82:85], v[178:181], v[214:217], v[82:85]
	v_mfma_f32_16x16x32_bf16 v[90:93], v[174:177], v[182:185], 0
	v_mfma_f32_16x16x32_bf16 v[90:93], v[178:181], v[206:209], v[90:93]
	v_mfma_f32_16x16x32_bf16 v[74:77], v[174:177], v[218:221], 0
	v_mfma_f32_16x16x32_bf16 v[74:77], v[178:181], v[236:239], v[74:77]
	v_mfma_f32_16x16x32_bf16 v[66:69], v[174:177], v[240:243], 0
	v_mfma_f32_16x16x32_bf16 v[66:69], v[178:181], v[244:247], v[66:69]
	v_mfma_f32_16x16x32_bf16 v[70:73], v[166:169], v[240:243], 0
	v_mfma_f32_16x16x32_bf16 v[70:73], v[170:173], v[244:247], v[70:73]
	v_mfma_f32_16x16x32_bf16 v[78:81], v[166:169], v[218:221], 0
	v_mfma_f32_16x16x32_bf16 v[78:81], v[170:173], v[236:239], v[78:81]
	s_barrier
	s_add_i32 s10, s13, s0
	s_mov_b32 m0, s10
	ds_read_b128 v[182:185], v165 offset:16384
	ds_read_b128 v[206:209], v165 offset:17408
	ds_read_b128 v[210:213], v165 offset:18432
	ds_read_b128 v[214:217], v165 offset:19456
	ds_read_b128 v[218:221], v165 offset:20480
	ds_read_b128 v[236:239], v165 offset:21504
	ds_read_b128 v[240:243], v165 offset:22528
	ds_read_b128 v[244:247], v165 offset:23552
	global_load_lds_dwordx4 v132, s[80:81]
	s_add_i32 m0, s10, 0x2000
	s_add_u32 s10, s80, 0x20000
	s_addc_u32 s11, s81, 0
	s_add_i32 s9, s9, s0
	global_load_lds_dwordx4 v136, s[80:81]
	s_mov_b32 m0, s9
	s_nop 0
	global_load_lds_dwordx4 v132, s[10:11]
	s_add_i32 m0, s9, 0x2000
	s_nop 0
	global_load_lds_dwordx4 v136, s[10:11]
	s_mov_b32 m0, s1
	s_nop 0
	global_load_lds_dwordx4 v130, s[84:85]
	s_mov_b32 m0, s25
	s_nop 0
	global_load_lds_dwordx4 v134, s[84:85]
	s_nop 0
	s_waitcnt vmcnt(8)
	s_waitcnt lgkmcnt(0)
	s_barrier
; #define PG8_STAGE(bufoff, gbase, voff) do { _Pragma("unroll") for (int _i = 0; _i < 2; ++_i) \
;         __builtin_amdgcn_global_load_lds((const unsigned*)((const char*)(gbase) + (voff)[_i]), (PG8_LAS unsigned*)(lds + (bufoff) + ldsw + _i * 8192), 16, 0, 0); } while (0)
; #define PG8_LDA(dst, b, h) do { _Pragma("unroll") for (int m = 0; m < 4; ++m) _Pragma("unroll") for (int k = 0; k < 2; ++k) dst[m][k] = *(const PG8_LAS bf16x8*)(lds + PG8_SA(b, h) + aoff + m * 2048 + k * 1024); } while (0)
; #define PG8_LDB(dst, b, h) do { _Pragma("unroll") for (int n = 0; n < 2; ++n) _Pragma("unroll") for (int k = 0; k < 2; ++k) dst[n][k] = *(const PG8_LAS bf16x8*)(lds + PG8_SB(b, h) + boff + n * 2048 + k * 1024); } while (0)
; #define PG8_MMA(ai, bj, At, Bt) do { __builtin_amdgcn_s_setprio(1); _Pragma("unroll") for (int m = 0; m < 4; ++m) _Pragma("unroll") for (int n = 0; n < 2; ++n) _Pragma("unroll") for (int k = 0; k < 2; ++k) \
;         acc[ai][bj][m][n] = __builtin_amdgcn_mfma_f32_16x16x32_bf16(Bt[n][k], At[m][k], acc[ai][bj][m][n], 0, 0, 0); __builtin_amdgcn_s_setprio(0); } while (0)
; #define PG8_WAIT_V(n) asm volatile("s_waitcnt vmcnt(" #n ")" ::: "memory")
; #define PG8_WAIT_L(n) asm volatile("s_waitcnt lgkmcnt(" #n ")" ::: "memory")
; #define PG8_BAR __builtin_amdgcn_s_barrier()
; #define PG8_SCHED __builtin_amdgcn_sched_barrier(0)
; template <class Epi, class Sched, bool ALIGN_EPI = false, bool SP2 = false>
; __device__ __forceinline__ void gemm_phase(PG8_LAS unsigned char* lds, const Gemm g, const Sched& S, const Epi& E) {
;     ...
;             PG8_WAIT_V(8); PG8_WAIT_L(0); PG8_BAR; PG8_MMA(1, 0, At, B0); PG8_MMA(1, 1, At, B1); PG8_BAR; PG8_SCHED;
;             PG8_LDB(B0, 1, 0); PG8_LDB(B1, 1, 1); PG8_SCHED; PG8_LDA(At, 1, 0); PG8_STAGE(PG8_SA(0, 1), a2 + hstep, voffA);
;             PG8_WAIT_V(8); PG8_WAIT_L(0); PG8_BAR; PG8_MMA(0, 0, At, B0); PG8_MMA(0, 1, At, B1); PG8_BAR; PG8_SCHED;
	v_mfma_f32_16x16x32_bf16 v[62:65], v[148:151], v[182:185], 0
	v_mfma_f32_16x16x32_bf16 v[62:65], v[152:155], v[206:209], v[62:65]
	v_mfma_f32_16x16x32_bf16 v[54:57], v[148:151], v[210:213], 0
	v_mfma_f32_16x16x32_bf16 v[54:57], v[152:155], v[214:217], v[54:57]
	v_mfma_f32_16x16x32_bf16 v[50:53], v[156:159], v[210:213], 0
	v_mfma_f32_16x16x32_bf16 v[50:53], v[160:163], v[214:217], v[50:53]
	v_mfma_f32_16x16x32_bf16 v[58:61], v[156:159], v[182:185], 0
	v_mfma_f32_16x16x32_bf16 v[58:61], v[160:163], v[206:209], v[58:61]
	v_mfma_f32_16x16x32_bf16 v[42:45], v[156:159], v[218:221], 0
	v_mfma_f32_16x16x32_bf16 v[42:45], v[160:163], v[236:239], v[42:45]
	v_mfma_f32_16x16x32_bf16 v[34:37], v[156:159], v[240:243], 0
	v_mfma_f32_16x16x32_bf16 v[34:37], v[160:163], v[244:247], v[34:37]
	v_mfma_f32_16x16x32_bf16 v[38:41], v[148:151], v[240:243], 0
	v_mfma_f32_16x16x32_bf16 v[38:41], v[152:155], v[244:247], v[38:41]
	v_mfma_f32_16x16x32_bf16 v[46:49], v[148:151], v[218:221], 0
	v_mfma_f32_16x16x32_bf16 v[46:49], v[152:155], v[236:239], v[46:49]
	v_mfma_f32_16x16x32_bf16 v[30:33], v[166:169], v[182:185], 0
	v_mfma_f32_16x16x32_bf16 v[30:33], v[170:173], v[206:209], v[30:33]
	v_mfma_f32_16x16x32_bf16 v[22:25], v[166:169], v[210:213], 0
	v_mfma_f32_16x16x32_bf16 v[22:25], v[170:173], v[214:217], v[22:25]
	v_mfma_f32_16x16x32_bf16 v[18:21], v[174:177], v[210:213], 0
	v_mfma_f32_16x16x32_bf16 v[18:21], v[178:181], v[214:217], v[18:21]
	v_mfma_f32_16x16x32_bf16 v[26:29], v[174:177], v[182:185], 0
	v_mfma_f32_16x16x32_bf16 v[26:29], v[178:181], v[206:209], v[26:29]
	v_mfma_f32_16x16x32_bf16 v[10:13], v[174:177], v[218:221], 0
	v_mfma_f32_16x16x32_bf16 v[10:13], v[178:181], v[236:239], v[10:13]
	v_mfma_f32_16x16x32_bf16 v[2:5], v[174:177], v[240:243], 0
	v_mfma_f32_16x16x32_bf16 v[2:5], v[178:181], v[244:247], v[2:5]
	v_mfma_f32_16x16x32_bf16 v[6:9], v[166:169], v[240:243], 0
	v_mfma_f32_16x16x32_bf16 v[6:9], v[170:173], v[244:247], v[6:9]
	v_mfma_f32_16x16x32_bf16 v[14:17], v[166:169], v[218:221], 0
	v_mfma_f32_16x16x32_bf16 v[14:17], v[170:173], v[236:239], v[14:17]
	s_barrier
	s_add_i32 s9, 0, 0x18000
	s_add_i32 s12, 0, 0x1c000
	ds_read_b128 v[148:151], v198
	ds_read_b128 v[152:155], v198 offset:1024
	ds_read_b128 v[156:159], v198 offset:2048
	ds_read_b128 v[160:163], v198 offset:3072
	ds_read_b128 v[166:169], v199
	ds_read_b128 v[170:173], v199 offset:1024
	ds_read_b128 v[174:177], v199 offset:2048
	ds_read_b128 v[178:181], v199 offset:3072
	s_add_u32 s10, s84, 0x80000
	s_addc_u32 s11, s85, 0
	s_mov_b32 m0, s42
	ds_read_b128 v[182:185], v165 offset:32768
	ds_read_b128 v[206:209], v165 offset:33792
	ds_read_b128 v[210:213], v165 offset:34816
	ds_read_b128 v[214:217], v165 offset:35840
	ds_read_b128 v[218:221], v165 offset:36864
	ds_read_b128 v[236:239], v165 offset:37888
	ds_read_b128 v[240:243], v165 offset:38912
	ds_read_b128 v[244:247], v165 offset:39936
	global_load_lds_dwordx4 v130, s[10:11]
	s_mov_b32 m0, s51
	s_nop 0
	global_load_lds_dwordx4 v134, s[10:11]
	s_waitcnt vmcnt(8)
	s_waitcnt lgkmcnt(0)
	s_barrier
	v_mfma_f32_16x16x32_bf16 v[126:129], v[148:151], v[182:185], v[126:129]
	v_mfma_f32_16x16x32_bf16 v[126:129], v[152:155], v[206:209], v[126:129]
	v_mfma_f32_16x16x32_bf16 v[118:121], v[148:151], v[210:213], v[118:121]
	v_mfma_f32_16x16x32_bf16 v[118:121], v[152:155], v[214:217], v[118:121]
	v_mfma_f32_16x16x32_bf16 v[114:117], v[156:159], v[210:213], v[114:117]
	v_mfma_f32_16x16x32_bf16 v[114:117], v[160:163], v[214:217], v[114:117]
	v_mfma_f32_16x16x32_bf16 v[122:125], v[156:159], v[182:185], v[122:125]
	v_mfma_f32_16x16x32_bf16 v[122:125], v[160:163], v[206:209], v[122:125]
	v_mfma_f32_16x16x32_bf16 v[106:109], v[156:159], v[218:221], v[106:109]
	v_mfma_f32_16x16x32_bf16 v[106:109], v[160:163], v[236:239], v[106:109]
	v_mfma_f32_16x16x32_bf16 v[98:101], v[156:159], v[240:243], v[98:101]
	v_mfma_f32_16x16x32_bf16 v[98:101], v[160:163], v[244:247], v[98:101]
	v_mfma_f32_16x16x32_bf16 v[102:105], v[148:151], v[240:243], v[102:105]
	v_mfma_f32_16x16x32_bf16 v[102:105], v[152:155], v[244:247], v[102:105]
	v_mfma_f32_16x16x32_bf16 v[110:113], v[148:151], v[218:221], v[110:113]
	v_mfma_f32_16x16x32_bf16 v[110:113], v[152:155], v[236:239], v[110:113]
	v_mfma_f32_16x16x32_bf16 v[94:97], v[166:169], v[182:185], v[94:97]
	v_mfma_f32_16x16x32_bf16 v[94:97], v[170:173], v[206:209], v[94:97]
	v_mfma_f32_16x16x32_bf16 v[86:89], v[166:169], v[210:213], v[86:89]
	v_mfma_f32_16x16x32_bf16 v[86:89], v[170:173], v[214:217], v[86:89]
	v_mfma_f32_16x16x32_bf16 v[82:85], v[174:177], v[210:213], v[82:85]
	v_mfma_f32_16x16x32_bf16 v[82:85], v[178:181], v[214:217], v[82:85]
	v_mfma_f32_16x16x32_bf16 v[90:93], v[174:177], v[182:185], v[90:93]
	v_mfma_f32_16x16x32_bf16 v[90:93], v[178:181], v[206:209], v[90:93]
	v_mfma_f32_16x16x32_bf16 v[74:77], v[174:177], v[218:221], v[74:77]
	v_mfma_f32_16x16x32_bf16 v[74:77], v[178:181], v[236:239], v[74:77]
	v_mfma_f32_16x16x32_bf16 v[66:69], v[174:177], v[240:243], v[66:69]
	v_mfma_f32_16x16x32_bf16 v[66:69], v[178:181], v[244:247], v[66:69]
	v_mfma_f32_16x16x32_bf16 v[70:73], v[166:169], v[240:243], v[70:73]
	v_mfma_f32_16x16x32_bf16 v[70:73], v[170:173], v[244:247], v[70:73]
	v_mfma_f32_16x16x32_bf16 v[78:81], v[166:169], v[218:221], v[78:81]
	v_mfma_f32_16x16x32_bf16 v[78:81], v[170:173], v[236:239], v[78:81]
	s_barrier
; #define PG8_STAGE(bufoff, gbase, voff) do { _Pragma("unroll") for (int _i = 0; _i < 2; ++_i) \
;         __builtin_amdgcn_global_load_lds((const unsigned*)((const char*)(gbase) + (voff)[_i]), (PG8_LAS unsigned*)(lds + (bufoff) + ldsw + _i * 8192), 16, 0, 0); } while (0)
; #define PG8_LDA(dst, b, h) do { _Pragma("unroll") for (int m = 0; m < 4; ++m) _Pragma("unroll") for (int k = 0; k < 2; ++k) dst[m][k] = *(const PG8_LAS bf16x8*)(lds + PG8_SA(b, h) + aoff + m * 2048 + k * 1024); } while (0)
; #define PG8_LDB(dst, b, h) do { _Pragma("unroll") for (int n = 0; n < 2; ++n) _Pragma("unroll") for (int k = 0; k < 2; ++k) dst[n][k] = *(const PG8_LAS bf16x8*)(lds + PG8_SB(b, h) + boff + n * 2048 + k * 1024); } while (0)
; #define PG8_BAR __builtin_amdgcn_s_barrier()
; template <class Epi, class Sched, bool ALIGN_EPI = false, bool SP2 = false>
; __device__ __forceinline__ void gemm_phase(PG8_LAS unsigned char* lds, const Gemm g, const Sched& S, const Epi& E) {
;     ...
;             const bool last = (t == nt - 2);
;             const char* a1 = cA + (size_t)(t + 1) * kstep;
;             const char* a2 = last ? nA : cA + (size_t)(t + 2) * kstep; const char* b2 = last ? nB : cB + (size_t)(t + 2) * kstep;
;             const char* a3 = a2 + kstep; const char* b3 = b2 + kstep;
;             if (last && has_next) S.a_ready(nxt);
;             if constexpr (SP2) {
;             PG8_LDB(B0, 0, 0); PG8_LDB(B1, 0, 1); PG8_SCHED; PG8_LDA(At, 0, 0); PG8_STAGE(PG8_SA(1, 1), a1 + hstep, voffA);
;             PG8_WAIT_V(8); PG8_WAIT_L(0); PG8_BAR; PG8_MMA(0, 0, At, B0); PG8_MMA(0, 1, At, B1); PG8_BAR; PG8_SCHED;
;             PG8_LDA(At, 0, 1); PG8_STAGE(PG8_SB(0, 0), b2, voffB); PG8_STAGE(PG8_SB(0, 1), b2 + hstepB, voffB); PG8_STAGE(PG8_SA(0, 0), a2, voffA);
;             PG8_WAIT_V(8); PG8_WAIT_L(0); PG8_BAR; PG8_MMA(1, 0, At, B0); PG8_MMA(1, 1, At, B1); PG8_BAR; PG8_SCHED;
;             PG8_LDB(B0, 1, 0); PG8_LDB(B1, 1, 1); PG8_SCHED; PG8_LDA(At, 1, 0); PG8_STAGE(PG8_SA(0, 1), a2 + hstep, voffA);
;             PG8_WAIT_V(8); PG8_WAIT_L(0); PG8_BAR; PG8_MMA(0, 0, At, B0); PG8_MMA(0, 1, At, B1); PG8_BAR; PG8_SCHED;
;             PG8_LDA(At, 1, 1); PG8_STAGE(PG8_SB(1, 0), b3, voffB); PG8_STAGE(PG8_SB(1, 1), b3 + hstepB, voffB); PG8_STAGE(PG8_SA(1, 0), a3, voffA);
;             PG8_WAIT_V(8); PG8_WAIT_L(0); PG8_BAR; PG8_MMA(1, 0, At, B0); PG8_MMA(1, 1, At, B1); PG8_BAR; PG8_SCHED;
	s_add_i32 s9, s9, s0
	s_mov_b32 m0, s9
	ds_read_b128 v[182:185], v165 offset:49152
	ds_read_b128 v[206:209], v165 offset:50176
	ds_read_b128 v[210:213], v165 offset:51200
	ds_read_b128 v[214:217], v165 offset:52224
	ds_read_b128 v[218:221], v165 offset:53248
	ds_read_b128 v[236:239], v165 offset:54272
	ds_read_b128 v[240:243], v165 offset:55296
	ds_read_b128 v[244:247], v165 offset:56320
	s_add_u32 s100, s80, s60
	s_addc_u32 s101, s81, s61
	global_load_lds_dwordx4 v132, s[100:101]
	s_add_i32 m0, s9, 0x2000
	s_add_u32 s10, s80, 0x20080
	s_addc_u32 s11, s81, 0
	s_add_i32 s9, s12, s0
	global_load_lds_dwordx4 v136, s[100:101]
	s_mov_b32 m0, s9
	s_nop 0
	global_load_lds_dwordx4 v132, s[10:11]
	s_add_i32 m0, s9, 0x2000
	s_nop 0
	global_load_lds_dwordx4 v136, s[10:11]
	s_mov_b32 m0, s66
	s_add_u32 s100, s84, s60
	s_addc_u32 s101, s85, s61
	global_load_lds_dwordx4 v130, s[100:101]
	s_mov_b32 m0, s67
	s_nop 0
	global_load_lds_dwordx4 v134, s[100:101]
	s_waitcnt vmcnt(8)
	s_waitcnt lgkmcnt(0)
	s_barrier
	v_mfma_f32_16x16x32_bf16 v[62:65], v[148:151], v[182:185], v[62:65]
	v_mfma_f32_16x16x32_bf16 v[62:65], v[152:155], v[206:209], v[62:65]
	v_mfma_f32_16x16x32_bf16 v[54:57], v[148:151], v[210:213], v[54:57]
	v_mfma_f32_16x16x32_bf16 v[54:57], v[152:155], v[214:217], v[54:57]
	v_mfma_f32_16x16x32_bf16 v[50:53], v[156:159], v[210:213], v[50:53]
	v_mfma_f32_16x16x32_bf16 v[50:53], v[160:163], v[214:217], v[50:53]
	v_mfma_f32_16x16x32_bf16 v[58:61], v[156:159], v[182:185], v[58:61]
	v_mfma_f32_16x16x32_bf16 v[58:61], v[160:163], v[206:209], v[58:61]
	v_mfma_f32_16x16x32_bf16 v[42:45], v[156:159], v[218:221], v[42:45]
	v_mfma_f32_16x16x32_bf16 v[42:45], v[160:163], v[236:239], v[42:45]
	v_mfma_f32_16x16x32_bf16 v[34:37], v[156:159], v[240:243], v[34:37]
	v_mfma_f32_16x16x32_bf16 v[34:37], v[160:163], v[244:247], v[34:37]
	v_mfma_f32_16x16x32_bf16 v[38:41], v[148:151], v[240:243], v[38:41]
	v_mfma_f32_16x16x32_bf16 v[38:41], v[152:155], v[244:247], v[38:41]
	v_mfma_f32_16x16x32_bf16 v[46:49], v[148:151], v[218:221], v[46:49]
	v_mfma_f32_16x16x32_bf16 v[46:49], v[152:155], v[236:239], v[46:49]
	v_mfma_f32_16x16x32_bf16 v[30:33], v[166:169], v[182:185], v[30:33]
	v_mfma_f32_16x16x32_bf16 v[30:33], v[170:173], v[206:209], v[30:33]
	v_mfma_f32_16x16x32_bf16 v[22:25], v[166:169], v[210:213], v[22:25]
	v_mfma_f32_16x16x32_bf16 v[22:25], v[170:173], v[214:217], v[22:25]
	v_mfma_f32_16x16x32_bf16 v[18:21], v[174:177], v[210:213], v[18:21]
	v_mfma_f32_16x16x32_bf16 v[18:21], v[178:181], v[214:217], v[18:21]
	v_mfma_f32_16x16x32_bf16 v[26:29], v[174:177], v[182:185], v[26:29]
	v_mfma_f32_16x16x32_bf16 v[26:29], v[178:181], v[206:209], v[26:29]
	v_mfma_f32_16x16x32_bf16 v[10:13], v[174:177], v[218:221], v[10:13]
	v_mfma_f32_16x16x32_bf16 v[10:13], v[178:181], v[236:239], v[10:13]
	v_mfma_f32_16x16x32_bf16 v[2:5], v[174:177], v[240:243], v[2:5]
	v_mfma_f32_16x16x32_bf16 v[2:5], v[178:181], v[244:247], v[2:5]
	v_mfma_f32_16x16x32_bf16 v[6:9], v[166:169], v[240:243], v[6:9]
	v_mfma_f32_16x16x32_bf16 v[6:9], v[170:173], v[244:247], v[6:9]
	v_mfma_f32_16x16x32_bf16 v[14:17], v[166:169], v[218:221], v[14:17]
	v_mfma_f32_16x16x32_bf16 v[14:17], v[170:173], v[236:239], v[14:17]
	s_barrier
	s_add_i32 s8, s8, 2
	s_add_u32 s46, s46, 0x100
	s_addc_u32 s47, s47, 0
	s_cmp_gt_u32 s8, 29
.LBB0_170:
	s_add_u32 s9, s70, s46
	s_addc_u32 s10, s71, s47
	s_add_u32 s9, s9, 0x100
	s_addc_u32 s10, s10, 0
	s_add_u32 s100, s9, 0x7ff80
	s_addc_u32 s101, s10, 0
	s_add_u32 s11, s93, s46
	s_addc_u32 s12, s94, s47
	s_add_i32 s13, 0, 0x10000
	s_cmpk_eq_i32 s46, 0xf00
	s_cselect_b32 s85, s4, s10
	s_cselect_b32 s84, s5, s9
	s_cselect_b32 s81, s6, s12
	s_cselect_b32 s80, s7, s11
	s_add_i32 s9, 0, 0x14000
	ds_read_b128 v[148:151], v186
	ds_read_b128 v[152:155], v186 offset:1024
	ds_read_b128 v[156:159], v186 offset:2048
	ds_read_b128 v[160:163], v186 offset:3072
	ds_read_b128 v[166:169], v187
	ds_read_b128 v[170:173], v187 offset:1024
	ds_read_b128 v[174:177], v187 offset:2048
	ds_read_b128 v[178:181], v187 offset:3072
	s_add_i32 m0, s1, 0xc000
	ds_read_b128 v[182:185], v165
	ds_read_b128 v[206:209], v165 offset:1024
	ds_read_b128 v[210:213], v165 offset:2048
	ds_read_b128 v[214:217], v165 offset:3072
	ds_read_b128 v[218:221], v165 offset:4096
	ds_read_b128 v[236:239], v165 offset:5120
	ds_read_b128 v[240:243], v165 offset:6144
	ds_read_b128 v[244:247], v165 offset:7168
	global_load_lds_dwordx4 v140, s[100:101]
	s_add_i32 m0, s1, 0xe000
	s_nop 0
	global_load_lds_dwordx4 v142, s[100:101]
	s_nop 0
	s_waitcnt vmcnt(8)
	s_waitcnt lgkmcnt(0)
	s_barrier
; #define PG8_STAGE(bufoff, gbase, voff) do { _Pragma("unroll") for (int _i = 0; _i < 2; ++_i) \
;         __builtin_amdgcn_global_load_lds((const unsigned*)((const char*)(gbase) + (voff)[_i]), (PG8_LAS unsigned*)(lds + (bufoff) + ldsw + _i * 8192), 16, 0, 0); } while (0)
; #define PG8_LDA(dst, b, h) do { _Pragma("unroll") for (int m = 0; m < 4; ++m) _Pragma("unroll") for (int k = 0; k < 2; ++k) dst[m][k] = *(const PG8_LAS bf16x8*)(lds + PG8_SA(b, h) + aoff + m * 2048 + k * 1024); } while (0)
; #define PG8_MMA(ai, bj, At, Bt) do { __builtin_amdgcn_s_setprio(1); _Pragma("unroll") for (int m = 0; m < 4; ++m) _Pragma("unroll") for (int n = 0; n < 2; ++n) _Pragma("unroll") for (int k = 0; k < 2; ++k) \
;         acc[ai][bj][m][n] = __builtin_amdgcn_mfma_f32_16x16x32_bf16(Bt[n][k], At[m][k], acc[ai][bj][m][n], 0, 0, 0); __builtin_amdgcn_s_setprio(0); } while (0)
; #define PG8_WAIT_V(n) asm volatile("s_waitcnt vmcnt(" #n ")" ::: "memory")
; #define PG8_WAIT_L(n) asm volatile("s_waitcnt lgkmcnt(" #n ")" ::: "memory")
; #define PG8_BAR __builtin_amdgcn_s_barrier()
; #define PG8_SCHED __builtin_amdgcn_sched_barrier(0)
; template <class Epi, class Sched, bool ALIGN_EPI = false, bool SP2 = false>
; __device__ __forceinline__ void gemm_phase(PG8_LAS unsigned char* lds, const Gemm g, const Sched& S, const Epi& E) {
;     ...
;             PG8_WAIT_V(8); PG8_WAIT_L(0); PG8_BAR; PG8_MMA(0, 0, At, B0); PG8_MMA(0, 1, At, B1); PG8_BAR; PG8_SCHED;
;             PG8_LDA(At, 0, 1); PG8_STAGE(PG8_SB(0, 0), b2, voffB); PG8_STAGE(PG8_SB(0, 1), b2 + hstepB, voffB); PG8_STAGE(PG8_SA(0, 0), a2, voffA);
;             PG8_WAIT_V(8); PG8_WAIT_L(0); PG8_BAR; PG8_MMA(1, 0, At, B0); PG8_MMA(1, 1, At, B1); PG8_BAR; PG8_SCHED;
	v_mfma_f32_16x16x32_bf16 v[126:129], v[148:151], v[182:185], v[126:129]
	v_mfma_f32_16x16x32_bf16 v[126:129], v[152:155], v[206:209], v[126:129]
	v_mfma_f32_16x16x32_bf16 v[118:121], v[148:151], v[210:213], v[118:121]
	v_mfma_f32_16x16x32_bf16 v[118:121], v[152:155], v[214:217], v[118:121]
	v_mfma_f32_16x16x32_bf16 v[114:117], v[156:159], v[210:213], v[114:117]
	v_mfma_f32_16x16x32_bf16 v[114:117], v[160:163], v[214:217], v[114:117]
	v_mfma_f32_16x16x32_bf16 v[122:125], v[156:159], v[182:185], v[122:125]
	v_mfma_f32_16x16x32_bf16 v[122:125], v[160:163], v[206:209], v[122:125]
	v_mfma_f32_16x16x32_bf16 v[106:109], v[156:159], v[218:221], v[106:109]
	v_mfma_f32_16x16x32_bf16 v[106:109], v[160:163], v[236:239], v[106:109]
	v_mfma_f32_16x16x32_bf16 v[98:101], v[156:159], v[240:243], v[98:101]
	v_mfma_f32_16x16x32_bf16 v[98:101], v[160:163], v[244:247], v[98:101]
	v_mfma_f32_16x16x32_bf16 v[102:105], v[148:151], v[240:243], v[102:105]
	v_mfma_f32_16x16x32_bf16 v[102:105], v[152:155], v[244:247], v[102:105]
	v_mfma_f32_16x16x32_bf16 v[110:113], v[148:151], v[218:221], v[110:113]
	v_mfma_f32_16x16x32_bf16 v[110:113], v[152:155], v[236:239], v[110:113]
	v_mfma_f32_16x16x32_bf16 v[94:97], v[166:169], v[182:185], v[94:97]
	v_mfma_f32_16x16x32_bf16 v[94:97], v[170:173], v[206:209], v[94:97]
	v_mfma_f32_16x16x32_bf16 v[86:89], v[166:169], v[210:213], v[86:89]
	v_mfma_f32_16x16x32_bf16 v[86:89], v[170:173], v[214:217], v[86:89]
	v_mfma_f32_16x16x32_bf16 v[82:85], v[174:177], v[210:213], v[82:85]
	v_mfma_f32_16x16x32_bf16 v[82:85], v[178:181], v[214:217], v[82:85]
	v_mfma_f32_16x16x32_bf16 v[90:93], v[174:177], v[182:185], v[90:93]
	v_mfma_f32_16x16x32_bf16 v[90:93], v[178:181], v[206:209], v[90:93]
	v_mfma_f32_16x16x32_bf16 v[74:77], v[174:177], v[218:221], v[74:77]
	v_mfma_f32_16x16x32_bf16 v[74:77], v[178:181], v[236:239], v[74:77]
	v_mfma_f32_16x16x32_bf16 v[66:69], v[174:177], v[240:243], v[66:69]
	v_mfma_f32_16x16x32_bf16 v[66:69], v[178:181], v[244:247], v[66:69]
	v_mfma_f32_16x16x32_bf16 v[70:73], v[166:169], v[240:243], v[70:73]
	v_mfma_f32_16x16x32_bf16 v[70:73], v[170:173], v[244:247], v[70:73]
	v_mfma_f32_16x16x32_bf16 v[78:81], v[166:169], v[218:221], v[78:81]
	v_mfma_f32_16x16x32_bf16 v[78:81], v[170:173], v[236:239], v[78:81]
	s_barrier
	s_add_i32 s10, s13, s0
	s_mov_b32 m0, s10
	ds_read_b128 v[182:185], v165 offset:16384
	ds_read_b128 v[206:209], v165 offset:17408
	ds_read_b128 v[210:213], v165 offset:18432
	ds_read_b128 v[214:217], v165 offset:19456
	ds_read_b128 v[218:221], v165 offset:20480
	ds_read_b128 v[236:239], v165 offset:21504
	ds_read_b128 v[240:243], v165 offset:22528
	ds_read_b128 v[244:247], v165 offset:23552
	global_load_lds_dwordx4 v132, s[80:81]
	s_add_i32 m0, s10, 0x2000
	s_add_u32 s10, s80, 0x20000
	s_addc_u32 s11, s81, 0
	s_add_i32 s9, s9, s0
	global_load_lds_dwordx4 v136, s[80:81]
	s_mov_b32 m0, s9
	s_nop 0
	global_load_lds_dwordx4 v132, s[10:11]
	s_add_i32 m0, s9, 0x2000
	s_nop 0
	global_load_lds_dwordx4 v136, s[10:11]
	s_mov_b32 m0, s1
	s_nop 0
	global_load_lds_dwordx4 v130, s[84:85]
	s_mov_b32 m0, s25
	s_nop 0
	global_load_lds_dwordx4 v134, s[84:85]
	s_nop 0
	s_waitcnt vmcnt(8)
	s_waitcnt lgkmcnt(0)
	s_barrier
	v_mfma_f32_16x16x32_bf16 v[62:65], v[148:151], v[182:185], v[62:65]
	v_mfma_f32_16x16x32_bf16 v[62:65], v[152:155], v[206:209], v[62:65]
	v_mfma_f32_16x16x32_bf16 v[54:57], v[148:151], v[210:213], v[54:57]
	v_mfma_f32_16x16x32_bf16 v[54:57], v[152:155], v[214:217], v[54:57]
	v_mfma_f32_16x16x32_bf16 v[50:53], v[156:159], v[210:213], v[50:53]
	v_mfma_f32_16x16x32_bf16 v[50:53], v[160:163], v[214:217], v[50:53]
	v_mfma_f32_16x16x32_bf16 v[58:61], v[156:159], v[182:185], v[58:61]
	v_mfma_f32_16x16x32_bf16 v[58:61], v[160:163], v[206:209], v[58:61]
	v_mfma_f32_16x16x32_bf16 v[42:45], v[156:159], v[218:221], v[42:45]
	v_mfma_f32_16x16x32_bf16 v[42:45], v[160:163], v[236:239], v[42:45]
	v_mfma_f32_16x16x32_bf16 v[34:37], v[156:159], v[240:243], v[34:37]
	v_mfma_f32_16x16x32_bf16 v[34:37], v[160:163], v[244:247], v[34:37]
	v_mfma_f32_16x16x32_bf16 v[38:41], v[148:151], v[240:243], v[38:41]
	v_mfma_f32_16x16x32_bf16 v[38:41], v[152:155], v[244:247], v[38:41]
	v_mfma_f32_16x16x32_bf16 v[46:49], v[148:151], v[218:221], v[46:49]
	v_mfma_f32_16x16x32_bf16 v[46:49], v[152:155], v[236:239], v[46:49]
	v_mfma_f32_16x16x32_bf16 v[30:33], v[166:169], v[182:185], v[30:33]
	v_mfma_f32_16x16x32_bf16 v[30:33], v[170:173], v[206:209], v[30:33]
	v_mfma_f32_16x16x32_bf16 v[22:25], v[166:169], v[210:213], v[22:25]
	v_mfma_f32_16x16x32_bf16 v[22:25], v[170:173], v[214:217], v[22:25]
	v_mfma_f32_16x16x32_bf16 v[18:21], v[174:177], v[210:213], v[18:21]
	v_mfma_f32_16x16x32_bf16 v[18:21], v[178:181], v[214:217], v[18:21]
	v_mfma_f32_16x16x32_bf16 v[26:29], v[174:177], v[182:185], v[26:29]
	v_mfma_f32_16x16x32_bf16 v[26:29], v[178:181], v[206:209], v[26:29]
	v_mfma_f32_16x16x32_bf16 v[10:13], v[174:177], v[218:221], v[10:13]
	v_mfma_f32_16x16x32_bf16 v[10:13], v[178:181], v[236:239], v[10:13]
	v_mfma_f32_16x16x32_bf16 v[2:5], v[174:177], v[240:243], v[2:5]
	v_mfma_f32_16x16x32_bf16 v[2:5], v[178:181], v[244:247], v[2:5]
	v_mfma_f32_16x16x32_bf16 v[6:9], v[166:169], v[240:243], v[6:9]
	v_mfma_f32_16x16x32_bf16 v[6:9], v[170:173], v[244:247], v[6:9]
	v_mfma_f32_16x16x32_bf16 v[14:17], v[166:169], v[218:221], v[14:17]
	v_mfma_f32_16x16x32_bf16 v[14:17], v[170:173], v[236:239], v[14:17]
	s_barrier
; #define PG8_STAGE(bufoff, gbase, voff) do { _Pragma("unroll") for (int _i = 0; _i < 2; ++_i) \
;         __builtin_amdgcn_global_load_lds((const unsigned*)((const char*)(gbase) + (voff)[_i]), (PG8_LAS unsigned*)(lds + (bufoff) + ldsw + _i * 8192), 16, 0, 0); } while (0)
; #define PG8_LDA(dst, b, h) do { _Pragma("unroll") for (int m = 0; m < 4; ++m) _Pragma("unroll") for (int k = 0; k < 2; ++k) dst[m][k] = *(const PG8_LAS bf16x8*)(lds + PG8_SA(b, h) + aoff + m * 2048 + k * 1024); } while (0)
; #define PG8_LDB(dst, b, h) do { _Pragma("unroll") for (int n = 0; n < 2; ++n) _Pragma("unroll") for (int k = 0; k < 2; ++k) dst[n][k] = *(const PG8_LAS bf16x8*)(lds + PG8_SB(b, h) + boff + n * 2048 + k * 1024); } while (0)
; #define PG8_MMA(ai, bj, At, Bt) do { __builtin_amdgcn_s_setprio(1); _Pragma("unroll") for (int m = 0; m < 4; ++m) _Pragma("unroll") for (int n = 0; n < 2; ++n) _Pragma("unroll") for (int k = 0; k < 2; ++k) \
;         acc[ai][bj][m][n] = __builtin_amdgcn_mfma_f32_16x16x32_bf16(Bt[n][k], At[m][k], acc[ai][bj][m][n], 0, 0, 0); __builtin_amdgcn_s_setprio(0); } while (0)
; #define PG8_WAIT_V(n) asm volatile("s_waitcnt vmcnt(" #n ")" ::: "memory")
; #define PG8_WAIT_L(n) asm volatile("s_waitcnt lgkmcnt(" #n ")" ::: "memory")
; #define PG8_BAR __builtin_amdgcn_s_barrier()
; #define PG8_SCHED __builtin_amdgcn_sched_barrier(0)
; template <class Epi, class Sched, bool ALIGN_EPI = false, bool SP2 = false>
; __device__ __forceinline__ void gemm_phase(PG8_LAS unsigned char* lds, const Gemm g, const Sched& S, const Epi& E) {
;     ...
;             PG8_LDB(B0, 1, 0); PG8_LDB(B1, 1, 1); PG8_SCHED; PG8_LDA(At, 1, 0); PG8_STAGE(PG8_SA(0, 1), a2 + hstep, voffA);
;             PG8_WAIT_V(8); PG8_WAIT_L(0); PG8_BAR; PG8_MMA(0, 0, At, B0); PG8_MMA(0, 1, At, B1); PG8_BAR; PG8_SCHED;
;             PG8_LDA(At, 1, 1); PG8_STAGE(PG8_SB(1, 0), b3, voffB); PG8_STAGE(PG8_SB(1, 1), b3 + hstepB, voffB); PG8_STAGE(PG8_SA(1, 0), a3, voffA);
;             PG8_WAIT_V(8); PG8_WAIT_L(0); PG8_BAR; PG8_MMA(1, 0, At, B0); PG8_MMA(1, 1, At, B1); PG8_BAR; PG8_SCHED;
;     ...
;         if constexpr (ALIGN_EPI) { if (wr == 0) PG8_BAR; }
	s_add_i32 s9, 0, 0x18000
	s_add_i32 s12, 0, 0x1c000
	ds_read_b128 v[148:151], v198
	ds_read_b128 v[152:155], v198 offset:1024
	ds_read_b128 v[156:159], v198 offset:2048
	ds_read_b128 v[160:163], v198 offset:3072
	ds_read_b128 v[166:169], v199
	ds_read_b128 v[170:173], v199 offset:1024
	ds_read_b128 v[174:177], v199 offset:2048
	ds_read_b128 v[178:181], v199 offset:3072
	s_add_u32 s10, s84, 0x80000
	s_addc_u32 s11, s85, 0
	s_mov_b32 m0, s42
	ds_read_b128 v[182:185], v165 offset:32768
	ds_read_b128 v[206:209], v165 offset:33792
	ds_read_b128 v[210:213], v165 offset:34816
	ds_read_b128 v[214:217], v165 offset:35840
	ds_read_b128 v[218:221], v165 offset:36864
	ds_read_b128 v[236:239], v165 offset:37888
	ds_read_b128 v[240:243], v165 offset:38912
	ds_read_b128 v[244:247], v165 offset:39936
	global_load_lds_dwordx4 v130, s[10:11]
	s_mov_b32 m0, s51
	s_nop 0
	global_load_lds_dwordx4 v134, s[10:11]
	s_waitcnt vmcnt(8)
	s_waitcnt lgkmcnt(0)
	s_barrier
	v_mfma_f32_16x16x32_bf16 v[126:129], v[148:151], v[182:185], v[126:129]
	v_mfma_f32_16x16x32_bf16 v[126:129], v[152:155], v[206:209], v[126:129]
	v_mfma_f32_16x16x32_bf16 v[118:121], v[148:151], v[210:213], v[118:121]
	v_mfma_f32_16x16x32_bf16 v[118:121], v[152:155], v[214:217], v[118:121]
	v_mfma_f32_16x16x32_bf16 v[114:117], v[156:159], v[210:213], v[114:117]
	v_mfma_f32_16x16x32_bf16 v[114:117], v[160:163], v[214:217], v[114:117]
	v_mfma_f32_16x16x32_bf16 v[122:125], v[156:159], v[182:185], v[122:125]
	v_mfma_f32_16x16x32_bf16 v[122:125], v[160:163], v[206:209], v[122:125]
	v_mfma_f32_16x16x32_bf16 v[106:109], v[156:159], v[218:221], v[106:109]
	v_mfma_f32_16x16x32_bf16 v[106:109], v[160:163], v[236:239], v[106:109]
	v_mfma_f32_16x16x32_bf16 v[98:101], v[156:159], v[240:243], v[98:101]
	v_mfma_f32_16x16x32_bf16 v[98:101], v[160:163], v[244:247], v[98:101]
	v_mfma_f32_16x16x32_bf16 v[102:105], v[148:151], v[240:243], v[102:105]
	v_mfma_f32_16x16x32_bf16 v[102:105], v[152:155], v[244:247], v[102:105]
	v_mfma_f32_16x16x32_bf16 v[110:113], v[148:151], v[218:221], v[110:113]
	v_mfma_f32_16x16x32_bf16 v[110:113], v[152:155], v[236:239], v[110:113]
	v_mfma_f32_16x16x32_bf16 v[94:97], v[166:169], v[182:185], v[94:97]
	v_mfma_f32_16x16x32_bf16 v[94:97], v[170:173], v[206:209], v[94:97]
	v_mfma_f32_16x16x32_bf16 v[86:89], v[166:169], v[210:213], v[86:89]
	v_mfma_f32_16x16x32_bf16 v[86:89], v[170:173], v[214:217], v[86:89]
	v_mfma_f32_16x16x32_bf16 v[82:85], v[174:177], v[210:213], v[82:85]
	v_mfma_f32_16x16x32_bf16 v[82:85], v[178:181], v[214:217], v[82:85]
	v_mfma_f32_16x16x32_bf16 v[90:93], v[174:177], v[182:185], v[90:93]
	v_mfma_f32_16x16x32_bf16 v[90:93], v[178:181], v[206:209], v[90:93]
	v_mfma_f32_16x16x32_bf16 v[74:77], v[174:177], v[218:221], v[74:77]
	v_mfma_f32_16x16x32_bf16 v[74:77], v[178:181], v[236:239], v[74:77]
	v_mfma_f32_16x16x32_bf16 v[66:69], v[174:177], v[240:243], v[66:69]
	v_mfma_f32_16x16x32_bf16 v[66:69], v[178:181], v[244:247], v[66:69]
	v_mfma_f32_16x16x32_bf16 v[70:73], v[166:169], v[240:243], v[70:73]
	v_mfma_f32_16x16x32_bf16 v[70:73], v[170:173], v[244:247], v[70:73]
	v_mfma_f32_16x16x32_bf16 v[78:81], v[166:169], v[218:221], v[78:81]
	v_mfma_f32_16x16x32_bf16 v[78:81], v[170:173], v[236:239], v[78:81]
	s_barrier
	s_add_i32 s9, s9, s0
	s_mov_b32 m0, s9
	ds_read_b128 v[182:185], v165 offset:49152
	ds_read_b128 v[206:209], v165 offset:50176
	ds_read_b128 v[210:213], v165 offset:51200
	ds_read_b128 v[214:217], v165 offset:52224
	ds_read_b128 v[218:221], v165 offset:53248
	ds_read_b128 v[236:239], v165 offset:54272
	ds_read_b128 v[240:243], v165 offset:55296
	ds_read_b128 v[244:247], v165 offset:56320
	s_add_u32 s100, s80, s60
	s_addc_u32 s101, s81, s61
	global_load_lds_dwordx4 v132, s[100:101]
	s_add_i32 m0, s9, 0x2000
	s_add_u32 s10, s80, 0x20080
	s_addc_u32 s11, s81, 0
	s_add_i32 s9, s12, s0
	global_load_lds_dwordx4 v136, s[100:101]
	s_mov_b32 m0, s9
	s_nop 0
	global_load_lds_dwordx4 v132, s[10:11]
	s_add_i32 m0, s9, 0x2000
	s_nop 0
	global_load_lds_dwordx4 v136, s[10:11]
	s_mov_b32 m0, s66
	s_add_u32 s100, s84, s60
	s_addc_u32 s101, s85, s61
	global_load_lds_dwordx4 v130, s[100:101]
	s_mov_b32 m0, s67
	s_nop 0
	global_load_lds_dwordx4 v134, s[100:101]
	s_waitcnt vmcnt(8)
	s_waitcnt lgkmcnt(0)
	s_barrier
	v_mfma_f32_16x16x32_bf16 v[62:65], v[148:151], v[182:185], v[62:65]
	v_mfma_f32_16x16x32_bf16 v[62:65], v[152:155], v[206:209], v[62:65]
	v_mfma_f32_16x16x32_bf16 v[54:57], v[148:151], v[210:213], v[54:57]
	v_mfma_f32_16x16x32_bf16 v[54:57], v[152:155], v[214:217], v[54:57]
	v_mfma_f32_16x16x32_bf16 v[50:53], v[156:159], v[210:213], v[50:53]
	v_mfma_f32_16x16x32_bf16 v[50:53], v[160:163], v[214:217], v[50:53]
	v_mfma_f32_16x16x32_bf16 v[58:61], v[156:159], v[182:185], v[58:61]
	v_mfma_f32_16x16x32_bf16 v[58:61], v[160:163], v[206:209], v[58:61]
	v_mfma_f32_16x16x32_bf16 v[42:45], v[156:159], v[218:221], v[42:45]
	v_mfma_f32_16x16x32_bf16 v[42:45], v[160:163], v[236:239], v[42:45]
	v_mfma_f32_16x16x32_bf16 v[34:37], v[156:159], v[240:243], v[34:37]
	v_mfma_f32_16x16x32_bf16 v[34:37], v[160:163], v[244:247], v[34:37]
	v_mfma_f32_16x16x32_bf16 v[38:41], v[148:151], v[240:243], v[38:41]
	v_mfma_f32_16x16x32_bf16 v[38:41], v[152:155], v[244:247], v[38:41]
	v_mfma_f32_16x16x32_bf16 v[46:49], v[148:151], v[218:221], v[46:49]
	v_mfma_f32_16x16x32_bf16 v[46:49], v[152:155], v[236:239], v[46:49]
	v_mfma_f32_16x16x32_bf16 v[30:33], v[166:169], v[182:185], v[30:33]
	v_mfma_f32_16x16x32_bf16 v[30:33], v[170:173], v[206:209], v[30:33]
	v_mfma_f32_16x16x32_bf16 v[22:25], v[166:169], v[210:213], v[22:25]
	v_mfma_f32_16x16x32_bf16 v[22:25], v[170:173], v[214:217], v[22:25]
	v_mfma_f32_16x16x32_bf16 v[18:21], v[174:177], v[210:213], v[18:21]
	v_mfma_f32_16x16x32_bf16 v[18:21], v[178:181], v[214:217], v[18:21]
	v_mfma_f32_16x16x32_bf16 v[26:29], v[174:177], v[182:185], v[26:29]
	v_mfma_f32_16x16x32_bf16 v[26:29], v[178:181], v[206:209], v[26:29]
	v_mfma_f32_16x16x32_bf16 v[10:13], v[174:177], v[218:221], v[10:13]
	v_mfma_f32_16x16x32_bf16 v[10:13], v[178:181], v[236:239], v[10:13]
	v_mfma_f32_16x16x32_bf16 v[2:5], v[174:177], v[240:243], v[2:5]
	v_mfma_f32_16x16x32_bf16 v[2:5], v[178:181], v[244:247], v[2:5]
	v_mfma_f32_16x16x32_bf16 v[6:9], v[166:169], v[240:243], v[6:9]
	v_mfma_f32_16x16x32_bf16 v[6:9], v[170:173], v[244:247], v[6:9]
	v_mfma_f32_16x16x32_bf16 v[14:17], v[166:169], v[218:221], v[14:17]
	v_mfma_f32_16x16x32_bf16 v[14:17], v[170:173], v[236:239], v[14:17]
	s_barrier
	s_add_i32 s8, s8, 2
	s_add_u32 s46, s46, 0x100
	s_addc_u32 s47, s47, 0
	s_cmp_gt_u32 s8, 29
	s_cbranch_scc0 .LBB0_170
	s_and_b64 vcc, exec, s[54:55]
	s_cbranch_vccz .LBB0_173
	s_barrier

; #define PG8_STAGE(bufoff, gbase, voff) do { _Pragma("unroll") for (int _i = 0; _i < 2; ++_i) \
;         __builtin_amdgcn_global_load_lds((const unsigned*)((const char*)(gbase) + (voff)[_i]), (PG8_LAS unsigned*)(lds + (bufoff) + ldsw + _i * 8192), 16, 0, 0); } while (0)
; #define PG8_LDA(dst, b, h) do { _Pragma("unroll") for (int m = 0; m < 4; ++m) _Pragma("unroll") for (int k = 0; k < 2; ++k) dst[m][k] = *(const PG8_LAS bf16x8*)(lds + PG8_SA(b, h) + aoff + m * 2048 + k * 1024); } while (0)
; #define PG8_LDB(dst, b, h) do { _Pragma("unroll") for (int n = 0; n < 2; ++n) _Pragma("unroll") for (int k = 0; k < 2; ++k) dst[n][k] = *(const PG8_LAS bf16x8*)(lds + PG8_SB(b, h) + boff + n * 2048 + k * 1024); } while (0)
; #define PG8_WAIT_V(n) asm volatile("s_waitcnt vmcnt(" #n ")" ::: "memory")
; #define PG8_WAIT_L(n) asm volatile("s_waitcnt lgkmcnt(" #n ")" ::: "memory")
; #define PG8_BAR __builtin_amdgcn_s_barrier()
; #define PG8_SCHED __builtin_amdgcn_sched_barrier(0)
; template <class Epi, class Sched, bool ALIGN_EPI = false, bool SP2 = false>
; __device__ __forceinline__ void gemm_phase(PG8_LAS unsigned char* lds, const Gemm g, const Sched& S, const Epi& E) {
;     ...
;         const bool has_next = S.next(ui + 1, nxt);
;         const char* nA = has_next ? (const char*)g.A + (size_t)nxt.pm * tstep : cA; const char* nB = has_next ? (const char*)g.Bt + (size_t)nxt.pn * tstep : cB;
;         for (int t = 0; t < nt; t += 2) {
;             const bool last = (t == nt - 2);
;             const char* a1 = cA + (size_t)(t + 1) * kstep;
;             const char* a2 = last ? nA : cA + (size_t)(t + 2) * kstep; const char* b2 = last ? nB : cB + (size_t)(t + 2) * kstep;
;             const char* a3 = a2 + kstep; const char* b3 = b2 + kstep;
;             if (last && has_next) S.a_ready(nxt);
;             if constexpr (SP2) {
;             PG8_LDB(B0, 0, 0); PG8_LDB(B1, 0, 1); PG8_SCHED; PG8_LDA(At, 0, 0); PG8_STAGE(PG8_SA(1, 1), a1 + hstep, voffA);
;             PG8_WAIT_V(8); PG8_WAIT_L(0); PG8_BAR; PG8_MMA(0, 0, At, B0); PG8_MMA(0, 1, At, B1); PG8_BAR; PG8_SCHED;
;             PG8_LDA(At, 0, 1); PG8_STAGE(PG8_SB(0, 0), b2, voffB); PG8_STAGE(PG8_SB(0, 1), b2 + hstepB, voffB); PG8_STAGE(PG8_SA(0, 0), a2, voffA);
;             PG8_WAIT_V(8); PG8_WAIT_L(0); PG8_BAR; PG8_MMA(1, 0, At, B0); PG8_MMA(1, 1, At, B1); PG8_BAR; PG8_SCHED;
.LBB0_926:
	s_ashr_i32 s73, s72, 31
	s_lshl_b64 s[4:5], s[72:73], 20
	v_readlane_b32 s6, v249, 9
	v_readlane_b32 s7, v249, 10
	s_add_u32 s76, s6, s4
	s_addc_u32 s77, s7, s5
	s_and_b64 s[4:5], s[92:93], exec
	s_cselect_b32 s36, s77, s39
	s_cselect_b32 s37, s76, s38
	s_ashr_i32 s69, s68, 31
	s_lshl_b64 s[4:5], s[68:69], 20
	v_readlane_b32 s6, v249, 17
	v_readlane_b32 s7, v249, 18
	s_add_u32 s80, s6, s4
	s_addc_u32 s81, s7, s5
	s_and_b64 s[4:5], s[92:93], exec
	s_cselect_b32 s4, s81, s47
	s_cselect_b32 s5, s80, s46
	s_add_u32 s38, s38, 0x80080
	s_addc_u32 s39, s39, 0
	s_add_u32 s6, s46, 0x100
	v_mov_b32_e32 v2, 0
	s_addc_u32 s7, s47, 0
	s_mov_b32 s8, -2
	v_mov_b32_e32 v3, v2
	v_mov_b32_e32 v4, v2
	v_mov_b32_e32 v5, v2
	v_mov_b32_e32 v6, v2
	v_mov_b32_e32 v7, v2
	v_mov_b32_e32 v8, v2
	v_mov_b32_e32 v9, v2
	v_mov_b32_e32 v18, v2
	v_mov_b32_e32 v19, v2
	v_mov_b32_e32 v20, v2
	v_mov_b32_e32 v21, v2
	v_mov_b32_e32 v22, v2
	v_mov_b32_e32 v23, v2
	v_mov_b32_e32 v24, v2
	v_mov_b32_e32 v25, v2
	v_mov_b32_e32 v34, v2
	s_waitcnt lgkmcnt(0)
	v_add_u32_e32 v186, 0x10000, v193
	v_add_u32_e32 v187, 0x14000, v193
	v_add_u32_e32 v198, 0x18000, v193
	v_add_u32_e32 v199, 0x1c000, v193
	s_add_u32 s9, s38, 0xfff80080
	s_addc_u32 s10, s39, -1
	s_add_i32 s11, 0, 0x10000
	s_cmp_eq_u32 s8, 28
	s_cselect_b32 s95, s36, s10
	s_cselect_b32 s94, s37, s9
	s_cselect_b32 s47, s4, s7
	s_cselect_b32 s46, s5, s6
	s_add_i32 s9, 0, 0x14000
	ds_read_b128 v[66:69], v186
	ds_read_b128 v[70:73], v186 offset:1024
	ds_read_b128 v[78:81], v186 offset:2048
	ds_read_b128 v[86:89], v186 offset:3072
	ds_read_b128 v[146:149], v187
	ds_read_b128 v[150:153], v187 offset:1024
	ds_read_b128 v[154:157], v187 offset:2048
	ds_read_b128 v[158:161], v187 offset:3072
	s_add_i32 m0, s66, 0xc000
	ds_read_b128 v[162:165], v236
	ds_read_b128 v[166:169], v236 offset:1024
	ds_read_b128 v[170:173], v236 offset:2048
	ds_read_b128 v[174:177], v236 offset:3072
	ds_read_b128 v[178:181], v236 offset:4096
	ds_read_b128 v[182:185], v236 offset:5120
	ds_read_b128 v[216:219], v236 offset:6144
	ds_read_b128 v[220:223], v236 offset:7168
	global_load_lds_dwordx4 v212, s[38:39]
	s_add_i32 m0, s66, 0xe000
	s_nop 0
	global_load_lds_dwordx4 v214, s[38:39]
	s_nop 0
	s_waitcnt vmcnt(8)
	s_waitcnt lgkmcnt(0)
	s_barrier
	v_mfma_f32_16x16x32_bf16 v[142:145], v[66:69], v[162:165], 0
	v_mfma_f32_16x16x32_bf16 v[142:145], v[70:73], v[166:169], v[142:145]
	v_mfma_f32_16x16x32_bf16 v[126:129], v[66:69], v[170:173], 0
	v_mfma_f32_16x16x32_bf16 v[126:129], v[70:73], v[174:177], v[126:129]
	v_mfma_f32_16x16x32_bf16 v[122:125], v[78:81], v[170:173], 0
	v_mfma_f32_16x16x32_bf16 v[122:125], v[86:89], v[174:177], v[122:125]
	v_mfma_f32_16x16x32_bf16 v[138:141], v[78:81], v[162:165], 0
	v_mfma_f32_16x16x32_bf16 v[138:141], v[86:89], v[166:169], v[138:141]
	v_mfma_f32_16x16x32_bf16 v[106:109], v[78:81], v[178:181], 0
	v_mfma_f32_16x16x32_bf16 v[106:109], v[86:89], v[182:185], v[106:109]
	v_mfma_f32_16x16x32_bf16 v[90:93], v[78:81], v[216:219], 0
	v_mfma_f32_16x16x32_bf16 v[90:93], v[86:89], v[220:223], v[90:93]
	v_mfma_f32_16x16x32_bf16 v[94:97], v[66:69], v[216:219], 0
	v_mfma_f32_16x16x32_bf16 v[94:97], v[70:73], v[220:223], v[94:97]
	v_mfma_f32_16x16x32_bf16 v[110:113], v[66:69], v[178:181], 0
	v_mfma_f32_16x16x32_bf16 v[110:113], v[70:73], v[182:185], v[110:113]
	v_mfma_f32_16x16x32_bf16 v[134:137], v[146:149], v[162:165], 0
	v_mfma_f32_16x16x32_bf16 v[134:137], v[150:153], v[166:169], v[134:137]
	v_mfma_f32_16x16x32_bf16 v[118:121], v[146:149], v[170:173], 0
	v_mfma_f32_16x16x32_bf16 v[118:121], v[150:153], v[174:177], v[118:121]
	v_mfma_f32_16x16x32_bf16 v[114:117], v[154:157], v[170:173], 0
	v_mfma_f32_16x16x32_bf16 v[114:117], v[158:161], v[174:177], v[114:117]
	v_mfma_f32_16x16x32_bf16 v[130:133], v[154:157], v[162:165], 0
	v_mfma_f32_16x16x32_bf16 v[130:133], v[158:161], v[166:169], v[130:133]
	v_mfma_f32_16x16x32_bf16 v[98:101], v[154:157], v[178:181], 0
	v_mfma_f32_16x16x32_bf16 v[98:101], v[158:161], v[182:185], v[98:101]
	v_mfma_f32_16x16x32_bf16 v[74:77], v[154:157], v[216:219], 0
	v_mfma_f32_16x16x32_bf16 v[74:77], v[158:161], v[220:223], v[74:77]
	v_mfma_f32_16x16x32_bf16 v[82:85], v[146:149], v[216:219], 0
	v_mfma_f32_16x16x32_bf16 v[82:85], v[150:153], v[220:223], v[82:85]
	v_mfma_f32_16x16x32_bf16 v[102:105], v[146:149], v[178:181], 0
	v_mfma_f32_16x16x32_bf16 v[102:105], v[150:153], v[182:185], v[102:105]
	s_barrier
	s_add_i32 s10, s11, s25
	s_mov_b32 m0, s10
	ds_read_b128 v[162:165], v236 offset:16384
	ds_read_b128 v[166:169], v236 offset:17408
	ds_read_b128 v[170:173], v236 offset:18432
	ds_read_b128 v[174:177], v236 offset:19456
	ds_read_b128 v[178:181], v236 offset:20480
	ds_read_b128 v[182:185], v236 offset:21504
	ds_read_b128 v[216:219], v236 offset:22528
	ds_read_b128 v[220:223], v236 offset:23552
	global_load_lds_dwordx4 v190, s[46:47]
	s_add_i32 m0, s10, 0x2000
	s_add_u32 s10, s46, 0x20000
	s_addc_u32 s11, s47, 0
	s_add_i32 s9, s9, s25
	global_load_lds_dwordx4 v206, s[46:47]
	s_mov_b32 m0, s9
	s_nop 0
	global_load_lds_dwordx4 v190, s[10:11]
	s_add_i32 m0, s9, 0x2000
	s_nop 0
	global_load_lds_dwordx4 v206, s[10:11]
	s_mov_b32 m0, s66
	s_nop 0
	global_load_lds_dwordx4 v210, s[94:95]
	s_mov_b32 m0, s67
	s_nop 0
	global_load_lds_dwordx4 v208, s[94:95]
	s_nop 0
	s_waitcnt vmcnt(8)
	s_waitcnt lgkmcnt(0)
	s_barrier
; #define PG8_STAGE(bufoff, gbase, voff) do { _Pragma("unroll") for (int _i = 0; _i < 2; ++_i) \
;         __builtin_amdgcn_global_load_lds((const unsigned*)((const char*)(gbase) + (voff)[_i]), (PG8_LAS unsigned*)(lds + (bufoff) + ldsw + _i * 8192), 16, 0, 0); } while (0)
; #define PG8_LDA(dst, b, h) do { _Pragma("unroll") for (int m = 0; m < 4; ++m) _Pragma("unroll") for (int k = 0; k < 2; ++k) dst[m][k] = *(const PG8_LAS bf16x8*)(lds + PG8_SA(b, h) + aoff + m * 2048 + k * 1024); } while (0)
; #define PG8_LDB(dst, b, h) do { _Pragma("unroll") for (int n = 0; n < 2; ++n) _Pragma("unroll") for (int k = 0; k < 2; ++k) dst[n][k] = *(const PG8_LAS bf16x8*)(lds + PG8_SB(b, h) + boff + n * 2048 + k * 1024); } while (0)
; #define PG8_MMA(ai, bj, At, Bt) do { __builtin_amdgcn_s_setprio(1); _Pragma("unroll") for (int m = 0; m < 4; ++m) _Pragma("unroll") for (int n = 0; n < 2; ++n) _Pragma("unroll") for (int k = 0; k < 2; ++k) \
;         acc[ai][bj][m][n] = __builtin_amdgcn_mfma_f32_16x16x32_bf16(Bt[n][k], At[m][k], acc[ai][bj][m][n], 0, 0, 0); __builtin_amdgcn_s_setprio(0); } while (0)
; #define PG8_WAIT_V(n) asm volatile("s_waitcnt vmcnt(" #n ")" ::: "memory")
; #define PG8_WAIT_L(n) asm volatile("s_waitcnt lgkmcnt(" #n ")" ::: "memory")
; #define PG8_BAR __builtin_amdgcn_s_barrier()
; #define PG8_SCHED __builtin_amdgcn_sched_barrier(0)
; template <class Epi, class Sched, bool ALIGN_EPI = false, bool SP2 = false>
; __device__ __forceinline__ void gemm_phase(PG8_LAS unsigned char* lds, const Gemm g, const Sched& S, const Epi& E) {
;     ...
;             PG8_WAIT_V(8); PG8_WAIT_L(0); PG8_BAR; PG8_MMA(1, 0, At, B0); PG8_MMA(1, 1, At, B1); PG8_BAR; PG8_SCHED;
;             PG8_LDB(B0, 1, 0); PG8_LDB(B1, 1, 1); PG8_SCHED; PG8_LDA(At, 1, 0); PG8_STAGE(PG8_SA(0, 1), a2 + hstep, voffA);
;             PG8_WAIT_V(8); PG8_WAIT_L(0); PG8_BAR; PG8_MMA(0, 0, At, B0); PG8_MMA(0, 1, At, B1); PG8_BAR; PG8_SCHED;
	v_mfma_f32_16x16x32_bf16 v[62:65], v[66:69], v[162:165], 0
	v_mfma_f32_16x16x32_bf16 v[62:65], v[70:73], v[166:169], v[62:65]
	v_mfma_f32_16x16x32_bf16 v[46:49], v[66:69], v[170:173], 0
	v_mfma_f32_16x16x32_bf16 v[46:49], v[70:73], v[174:177], v[46:49]
	v_mfma_f32_16x16x32_bf16 v[42:45], v[78:81], v[170:173], 0
	v_mfma_f32_16x16x32_bf16 v[42:45], v[86:89], v[174:177], v[42:45]
	v_mfma_f32_16x16x32_bf16 v[58:61], v[78:81], v[162:165], 0
	v_mfma_f32_16x16x32_bf16 v[58:61], v[86:89], v[166:169], v[58:61]
	v_mfma_f32_16x16x32_bf16 v[26:29], v[78:81], v[178:181], 0
	v_mfma_f32_16x16x32_bf16 v[26:29], v[86:89], v[182:185], v[26:29]
	v_mfma_f32_16x16x32_bf16 v[10:13], v[78:81], v[216:219], 0
	v_mfma_f32_16x16x32_bf16 v[10:13], v[86:89], v[220:223], v[10:13]
	v_mfma_f32_16x16x32_bf16 v[14:17], v[66:69], v[216:219], 0
	v_mfma_f32_16x16x32_bf16 v[14:17], v[70:73], v[220:223], v[14:17]
	v_mfma_f32_16x16x32_bf16 v[30:33], v[66:69], v[178:181], 0
	v_mfma_f32_16x16x32_bf16 v[30:33], v[70:73], v[182:185], v[30:33]
	v_mfma_f32_16x16x32_bf16 v[54:57], v[146:149], v[162:165], 0
	v_mfma_f32_16x16x32_bf16 v[54:57], v[150:153], v[166:169], v[54:57]
	v_mfma_f32_16x16x32_bf16 v[38:41], v[146:149], v[170:173], 0
	v_mfma_f32_16x16x32_bf16 v[38:41], v[150:153], v[174:177], v[38:41]
	v_mfma_f32_16x16x32_bf16 v[34:37], v[154:157], v[170:173], 0
	v_mfma_f32_16x16x32_bf16 v[34:37], v[158:161], v[174:177], v[34:37]
	v_mfma_f32_16x16x32_bf16 v[50:53], v[154:157], v[162:165], 0
	v_mfma_f32_16x16x32_bf16 v[50:53], v[158:161], v[166:169], v[50:53]
	v_mfma_f32_16x16x32_bf16 v[18:21], v[154:157], v[178:181], 0
	v_mfma_f32_16x16x32_bf16 v[18:21], v[158:161], v[182:185], v[18:21]
	v_mfma_f32_16x16x32_bf16 v[2:5], v[154:157], v[216:219], 0
	v_mfma_f32_16x16x32_bf16 v[2:5], v[158:161], v[220:223], v[2:5]
	v_mfma_f32_16x16x32_bf16 v[6:9], v[146:149], v[216:219], 0
	v_mfma_f32_16x16x32_bf16 v[6:9], v[150:153], v[220:223], v[6:9]
	v_mfma_f32_16x16x32_bf16 v[22:25], v[146:149], v[178:181], 0
	v_mfma_f32_16x16x32_bf16 v[22:25], v[150:153], v[182:185], v[22:25]
	s_barrier
	s_add_i32 s9, 0, 0x18000
	s_add_i32 s12, 0, 0x1c000
	ds_read_b128 v[66:69], v198
	ds_read_b128 v[70:73], v198 offset:1024
	ds_read_b128 v[78:81], v198 offset:2048
	ds_read_b128 v[86:89], v198 offset:3072
	ds_read_b128 v[146:149], v199
	ds_read_b128 v[150:153], v199 offset:1024
	ds_read_b128 v[154:157], v199 offset:2048
	ds_read_b128 v[158:161], v199 offset:3072
	s_add_u32 s10, s94, 0x80000
	s_addc_u32 s11, s95, 0
	s_mov_b32 m0, s59
	ds_read_b128 v[162:165], v236 offset:32768
	ds_read_b128 v[166:169], v236 offset:33792
	ds_read_b128 v[170:173], v236 offset:34816
	ds_read_b128 v[174:177], v236 offset:35840
	ds_read_b128 v[178:181], v236 offset:36864
	ds_read_b128 v[182:185], v236 offset:37888
	ds_read_b128 v[216:219], v236 offset:38912
	ds_read_b128 v[220:223], v236 offset:39936
	global_load_lds_dwordx4 v210, s[10:11]
	s_mov_b32 m0, s74
	s_nop 0
	global_load_lds_dwordx4 v208, s[10:11]
	s_waitcnt vmcnt(8)
	s_waitcnt lgkmcnt(0)
	s_barrier
	v_mfma_f32_16x16x32_bf16 v[142:145], v[66:69], v[162:165], v[142:145]
	v_mfma_f32_16x16x32_bf16 v[142:145], v[70:73], v[166:169], v[142:145]
	v_mfma_f32_16x16x32_bf16 v[126:129], v[66:69], v[170:173], v[126:129]
	v_mfma_f32_16x16x32_bf16 v[126:129], v[70:73], v[174:177], v[126:129]
	v_mfma_f32_16x16x32_bf16 v[122:125], v[78:81], v[170:173], v[122:125]
	v_mfma_f32_16x16x32_bf16 v[122:125], v[86:89], v[174:177], v[122:125]
	v_mfma_f32_16x16x32_bf16 v[138:141], v[78:81], v[162:165], v[138:141]
	v_mfma_f32_16x16x32_bf16 v[138:141], v[86:89], v[166:169], v[138:141]
	v_mfma_f32_16x16x32_bf16 v[106:109], v[78:81], v[178:181], v[106:109]
	v_mfma_f32_16x16x32_bf16 v[106:109], v[86:89], v[182:185], v[106:109]
	v_mfma_f32_16x16x32_bf16 v[90:93], v[78:81], v[216:219], v[90:93]
	v_mfma_f32_16x16x32_bf16 v[90:93], v[86:89], v[220:223], v[90:93]
	v_mfma_f32_16x16x32_bf16 v[94:97], v[66:69], v[216:219], v[94:97]
	v_mfma_f32_16x16x32_bf16 v[94:97], v[70:73], v[220:223], v[94:97]
	v_mfma_f32_16x16x32_bf16 v[110:113], v[66:69], v[178:181], v[110:113]
	v_mfma_f32_16x16x32_bf16 v[110:113], v[70:73], v[182:185], v[110:113]
	v_mfma_f32_16x16x32_bf16 v[134:137], v[146:149], v[162:165], v[134:137]
	v_mfma_f32_16x16x32_bf16 v[134:137], v[150:153], v[166:169], v[134:137]
	v_mfma_f32_16x16x32_bf16 v[118:121], v[146:149], v[170:173], v[118:121]
	v_mfma_f32_16x16x32_bf16 v[118:121], v[150:153], v[174:177], v[118:121]
	v_mfma_f32_16x16x32_bf16 v[114:117], v[154:157], v[170:173], v[114:117]
	v_mfma_f32_16x16x32_bf16 v[114:117], v[158:161], v[174:177], v[114:117]
	v_mfma_f32_16x16x32_bf16 v[130:133], v[154:157], v[162:165], v[130:133]
	v_mfma_f32_16x16x32_bf16 v[130:133], v[158:161], v[166:169], v[130:133]
	v_mfma_f32_16x16x32_bf16 v[98:101], v[154:157], v[178:181], v[98:101]
	v_mfma_f32_16x16x32_bf16 v[98:101], v[158:161], v[182:185], v[98:101]
	v_mfma_f32_16x16x32_bf16 v[74:77], v[154:157], v[216:219], v[74:77]
	v_mfma_f32_16x16x32_bf16 v[74:77], v[158:161], v[220:223], v[74:77]
	v_mfma_f32_16x16x32_bf16 v[82:85], v[146:149], v[216:219], v[82:85]
	v_mfma_f32_16x16x32_bf16 v[82:85], v[150:153], v[220:223], v[82:85]
	v_mfma_f32_16x16x32_bf16 v[102:105], v[146:149], v[178:181], v[102:105]
	v_mfma_f32_16x16x32_bf16 v[102:105], v[150:153], v[182:185], v[102:105]
	s_barrier
; #define PG8_STAGE(bufoff, gbase, voff) do { _Pragma("unroll") for (int _i = 0; _i < 2; ++_i) \
;         __builtin_amdgcn_global_load_lds((const unsigned*)((const char*)(gbase) + (voff)[_i]), (PG8_LAS unsigned*)(lds + (bufoff) + ldsw + _i * 8192), 16, 0, 0); } while (0)
; #define PG8_LDA(dst, b, h) do { _Pragma("unroll") for (int m = 0; m < 4; ++m) _Pragma("unroll") for (int k = 0; k < 2; ++k) dst[m][k] = *(const PG8_LAS bf16x8*)(lds + PG8_SA(b, h) + aoff + m * 2048 + k * 1024); } while (0)
; #define PG8_LDB(dst, b, h) do { _Pragma("unroll") for (int n = 0; n < 2; ++n) _Pragma("unroll") for (int k = 0; k < 2; ++k) dst[n][k] = *(const PG8_LAS bf16x8*)(lds + PG8_SB(b, h) + boff + n * 2048 + k * 1024); } while (0)
; #define PG8_BAR __builtin_amdgcn_s_barrier()
; template <class Epi, class Sched, bool ALIGN_EPI = false, bool SP2 = false>
; __device__ __forceinline__ void gemm_phase(PG8_LAS unsigned char* lds, const Gemm g, const Sched& S, const Epi& E) {
;     ...
;             const bool last = (t == nt - 2);
;             const char* a1 = cA + (size_t)(t + 1) * kstep;
;             const char* a2 = last ? nA : cA + (size_t)(t + 2) * kstep; const char* b2 = last ? nB : cB + (size_t)(t + 2) * kstep;
;             const char* a3 = a2 + kstep; const char* b3 = b2 + kstep;
;             if (last && has_next) S.a_ready(nxt);
;             if constexpr (SP2) {
;             PG8_LDB(B0, 0, 0); PG8_LDB(B1, 0, 1); PG8_SCHED; PG8_LDA(At, 0, 0); PG8_STAGE(PG8_SA(1, 1), a1 + hstep, voffA);
;             PG8_WAIT_V(8); PG8_WAIT_L(0); PG8_BAR; PG8_MMA(0, 0, At, B0); PG8_MMA(0, 1, At, B1); PG8_BAR; PG8_SCHED;
;             PG8_LDA(At, 0, 1); PG8_STAGE(PG8_SB(0, 0), b2, voffB); PG8_STAGE(PG8_SB(0, 1), b2 + hstepB, voffB); PG8_STAGE(PG8_SA(0, 0), a2, voffA);
;             PG8_WAIT_V(8); PG8_WAIT_L(0); PG8_BAR; PG8_MMA(1, 0, At, B0); PG8_MMA(1, 1, At, B1); PG8_BAR; PG8_SCHED;
;             PG8_LDB(B0, 1, 0); PG8_LDB(B1, 1, 1); PG8_SCHED; PG8_LDA(At, 1, 0); PG8_STAGE(PG8_SA(0, 1), a2 + hstep, voffA);
;             PG8_WAIT_V(8); PG8_WAIT_L(0); PG8_BAR; PG8_MMA(0, 0, At, B0); PG8_MMA(0, 1, At, B1); PG8_BAR; PG8_SCHED;
;             PG8_LDA(At, 1, 1); PG8_STAGE(PG8_SB(1, 0), b3, voffB); PG8_STAGE(PG8_SB(1, 1), b3 + hstepB, voffB); PG8_STAGE(PG8_SA(1, 0), a3, voffA);
;             PG8_WAIT_V(8); PG8_WAIT_L(0); PG8_BAR; PG8_MMA(1, 0, At, B0); PG8_MMA(1, 1, At, B1); PG8_BAR; PG8_SCHED;
	s_add_i32 s9, s9, s25
	s_mov_b32 m0, s9
	ds_read_b128 v[162:165], v236 offset:49152
	ds_read_b128 v[166:169], v236 offset:50176
	ds_read_b128 v[170:173], v236 offset:51200
	ds_read_b128 v[174:177], v236 offset:52224
	ds_read_b128 v[178:181], v236 offset:53248
	ds_read_b128 v[182:185], v236 offset:54272
	ds_read_b128 v[216:219], v236 offset:55296
	ds_read_b128 v[220:223], v236 offset:56320
	s_add_u32 s100, s46, s60
	s_addc_u32 s101, s47, s61
	global_load_lds_dwordx4 v190, s[100:101]
	s_add_i32 m0, s9, 0x2000
	s_add_u32 s10, s46, 0x20080
	s_addc_u32 s11, s47, 0
	s_add_i32 s9, s12, s25
	global_load_lds_dwordx4 v206, s[100:101]
	s_mov_b32 m0, s9
	s_nop 0
	global_load_lds_dwordx4 v190, s[10:11]
	s_add_i32 m0, s9, 0x2000
	s_nop 0
	global_load_lds_dwordx4 v206, s[10:11]
	s_mov_b32 m0, s75
	s_add_u32 s100, s94, s60
	s_addc_u32 s101, s95, s61
	global_load_lds_dwordx4 v210, s[100:101]
	s_mov_b32 m0, s0
	s_nop 0
	global_load_lds_dwordx4 v208, s[100:101]
	s_waitcnt vmcnt(8)
	s_waitcnt lgkmcnt(0)
	s_barrier
	v_mfma_f32_16x16x32_bf16 v[62:65], v[66:69], v[162:165], v[62:65]
	v_mfma_f32_16x16x32_bf16 v[62:65], v[70:73], v[166:169], v[62:65]
	v_mfma_f32_16x16x32_bf16 v[46:49], v[66:69], v[170:173], v[46:49]
	v_mfma_f32_16x16x32_bf16 v[46:49], v[70:73], v[174:177], v[46:49]
	v_mfma_f32_16x16x32_bf16 v[42:45], v[78:81], v[170:173], v[42:45]
	v_mfma_f32_16x16x32_bf16 v[42:45], v[86:89], v[174:177], v[42:45]
	v_mfma_f32_16x16x32_bf16 v[58:61], v[78:81], v[162:165], v[58:61]
	v_mfma_f32_16x16x32_bf16 v[58:61], v[86:89], v[166:169], v[58:61]
	v_mfma_f32_16x16x32_bf16 v[26:29], v[78:81], v[178:181], v[26:29]
	v_mfma_f32_16x16x32_bf16 v[26:29], v[86:89], v[182:185], v[26:29]
	v_mfma_f32_16x16x32_bf16 v[10:13], v[78:81], v[216:219], v[10:13]
	v_mfma_f32_16x16x32_bf16 v[10:13], v[86:89], v[220:223], v[10:13]
	v_mfma_f32_16x16x32_bf16 v[14:17], v[66:69], v[216:219], v[14:17]
	v_mfma_f32_16x16x32_bf16 v[14:17], v[70:73], v[220:223], v[14:17]
	v_mfma_f32_16x16x32_bf16 v[30:33], v[66:69], v[178:181], v[30:33]
	v_mfma_f32_16x16x32_bf16 v[30:33], v[70:73], v[182:185], v[30:33]
	v_mfma_f32_16x16x32_bf16 v[54:57], v[146:149], v[162:165], v[54:57]
	v_mfma_f32_16x16x32_bf16 v[54:57], v[150:153], v[166:169], v[54:57]
	v_mfma_f32_16x16x32_bf16 v[38:41], v[146:149], v[170:173], v[38:41]
	v_mfma_f32_16x16x32_bf16 v[38:41], v[150:153], v[174:177], v[38:41]
	v_mfma_f32_16x16x32_bf16 v[34:37], v[154:157], v[170:173], v[34:37]
	v_mfma_f32_16x16x32_bf16 v[34:37], v[158:161], v[174:177], v[34:37]
	v_mfma_f32_16x16x32_bf16 v[50:53], v[154:157], v[162:165], v[50:53]
	v_mfma_f32_16x16x32_bf16 v[50:53], v[158:161], v[166:169], v[50:53]
	v_mfma_f32_16x16x32_bf16 v[18:21], v[154:157], v[178:181], v[18:21]
	v_mfma_f32_16x16x32_bf16 v[18:21], v[158:161], v[182:185], v[18:21]
	v_mfma_f32_16x16x32_bf16 v[2:5], v[154:157], v[216:219], v[2:5]
	v_mfma_f32_16x16x32_bf16 v[2:5], v[158:161], v[220:223], v[2:5]
	v_mfma_f32_16x16x32_bf16 v[6:9], v[146:149], v[216:219], v[6:9]
	v_mfma_f32_16x16x32_bf16 v[6:9], v[150:153], v[220:223], v[6:9]
	v_mfma_f32_16x16x32_bf16 v[22:25], v[146:149], v[178:181], v[22:25]
	v_mfma_f32_16x16x32_bf16 v[22:25], v[150:153], v[182:185], v[22:25]
	s_barrier
	s_add_i32 s8, s8, 2
	s_add_u32 s38, s38, 0x100
	s_addc_u32 s39, s39, 0
	s_add_u32 s6, s6, 0x100
	s_addc_u32 s7, s7, 0
	s_cmp_gt_u32 s8, 29
.LBB0_927:
	s_add_u32 s9, s38, 0xfff80080
	s_addc_u32 s10, s39, -1
	s_add_i32 s11, 0, 0x10000
	s_cmp_eq_u32 s8, 28
	s_cselect_b32 s95, s36, s10
	s_cselect_b32 s94, s37, s9
	s_cselect_b32 s47, s4, s7
	s_cselect_b32 s46, s5, s6
	s_add_i32 s9, 0, 0x14000
	ds_read_b128 v[66:69], v186
	ds_read_b128 v[70:73], v186 offset:1024
	ds_read_b128 v[78:81], v186 offset:2048
	ds_read_b128 v[86:89], v186 offset:3072
	ds_read_b128 v[146:149], v187
	ds_read_b128 v[150:153], v187 offset:1024
	ds_read_b128 v[154:157], v187 offset:2048
	ds_read_b128 v[158:161], v187 offset:3072
	s_add_i32 m0, s66, 0xc000
	ds_read_b128 v[162:165], v236
	ds_read_b128 v[166:169], v236 offset:1024
	ds_read_b128 v[170:173], v236 offset:2048
	ds_read_b128 v[174:177], v236 offset:3072
	ds_read_b128 v[178:181], v236 offset:4096
	ds_read_b128 v[182:185], v236 offset:5120
	ds_read_b128 v[216:219], v236 offset:6144
	ds_read_b128 v[220:223], v236 offset:7168
	global_load_lds_dwordx4 v212, s[38:39]
	s_add_i32 m0, s66, 0xe000
	s_nop 0
	global_load_lds_dwordx4 v214, s[38:39]
	s_nop 0
	s_waitcnt vmcnt(8)
	s_waitcnt lgkmcnt(0)
	s_barrier
	v_mfma_f32_16x16x32_bf16 v[142:145], v[66:69], v[162:165], v[142:145]
	v_mfma_f32_16x16x32_bf16 v[142:145], v[70:73], v[166:169], v[142:145]
	v_mfma_f32_16x16x32_bf16 v[126:129], v[66:69], v[170:173], v[126:129]
	v_mfma_f32_16x16x32_bf16 v[126:129], v[70:73], v[174:177], v[126:129]
	v_mfma_f32_16x16x32_bf16 v[122:125], v[78:81], v[170:173], v[122:125]
	v_mfma_f32_16x16x32_bf16 v[122:125], v[86:89], v[174:177], v[122:125]
	v_mfma_f32_16x16x32_bf16 v[138:141], v[78:81], v[162:165], v[138:141]
	v_mfma_f32_16x16x32_bf16 v[138:141], v[86:89], v[166:169], v[138:141]
	v_mfma_f32_16x16x32_bf16 v[106:109], v[78:81], v[178:181], v[106:109]
	v_mfma_f32_16x16x32_bf16 v[106:109], v[86:89], v[182:185], v[106:109]
	v_mfma_f32_16x16x32_bf16 v[90:93], v[78:81], v[216:219], v[90:93]
	v_mfma_f32_16x16x32_bf16 v[90:93], v[86:89], v[220:223], v[90:93]
	v_mfma_f32_16x16x32_bf16 v[94:97], v[66:69], v[216:219], v[94:97]
	v_mfma_f32_16x16x32_bf16 v[94:97], v[70:73], v[220:223], v[94:97]
	v_mfma_f32_16x16x32_bf16 v[110:113], v[66:69], v[178:181], v[110:113]
	v_mfma_f32_16x16x32_bf16 v[110:113], v[70:73], v[182:185], v[110:113]
	v_mfma_f32_16x16x32_bf16 v[134:137], v[146:149], v[162:165], v[134:137]
	v_mfma_f32_16x16x32_bf16 v[134:137], v[150:153], v[166:169], v[134:137]
	v_mfma_f32_16x16x32_bf16 v[118:121], v[146:149], v[170:173], v[118:121]
	v_mfma_f32_16x16x32_bf16 v[118:121], v[150:153], v[174:177], v[118:121]
	v_mfma_f32_16x16x32_bf16 v[114:117], v[154:157], v[170:173], v[114:117]
	v_mfma_f32_16x16x32_bf16 v[114:117], v[158:161], v[174:177], v[114:117]
	v_mfma_f32_16x16x32_bf16 v[130:133], v[154:157], v[162:165], v[130:133]
	v_mfma_f32_16x16x32_bf16 v[130:133], v[158:161], v[166:169], v[130:133]
	v_mfma_f32_16x16x32_bf16 v[98:101], v[154:157], v[178:181], v[98:101]
	v_mfma_f32_16x16x32_bf16 v[98:101], v[158:161], v[182:185], v[98:101]
	v_mfma_f32_16x16x32_bf16 v[74:77], v[154:157], v[216:219], v[74:77]
	v_mfma_f32_16x16x32_bf16 v[74:77], v[158:161], v[220:223], v[74:77]
	v_mfma_f32_16x16x32_bf16 v[82:85], v[146:149], v[216:219], v[82:85]
	v_mfma_f32_16x16x32_bf16 v[82:85], v[150:153], v[220:223], v[82:85]
	v_mfma_f32_16x16x32_bf16 v[102:105], v[146:149], v[178:181], v[102:105]
	v_mfma_f32_16x16x32_bf16 v[102:105], v[150:153], v[182:185], v[102:105]
	s_barrier
; #define PG8_STAGE(bufoff, gbase, voff) do { _Pragma("unroll") for (int _i = 0; _i < 2; ++_i) \
;         __builtin_amdgcn_global_load_lds((const unsigned*)((const char*)(gbase) + (voff)[_i]), (PG8_LAS unsigned*)(lds + (bufoff) + ldsw + _i * 8192), 16, 0, 0); } while (0)
; #define PG8_LDA(dst, b, h) do { _Pragma("unroll") for (int m = 0; m < 4; ++m) _Pragma("unroll") for (int k = 0; k < 2; ++k) dst[m][k] = *(const PG8_LAS bf16x8*)(lds + PG8_SA(b, h) + aoff + m * 2048 + k * 1024); } while (0)
; #define PG8_LDB(dst, b, h) do { _Pragma("unroll") for (int n = 0; n < 2; ++n) _Pragma("unroll") for (int k = 0; k < 2; ++k) dst[n][k] = *(const PG8_LAS bf16x8*)(lds + PG8_SB(b, h) + boff + n * 2048 + k * 1024); } while (0)
; #define PG8_MMA(ai, bj, At, Bt) do { __builtin_amdgcn_s_setprio(1); _Pragma("unroll") for (int m = 0; m < 4; ++m) _Pragma("unroll") for (int n = 0; n < 2; ++n) _Pragma("unroll") for (int k = 0; k < 2; ++k) \
;         acc[ai][bj][m][n] = __builtin_amdgcn_mfma_f32_16x16x32_bf16(Bt[n][k], At[m][k], acc[ai][bj][m][n], 0, 0, 0); __builtin_amdgcn_s_setprio(0); } while (0)
; #define PG8_WAIT_V(n) asm volatile("s_waitcnt vmcnt(" #n ")" ::: "memory")
; #define PG8_WAIT_L(n) asm volatile("s_waitcnt lgkmcnt(" #n ")" ::: "memory")
; #define PG8_BAR __builtin_amdgcn_s_barrier()
; #define PG8_SCHED __builtin_amdgcn_sched_barrier(0)
; template <class Epi, class Sched, bool ALIGN_EPI = false, bool SP2 = false>
; __device__ __forceinline__ void gemm_phase(PG8_LAS unsigned char* lds, const Gemm g, const Sched& S, const Epi& E) {
;     ...
;             PG8_LDA(At, 0, 1); PG8_STAGE(PG8_SB(0, 0), b2, voffB); PG8_STAGE(PG8_SB(0, 1), b2 + hstepB, voffB); PG8_STAGE(PG8_SA(0, 0), a2, voffA);
;             PG8_WAIT_V(8); PG8_WAIT_L(0); PG8_BAR; PG8_MMA(1, 0, At, B0); PG8_MMA(1, 1, At, B1); PG8_BAR; PG8_SCHED;
;             PG8_LDB(B0, 1, 0); PG8_LDB(B1, 1, 1); PG8_SCHED; PG8_LDA(At, 1, 0); PG8_STAGE(PG8_SA(0, 1), a2 + hstep, voffA);
;             PG8_WAIT_V(8); PG8_WAIT_L(0); PG8_BAR; PG8_MMA(0, 0, At, B0); PG8_MMA(0, 1, At, B1); PG8_BAR; PG8_SCHED;
	s_add_i32 s10, s11, s25
	s_mov_b32 m0, s10
	ds_read_b128 v[162:165], v236 offset:16384
	ds_read_b128 v[166:169], v236 offset:17408
	ds_read_b128 v[170:173], v236 offset:18432
	ds_read_b128 v[174:177], v236 offset:19456
	ds_read_b128 v[178:181], v236 offset:20480
	ds_read_b128 v[182:185], v236 offset:21504
	ds_read_b128 v[216:219], v236 offset:22528
	ds_read_b128 v[220:223], v236 offset:23552
	global_load_lds_dwordx4 v190, s[46:47]
	s_add_i32 m0, s10, 0x2000
	s_add_u32 s10, s46, 0x20000
	s_addc_u32 s11, s47, 0
	s_add_i32 s9, s9, s25
	global_load_lds_dwordx4 v206, s[46:47]
	s_mov_b32 m0, s9
	s_nop 0
	global_load_lds_dwordx4 v190, s[10:11]
	s_add_i32 m0, s9, 0x2000
	s_nop 0
	global_load_lds_dwordx4 v206, s[10:11]
	s_mov_b32 m0, s66
	s_nop 0
	global_load_lds_dwordx4 v210, s[94:95]
	s_mov_b32 m0, s67
	s_nop 0
	global_load_lds_dwordx4 v208, s[94:95]
	s_nop 0
	s_waitcnt vmcnt(8)
	s_waitcnt lgkmcnt(0)
	s_barrier
	v_mfma_f32_16x16x32_bf16 v[62:65], v[66:69], v[162:165], v[62:65]
	v_mfma_f32_16x16x32_bf16 v[62:65], v[70:73], v[166:169], v[62:65]
	v_mfma_f32_16x16x32_bf16 v[46:49], v[66:69], v[170:173], v[46:49]
	v_mfma_f32_16x16x32_bf16 v[46:49], v[70:73], v[174:177], v[46:49]
	v_mfma_f32_16x16x32_bf16 v[42:45], v[78:81], v[170:173], v[42:45]
	v_mfma_f32_16x16x32_bf16 v[42:45], v[86:89], v[174:177], v[42:45]
	v_mfma_f32_16x16x32_bf16 v[58:61], v[78:81], v[162:165], v[58:61]
	v_mfma_f32_16x16x32_bf16 v[58:61], v[86:89], v[166:169], v[58:61]
	v_mfma_f32_16x16x32_bf16 v[26:29], v[78:81], v[178:181], v[26:29]
	v_mfma_f32_16x16x32_bf16 v[26:29], v[86:89], v[182:185], v[26:29]
	v_mfma_f32_16x16x32_bf16 v[10:13], v[78:81], v[216:219], v[10:13]
	v_mfma_f32_16x16x32_bf16 v[10:13], v[86:89], v[220:223], v[10:13]
	v_mfma_f32_16x16x32_bf16 v[14:17], v[66:69], v[216:219], v[14:17]
	v_mfma_f32_16x16x32_bf16 v[14:17], v[70:73], v[220:223], v[14:17]
	v_mfma_f32_16x16x32_bf16 v[30:33], v[66:69], v[178:181], v[30:33]
	v_mfma_f32_16x16x32_bf16 v[30:33], v[70:73], v[182:185], v[30:33]
	v_mfma_f32_16x16x32_bf16 v[54:57], v[146:149], v[162:165], v[54:57]
	v_mfma_f32_16x16x32_bf16 v[54:57], v[150:153], v[166:169], v[54:57]
	v_mfma_f32_16x16x32_bf16 v[38:41], v[146:149], v[170:173], v[38:41]
	v_mfma_f32_16x16x32_bf16 v[38:41], v[150:153], v[174:177], v[38:41]
	v_mfma_f32_16x16x32_bf16 v[34:37], v[154:157], v[170:173], v[34:37]
	v_mfma_f32_16x16x32_bf16 v[34:37], v[158:161], v[174:177], v[34:37]
	v_mfma_f32_16x16x32_bf16 v[50:53], v[154:157], v[162:165], v[50:53]
	v_mfma_f32_16x16x32_bf16 v[50:53], v[158:161], v[166:169], v[50:53]
	v_mfma_f32_16x16x32_bf16 v[18:21], v[154:157], v[178:181], v[18:21]
	v_mfma_f32_16x16x32_bf16 v[18:21], v[158:161], v[182:185], v[18:21]
	v_mfma_f32_16x16x32_bf16 v[2:5], v[154:157], v[216:219], v[2:5]
	v_mfma_f32_16x16x32_bf16 v[2:5], v[158:161], v[220:223], v[2:5]
	v_mfma_f32_16x16x32_bf16 v[6:9], v[146:149], v[216:219], v[6:9]
	v_mfma_f32_16x16x32_bf16 v[6:9], v[150:153], v[220:223], v[6:9]
	v_mfma_f32_16x16x32_bf16 v[22:25], v[146:149], v[178:181], v[22:25]
	v_mfma_f32_16x16x32_bf16 v[22:25], v[150:153], v[182:185], v[22:25]
	s_barrier
	s_add_i32 s9, 0, 0x18000
	s_add_i32 s12, 0, 0x1c000
	ds_read_b128 v[66:69], v198
	ds_read_b128 v[70:73], v198 offset:1024
	ds_read_b128 v[78:81], v198 offset:2048
	ds_read_b128 v[86:89], v198 offset:3072
	ds_read_b128 v[146:149], v199
	ds_read_b128 v[150:153], v199 offset:1024
	ds_read_b128 v[154:157], v199 offset:2048
	ds_read_b128 v[158:161], v199 offset:3072
	s_add_u32 s10, s94, 0x80000
	s_addc_u32 s11, s95, 0
	s_mov_b32 m0, s59
	ds_read_b128 v[162:165], v236 offset:32768
	ds_read_b128 v[166:169], v236 offset:33792
	ds_read_b128 v[170:173], v236 offset:34816
	ds_read_b128 v[174:177], v236 offset:35840
	ds_read_b128 v[178:181], v236 offset:36864
	ds_read_b128 v[182:185], v236 offset:37888
	ds_read_b128 v[216:219], v236 offset:38912
	ds_read_b128 v[220:223], v236 offset:39936
	global_load_lds_dwordx4 v210, s[10:11]
	s_mov_b32 m0, s74
	s_nop 0
	global_load_lds_dwordx4 v208, s[10:11]
	s_waitcnt vmcnt(8)
	s_waitcnt lgkmcnt(0)
	s_barrier
; #define PG8_STAGE(bufoff, gbase, voff) do { _Pragma("unroll") for (int _i = 0; _i < 2; ++_i) \
;         __builtin_amdgcn_global_load_lds((const unsigned*)((const char*)(gbase) + (voff)[_i]), (PG8_LAS unsigned*)(lds + (bufoff) + ldsw + _i * 8192), 16, 0, 0); } while (0)
; #define PG8_LDA(dst, b, h) do { _Pragma("unroll") for (int m = 0; m < 4; ++m) _Pragma("unroll") for (int k = 0; k < 2; ++k) dst[m][k] = *(const PG8_LAS bf16x8*)(lds + PG8_SA(b, h) + aoff + m * 2048 + k * 1024); } while (0)
; #define PG8_MMA(ai, bj, At, Bt) do { __builtin_amdgcn_s_setprio(1); _Pragma("unroll") for (int m = 0; m < 4; ++m) _Pragma("unroll") for (int n = 0; n < 2; ++n) _Pragma("unroll") for (int k = 0; k < 2; ++k) \
;         acc[ai][bj][m][n] = __builtin_amdgcn_mfma_f32_16x16x32_bf16(Bt[n][k], At[m][k], acc[ai][bj][m][n], 0, 0, 0); __builtin_amdgcn_s_setprio(0); } while (0)
; #define PG8_WAIT_V(n) asm volatile("s_waitcnt vmcnt(" #n ")" ::: "memory")
; #define PG8_WAIT_L(n) asm volatile("s_waitcnt lgkmcnt(" #n ")" ::: "memory")
; #define PG8_BAR __builtin_amdgcn_s_barrier()
; #define PG8_SCHED __builtin_amdgcn_sched_barrier(0)
; template <class Epi, class Sched, bool ALIGN_EPI = false, bool SP2 = false>
; __device__ __forceinline__ void gemm_phase(PG8_LAS unsigned char* lds, const Gemm g, const Sched& S, const Epi& E) {
;     ...
;             PG8_WAIT_V(8); PG8_WAIT_L(0); PG8_BAR; PG8_MMA(0, 0, At, B0); PG8_MMA(0, 1, At, B1); PG8_BAR; PG8_SCHED;
;             PG8_LDA(At, 1, 1); PG8_STAGE(PG8_SB(1, 0), b3, voffB); PG8_STAGE(PG8_SB(1, 1), b3 + hstepB, voffB); PG8_STAGE(PG8_SA(1, 0), a3, voffA);
;             PG8_WAIT_V(8); PG8_WAIT_L(0); PG8_BAR; PG8_MMA(1, 0, At, B0); PG8_MMA(1, 1, At, B1); PG8_BAR; PG8_SCHED;
;     ...
;         if constexpr (ALIGN_EPI) { if (wr == 0) PG8_BAR; }
	v_mfma_f32_16x16x32_bf16 v[142:145], v[66:69], v[162:165], v[142:145]
	v_mfma_f32_16x16x32_bf16 v[142:145], v[70:73], v[166:169], v[142:145]
	v_mfma_f32_16x16x32_bf16 v[126:129], v[66:69], v[170:173], v[126:129]
	v_mfma_f32_16x16x32_bf16 v[126:129], v[70:73], v[174:177], v[126:129]
	v_mfma_f32_16x16x32_bf16 v[122:125], v[78:81], v[170:173], v[122:125]
	v_mfma_f32_16x16x32_bf16 v[122:125], v[86:89], v[174:177], v[122:125]
	v_mfma_f32_16x16x32_bf16 v[138:141], v[78:81], v[162:165], v[138:141]
	v_mfma_f32_16x16x32_bf16 v[138:141], v[86:89], v[166:169], v[138:141]
	v_mfma_f32_16x16x32_bf16 v[106:109], v[78:81], v[178:181], v[106:109]
	v_mfma_f32_16x16x32_bf16 v[106:109], v[86:89], v[182:185], v[106:109]
	v_mfma_f32_16x16x32_bf16 v[90:93], v[78:81], v[216:219], v[90:93]
	v_mfma_f32_16x16x32_bf16 v[90:93], v[86:89], v[220:223], v[90:93]
	v_mfma_f32_16x16x32_bf16 v[94:97], v[66:69], v[216:219], v[94:97]
	v_mfma_f32_16x16x32_bf16 v[94:97], v[70:73], v[220:223], v[94:97]
	v_mfma_f32_16x16x32_bf16 v[110:113], v[66:69], v[178:181], v[110:113]
	v_mfma_f32_16x16x32_bf16 v[110:113], v[70:73], v[182:185], v[110:113]
	v_mfma_f32_16x16x32_bf16 v[134:137], v[146:149], v[162:165], v[134:137]
	v_mfma_f32_16x16x32_bf16 v[134:137], v[150:153], v[166:169], v[134:137]
	v_mfma_f32_16x16x32_bf16 v[118:121], v[146:149], v[170:173], v[118:121]
	v_mfma_f32_16x16x32_bf16 v[118:121], v[150:153], v[174:177], v[118:121]
	v_mfma_f32_16x16x32_bf16 v[114:117], v[154:157], v[170:173], v[114:117]
	v_mfma_f32_16x16x32_bf16 v[114:117], v[158:161], v[174:177], v[114:117]
	v_mfma_f32_16x16x32_bf16 v[130:133], v[154:157], v[162:165], v[130:133]
	v_mfma_f32_16x16x32_bf16 v[130:133], v[158:161], v[166:169], v[130:133]
	v_mfma_f32_16x16x32_bf16 v[98:101], v[154:157], v[178:181], v[98:101]
	v_mfma_f32_16x16x32_bf16 v[98:101], v[158:161], v[182:185], v[98:101]
	v_mfma_f32_16x16x32_bf16 v[74:77], v[154:157], v[216:219], v[74:77]
	v_mfma_f32_16x16x32_bf16 v[74:77], v[158:161], v[220:223], v[74:77]
	v_mfma_f32_16x16x32_bf16 v[82:85], v[146:149], v[216:219], v[82:85]
	v_mfma_f32_16x16x32_bf16 v[82:85], v[150:153], v[220:223], v[82:85]
	v_mfma_f32_16x16x32_bf16 v[102:105], v[146:149], v[178:181], v[102:105]
	v_mfma_f32_16x16x32_bf16 v[102:105], v[150:153], v[182:185], v[102:105]
	s_barrier
	s_add_i32 s9, s9, s25
	s_mov_b32 m0, s9
	ds_read_b128 v[162:165], v236 offset:49152
	ds_read_b128 v[166:169], v236 offset:50176
	ds_read_b128 v[170:173], v236 offset:51200
	ds_read_b128 v[174:177], v236 offset:52224
	ds_read_b128 v[178:181], v236 offset:53248
	ds_read_b128 v[182:185], v236 offset:54272
	ds_read_b128 v[216:219], v236 offset:55296
	ds_read_b128 v[220:223], v236 offset:56320
	s_add_u32 s100, s46, s60
	s_addc_u32 s101, s47, s61
	global_load_lds_dwordx4 v190, s[100:101]
	s_add_i32 m0, s9, 0x2000
	s_add_u32 s10, s46, 0x20080
	s_addc_u32 s11, s47, 0
	s_add_i32 s9, s12, s25
	global_load_lds_dwordx4 v206, s[100:101]
	s_mov_b32 m0, s9
	s_nop 0
	global_load_lds_dwordx4 v190, s[10:11]
	s_add_i32 m0, s9, 0x2000
	s_nop 0
	global_load_lds_dwordx4 v206, s[10:11]
	s_mov_b32 m0, s75
	s_add_u32 s100, s94, s60
	s_addc_u32 s101, s95, s61
	global_load_lds_dwordx4 v210, s[100:101]
	s_mov_b32 m0, s0
	s_nop 0
	global_load_lds_dwordx4 v208, s[100:101]
	s_waitcnt vmcnt(8)
	s_waitcnt lgkmcnt(0)
	s_barrier
	v_mfma_f32_16x16x32_bf16 v[62:65], v[66:69], v[162:165], v[62:65]
	v_mfma_f32_16x16x32_bf16 v[62:65], v[70:73], v[166:169], v[62:65]
	v_mfma_f32_16x16x32_bf16 v[46:49], v[66:69], v[170:173], v[46:49]
	v_mfma_f32_16x16x32_bf16 v[46:49], v[70:73], v[174:177], v[46:49]
	v_mfma_f32_16x16x32_bf16 v[42:45], v[78:81], v[170:173], v[42:45]
	v_mfma_f32_16x16x32_bf16 v[42:45], v[86:89], v[174:177], v[42:45]
	v_mfma_f32_16x16x32_bf16 v[58:61], v[78:81], v[162:165], v[58:61]
	v_mfma_f32_16x16x32_bf16 v[58:61], v[86:89], v[166:169], v[58:61]
	v_mfma_f32_16x16x32_bf16 v[26:29], v[78:81], v[178:181], v[26:29]
	v_mfma_f32_16x16x32_bf16 v[26:29], v[86:89], v[182:185], v[26:29]
	v_mfma_f32_16x16x32_bf16 v[10:13], v[78:81], v[216:219], v[10:13]
	v_mfma_f32_16x16x32_bf16 v[10:13], v[86:89], v[220:223], v[10:13]
	v_mfma_f32_16x16x32_bf16 v[14:17], v[66:69], v[216:219], v[14:17]
	v_mfma_f32_16x16x32_bf16 v[14:17], v[70:73], v[220:223], v[14:17]
	v_mfma_f32_16x16x32_bf16 v[30:33], v[66:69], v[178:181], v[30:33]
	v_mfma_f32_16x16x32_bf16 v[30:33], v[70:73], v[182:185], v[30:33]
	v_mfma_f32_16x16x32_bf16 v[54:57], v[146:149], v[162:165], v[54:57]
	v_mfma_f32_16x16x32_bf16 v[54:57], v[150:153], v[166:169], v[54:57]
	v_mfma_f32_16x16x32_bf16 v[38:41], v[146:149], v[170:173], v[38:41]
	v_mfma_f32_16x16x32_bf16 v[38:41], v[150:153], v[174:177], v[38:41]
	v_mfma_f32_16x16x32_bf16 v[34:37], v[154:157], v[170:173], v[34:37]
	v_mfma_f32_16x16x32_bf16 v[34:37], v[158:161], v[174:177], v[34:37]
	v_mfma_f32_16x16x32_bf16 v[50:53], v[154:157], v[162:165], v[50:53]
	v_mfma_f32_16x16x32_bf16 v[50:53], v[158:161], v[166:169], v[50:53]
	v_mfma_f32_16x16x32_bf16 v[18:21], v[154:157], v[178:181], v[18:21]
	v_mfma_f32_16x16x32_bf16 v[18:21], v[158:161], v[182:185], v[18:21]
	v_mfma_f32_16x16x32_bf16 v[2:5], v[154:157], v[216:219], v[2:5]
	v_mfma_f32_16x16x32_bf16 v[2:5], v[158:161], v[220:223], v[2:5]
	v_mfma_f32_16x16x32_bf16 v[6:9], v[146:149], v[216:219], v[6:9]
	v_mfma_f32_16x16x32_bf16 v[6:9], v[150:153], v[220:223], v[6:9]
	v_mfma_f32_16x16x32_bf16 v[22:25], v[146:149], v[178:181], v[22:25]
	v_mfma_f32_16x16x32_bf16 v[22:25], v[150:153], v[182:185], v[22:25]
	s_barrier
	s_add_i32 s8, s8, 2
	s_add_u32 s38, s38, 0x100
	s_addc_u32 s39, s39, 0
	s_add_u32 s6, s6, 0x100
	s_addc_u32 s7, s7, 0
	s_cmp_gt_u32 s8, 29
	s_cbranch_scc0 .LBB0_927
	s_and_b64 vcc, exec, s[70:71]
	s_cbranch_vccz .LBB0_930
	s_barrier

; #define PG8_STAGE(bufoff, gbase, voff) do { _Pragma("unroll") for (int _i = 0; _i < 2; ++_i) \
;         __builtin_amdgcn_global_load_lds((const unsigned*)((const char*)(gbase) + (voff)[_i]), (PG8_LAS unsigned*)(lds + (bufoff) + ldsw + _i * 8192), 16, 0, 0); } while (0)
; #define PG8_LDA(dst, b, h) do { _Pragma("unroll") for (int m = 0; m < 4; ++m) _Pragma("unroll") for (int k = 0; k < 2; ++k) dst[m][k] = *(const PG8_LAS bf16x8*)(lds + PG8_SA(b, h) + aoff + m * 2048 + k * 1024); } while (0)
; #define PG8_LDB(dst, b, h) do { _Pragma("unroll") for (int n = 0; n < 2; ++n) _Pragma("unroll") for (int k = 0; k < 2; ++k) dst[n][k] = *(const PG8_LAS bf16x8*)(lds + PG8_SB(b, h) + boff + n * 2048 + k * 1024); } while (0)
; #define PG8_WAIT_V(n) asm volatile("s_waitcnt vmcnt(" #n ")" ::: "memory")
; #define PG8_WAIT_L(n) asm volatile("s_waitcnt lgkmcnt(" #n ")" ::: "memory")
; #define PG8_BAR __builtin_amdgcn_s_barrier()
; #define PG8_SCHED __builtin_amdgcn_sched_barrier(0)
; template <class Epi, class Sched, bool ALIGN_EPI = false, bool SP2 = false>
; __device__ __forceinline__ void gemm_phase(PG8_LAS unsigned char* lds, const Gemm g, const Sched& S, const Epi& E) {
;     ...
;         const bool has_next = S.next(ui + 1, nxt);
;         const char* nA = has_next ? (const char*)g.A + (size_t)nxt.pm * tstep : cA; const char* nB = has_next ? (const char*)g.Bt + (size_t)nxt.pn * tstep : cB;
;         for (int t = 0; t < nt; t += 2) {
;             const bool last = (t == nt - 2);
;             const char* a1 = cA + (size_t)(t + 1) * kstep;
;             const char* a2 = last ? nA : cA + (size_t)(t + 2) * kstep; const char* b2 = last ? nB : cB + (size_t)(t + 2) * kstep;
;             const char* a3 = a2 + kstep; const char* b3 = b2 + kstep;
;             if (last && has_next) S.a_ready(nxt);
;             if constexpr (SP2) {
;             PG8_LDB(B0, 0, 0); PG8_LDB(B1, 0, 1); PG8_SCHED; PG8_LDA(At, 0, 0); PG8_STAGE(PG8_SA(1, 1), a1 + hstep, voffA);
;             PG8_WAIT_V(8); PG8_WAIT_L(0); PG8_BAR; PG8_MMA(0, 0, At, B0); PG8_MMA(0, 1, At, B1); PG8_BAR; PG8_SCHED;
;             PG8_LDA(At, 0, 1); PG8_STAGE(PG8_SB(0, 0), b2, voffB); PG8_STAGE(PG8_SB(0, 1), b2 + hstepB, voffB); PG8_STAGE(PG8_SA(0, 0), a2, voffA);
;             PG8_WAIT_V(8); PG8_WAIT_L(0); PG8_BAR; PG8_MMA(1, 0, At, B0); PG8_MMA(1, 1, At, B1); PG8_BAR; PG8_SCHED;
.LBB0_1070:
	s_ashr_i32 s97, s96, 31
	s_lshl_b64 s[4:5], s[96:97], 22
	s_add_u32 s26, s0, s4
	s_addc_u32 s27, s1, s5
	s_and_b64 s[4:5], s[92:93], exec
	s_cselect_b32 s97, s27, s39
	s_cselect_b32 s4, s26, s38
	s_ashr_i32 s85, s84, 31
	s_lshl_b64 s[6:7], s[84:85], 22
	s_add_u32 s94, s56, s6
	s_addc_u32 s95, s57, s7
	s_and_b64 s[6:7], s[92:93], exec
	s_cselect_b32 s5, s95, s47
	s_cselect_b32 s6, s94, s46
	s_add_u32 s38, s38, 0x200080
	s_addc_u32 s39, s39, 0
	s_add_u32 s7, s46, 0x100
	s_addc_u32 s8, s47, 0
	s_mov_b32 s9, -2
	s_waitcnt lgkmcnt(0)
	v_add_u32_e32 v186, 0x10000, v164
	v_add_u32_e32 v187, 0x14000, v164
	v_add_u32_e32 v198, 0x18000, v164
	v_add_u32_e32 v199, 0x1c000, v164
	s_add_u32 s10, s38, 0xffe00080
	s_addc_u32 s11, s39, -1
	s_add_i32 s12, 0, 0x10000
	s_cmpk_eq_i32 s9, 0x7c
	s_cselect_b32 vcc_hi, s97, s11
	s_cselect_b32 vcc_lo, s4, s10
	s_cselect_b32 s47, s5, s8
	s_cselect_b32 s46, s6, s7
	s_add_i32 s13, 0, 0x14000
	ds_read_b128 v[130:133], v186
	ds_read_b128 v[134:137], v186 offset:1024
	ds_read_b128 v[138:141], v186 offset:2048
	ds_read_b128 v[152:155], v186 offset:3072
	ds_read_b128 v[156:159], v187
	ds_read_b128 v[160:163], v187 offset:1024
	ds_read_b128 v[168:171], v187 offset:2048
	ds_read_b128 v[172:175], v187 offset:3072
	s_add_i32 m0, s74, 0xc000
	ds_read_b128 v[176:179], v166
	ds_read_b128 v[180:183], v166 offset:1024
	ds_read_b128 v[206:209], v166 offset:2048
	ds_read_b128 v[210:213], v166 offset:3072
	ds_read_b128 v[214:217], v166 offset:4096
	ds_read_b128 v[218:221], v166 offset:5120
	ds_read_b128 v[236:239], v166 offset:6144
	ds_read_b128 v[240:243], v166 offset:7168
	global_load_lds_dwordx4 v148, s[38:39]
	s_add_i32 m0, s74, 0xe000
	s_nop 0
	global_load_lds_dwordx4 v150, s[38:39]
	s_nop 0
	s_waitcnt vmcnt(8)
	s_waitcnt lgkmcnt(0)
	s_barrier
	v_mfma_f32_16x16x32_bf16 v[126:129], v[130:133], v[176:179], 0
	v_mfma_f32_16x16x32_bf16 v[126:129], v[134:137], v[180:183], v[126:129]
	v_mfma_f32_16x16x32_bf16 v[110:113], v[130:133], v[206:209], 0
	v_mfma_f32_16x16x32_bf16 v[110:113], v[134:137], v[210:213], v[110:113]
	v_mfma_f32_16x16x32_bf16 v[106:109], v[138:141], v[206:209], 0
	v_mfma_f32_16x16x32_bf16 v[106:109], v[152:155], v[210:213], v[106:109]
	v_mfma_f32_16x16x32_bf16 v[122:125], v[138:141], v[176:179], 0
	v_mfma_f32_16x16x32_bf16 v[122:125], v[152:155], v[180:183], v[122:125]
	v_mfma_f32_16x16x32_bf16 v[90:93], v[138:141], v[214:217], 0
	v_mfma_f32_16x16x32_bf16 v[90:93], v[152:155], v[218:221], v[90:93]
	v_mfma_f32_16x16x32_bf16 v[74:77], v[138:141], v[236:239], 0
	v_mfma_f32_16x16x32_bf16 v[74:77], v[152:155], v[240:243], v[74:77]
	v_mfma_f32_16x16x32_bf16 v[78:81], v[130:133], v[236:239], 0
	v_mfma_f32_16x16x32_bf16 v[78:81], v[134:137], v[240:243], v[78:81]
	v_mfma_f32_16x16x32_bf16 v[94:97], v[130:133], v[214:217], 0
	v_mfma_f32_16x16x32_bf16 v[94:97], v[134:137], v[218:221], v[94:97]
	v_mfma_f32_16x16x32_bf16 v[118:121], v[156:159], v[176:179], 0
	v_mfma_f32_16x16x32_bf16 v[118:121], v[160:163], v[180:183], v[118:121]
	v_mfma_f32_16x16x32_bf16 v[102:105], v[156:159], v[206:209], 0
	v_mfma_f32_16x16x32_bf16 v[102:105], v[160:163], v[210:213], v[102:105]
	v_mfma_f32_16x16x32_bf16 v[98:101], v[168:171], v[206:209], 0
	v_mfma_f32_16x16x32_bf16 v[98:101], v[172:175], v[210:213], v[98:101]
	v_mfma_f32_16x16x32_bf16 v[114:117], v[168:171], v[176:179], 0
	v_mfma_f32_16x16x32_bf16 v[114:117], v[172:175], v[180:183], v[114:117]
	v_mfma_f32_16x16x32_bf16 v[82:85], v[168:171], v[214:217], 0
	v_mfma_f32_16x16x32_bf16 v[82:85], v[172:175], v[218:221], v[82:85]
	v_mfma_f32_16x16x32_bf16 v[66:69], v[168:171], v[236:239], 0
	v_mfma_f32_16x16x32_bf16 v[66:69], v[172:175], v[240:243], v[66:69]
	v_mfma_f32_16x16x32_bf16 v[70:73], v[156:159], v[236:239], 0
	v_mfma_f32_16x16x32_bf16 v[70:73], v[160:163], v[240:243], v[70:73]
	v_mfma_f32_16x16x32_bf16 v[86:89], v[156:159], v[214:217], 0
	v_mfma_f32_16x16x32_bf16 v[86:89], v[160:163], v[218:221], v[86:89]
	s_barrier
	s_add_i32 s10, s12, s67
	s_mov_b32 m0, s10
	ds_read_b128 v[176:179], v166 offset:16384
	ds_read_b128 v[180:183], v166 offset:17408
	ds_read_b128 v[206:209], v166 offset:18432
	ds_read_b128 v[210:213], v166 offset:19456
	ds_read_b128 v[214:217], v166 offset:20480
	ds_read_b128 v[218:221], v166 offset:21504
	ds_read_b128 v[236:239], v166 offset:22528
	ds_read_b128 v[240:243], v166 offset:23552
	global_load_lds_dwordx4 v146, s[46:47]
	s_add_i32 m0, s10, 0x2000
	s_add_u32 s10, s46, 0x80000
	s_addc_u32 s11, s47, 0
	s_add_i32 s12, s13, s67
	global_load_lds_dwordx4 v142, s[46:47]
	s_mov_b32 m0, s12
	s_nop 0
	global_load_lds_dwordx4 v146, s[10:11]
	s_add_i32 m0, s12, 0x2000
	s_nop 0
	global_load_lds_dwordx4 v142, s[10:11]
	s_mov_b32 m0, s74
	s_nop 0
	global_load_lds_dwordx4 v190, vcc
	s_mov_b32 m0, s75
	s_nop 0
	global_load_lds_dwordx4 v144, vcc
	s_nop 0
	s_waitcnt vmcnt(8)
	s_waitcnt lgkmcnt(0)
	s_barrier
; #define PG8_STAGE(bufoff, gbase, voff) do { _Pragma("unroll") for (int _i = 0; _i < 2; ++_i) \
;         __builtin_amdgcn_global_load_lds((const unsigned*)((const char*)(gbase) + (voff)[_i]), (PG8_LAS unsigned*)(lds + (bufoff) + ldsw + _i * 8192), 16, 0, 0); } while (0)
; #define PG8_LDA(dst, b, h) do { _Pragma("unroll") for (int m = 0; m < 4; ++m) _Pragma("unroll") for (int k = 0; k < 2; ++k) dst[m][k] = *(const PG8_LAS bf16x8*)(lds + PG8_SA(b, h) + aoff + m * 2048 + k * 1024); } while (0)
; #define PG8_LDB(dst, b, h) do { _Pragma("unroll") for (int n = 0; n < 2; ++n) _Pragma("unroll") for (int k = 0; k < 2; ++k) dst[n][k] = *(const PG8_LAS bf16x8*)(lds + PG8_SB(b, h) + boff + n * 2048 + k * 1024); } while (0)
; #define PG8_MMA(ai, bj, At, Bt) do { __builtin_amdgcn_s_setprio(1); _Pragma("unroll") for (int m = 0; m < 4; ++m) _Pragma("unroll") for (int n = 0; n < 2; ++n) _Pragma("unroll") for (int k = 0; k < 2; ++k) \
;         acc[ai][bj][m][n] = __builtin_amdgcn_mfma_f32_16x16x32_bf16(Bt[n][k], At[m][k], acc[ai][bj][m][n], 0, 0, 0); __builtin_amdgcn_s_setprio(0); } while (0)
; #define PG8_WAIT_V(n) asm volatile("s_waitcnt vmcnt(" #n ")" ::: "memory")
; #define PG8_WAIT_L(n) asm volatile("s_waitcnt lgkmcnt(" #n ")" ::: "memory")
; #define PG8_BAR __builtin_amdgcn_s_barrier()
; #define PG8_SCHED __builtin_amdgcn_sched_barrier(0)
; template <class Epi, class Sched, bool ALIGN_EPI = false, bool SP2 = false>
; __device__ __forceinline__ void gemm_phase(PG8_LAS unsigned char* lds, const Gemm g, const Sched& S, const Epi& E) {
;     ...
;             PG8_WAIT_V(8); PG8_WAIT_L(0); PG8_BAR; PG8_MMA(0, 0, At, B0); PG8_MMA(0, 1, At, B1); PG8_BAR; PG8_SCHED;
;             PG8_LDA(At, 0, 1); PG8_STAGE(PG8_SB(0, 0), b2, voffB); PG8_STAGE(PG8_SB(0, 1), b2 + hstepB, voffB); PG8_STAGE(PG8_SA(0, 0), a2, voffA);
;             PG8_WAIT_V(8); PG8_WAIT_L(0); PG8_BAR; PG8_MMA(1, 0, At, B0); PG8_MMA(1, 1, At, B1); PG8_BAR; PG8_SCHED;
;             PG8_LDB(B0, 1, 0); PG8_LDB(B1, 1, 1); PG8_SCHED; PG8_LDA(At, 1, 0); PG8_STAGE(PG8_SA(0, 1), a2 + hstep, voffA);
;             PG8_WAIT_V(8); PG8_WAIT_L(0); PG8_BAR; PG8_MMA(0, 0, At, B0); PG8_MMA(0, 1, At, B1); PG8_BAR; PG8_SCHED;
	v_mfma_f32_16x16x32_bf16 v[62:65], v[130:133], v[176:179], 0
	v_mfma_f32_16x16x32_bf16 v[62:65], v[134:137], v[180:183], v[62:65]
	v_mfma_f32_16x16x32_bf16 v[46:49], v[130:133], v[206:209], 0
	v_mfma_f32_16x16x32_bf16 v[46:49], v[134:137], v[210:213], v[46:49]
	v_mfma_f32_16x16x32_bf16 v[42:45], v[138:141], v[206:209], 0
	v_mfma_f32_16x16x32_bf16 v[42:45], v[152:155], v[210:213], v[42:45]
	v_mfma_f32_16x16x32_bf16 v[58:61], v[138:141], v[176:179], 0
	v_mfma_f32_16x16x32_bf16 v[58:61], v[152:155], v[180:183], v[58:61]
	v_mfma_f32_16x16x32_bf16 v[26:29], v[138:141], v[214:217], 0
	v_mfma_f32_16x16x32_bf16 v[26:29], v[152:155], v[218:221], v[26:29]
	v_mfma_f32_16x16x32_bf16 v[10:13], v[138:141], v[236:239], 0
	v_mfma_f32_16x16x32_bf16 v[10:13], v[152:155], v[240:243], v[10:13]
	v_mfma_f32_16x16x32_bf16 v[14:17], v[130:133], v[236:239], 0
	v_mfma_f32_16x16x32_bf16 v[14:17], v[134:137], v[240:243], v[14:17]
	v_mfma_f32_16x16x32_bf16 v[30:33], v[130:133], v[214:217], 0
	v_mfma_f32_16x16x32_bf16 v[30:33], v[134:137], v[218:221], v[30:33]
	v_mfma_f32_16x16x32_bf16 v[54:57], v[156:159], v[176:179], 0
	v_mfma_f32_16x16x32_bf16 v[54:57], v[160:163], v[180:183], v[54:57]
	v_mfma_f32_16x16x32_bf16 v[38:41], v[156:159], v[206:209], 0
	v_mfma_f32_16x16x32_bf16 v[38:41], v[160:163], v[210:213], v[38:41]
	v_mfma_f32_16x16x32_bf16 v[34:37], v[168:171], v[206:209], 0
	v_mfma_f32_16x16x32_bf16 v[34:37], v[172:175], v[210:213], v[34:37]
	v_mfma_f32_16x16x32_bf16 v[50:53], v[168:171], v[176:179], 0
	v_mfma_f32_16x16x32_bf16 v[50:53], v[172:175], v[180:183], v[50:53]
	v_mfma_f32_16x16x32_bf16 v[18:21], v[168:171], v[214:217], 0
	v_mfma_f32_16x16x32_bf16 v[18:21], v[172:175], v[218:221], v[18:21]
	v_mfma_f32_16x16x32_bf16 v[2:5], v[168:171], v[236:239], 0
	v_mfma_f32_16x16x32_bf16 v[2:5], v[172:175], v[240:243], v[2:5]
	v_mfma_f32_16x16x32_bf16 v[6:9], v[156:159], v[236:239], 0
	v_mfma_f32_16x16x32_bf16 v[6:9], v[160:163], v[240:243], v[6:9]
	v_mfma_f32_16x16x32_bf16 v[22:25], v[156:159], v[214:217], 0
	v_mfma_f32_16x16x32_bf16 v[22:25], v[160:163], v[218:221], v[22:25]
	s_barrier
	s_add_i32 s12, 0, 0x18000
	s_add_i32 s13, 0, 0x1c000
	ds_read_b128 v[130:133], v198
	ds_read_b128 v[134:137], v198 offset:1024
	ds_read_b128 v[138:141], v198 offset:2048
	ds_read_b128 v[152:155], v198 offset:3072
	ds_read_b128 v[156:159], v199
	ds_read_b128 v[160:163], v199 offset:1024
	ds_read_b128 v[168:171], v199 offset:2048
	ds_read_b128 v[172:175], v199 offset:3072
	s_add_u32 s10, vcc_lo, 0x200000
	s_addc_u32 s11, vcc_hi, 0
	s_mov_b32 m0, s86
	ds_read_b128 v[176:179], v166 offset:32768
	ds_read_b128 v[180:183], v166 offset:33792
	ds_read_b128 v[206:209], v166 offset:34816
	ds_read_b128 v[210:213], v166 offset:35840
	ds_read_b128 v[214:217], v166 offset:36864
	ds_read_b128 v[218:221], v166 offset:37888
	ds_read_b128 v[236:239], v166 offset:38912
	ds_read_b128 v[240:243], v166 offset:39936
	global_load_lds_dwordx4 v190, s[10:11]
	s_mov_b32 m0, s87
	s_nop 0
	global_load_lds_dwordx4 v144, s[10:11]
	s_waitcnt vmcnt(8)
	s_waitcnt lgkmcnt(0)
	s_barrier
	v_mfma_f32_16x16x32_bf16 v[126:129], v[130:133], v[176:179], v[126:129]
	v_mfma_f32_16x16x32_bf16 v[126:129], v[134:137], v[180:183], v[126:129]
	v_mfma_f32_16x16x32_bf16 v[110:113], v[130:133], v[206:209], v[110:113]
	v_mfma_f32_16x16x32_bf16 v[110:113], v[134:137], v[210:213], v[110:113]
	v_mfma_f32_16x16x32_bf16 v[106:109], v[138:141], v[206:209], v[106:109]
	v_mfma_f32_16x16x32_bf16 v[106:109], v[152:155], v[210:213], v[106:109]
	v_mfma_f32_16x16x32_bf16 v[122:125], v[138:141], v[176:179], v[122:125]
	v_mfma_f32_16x16x32_bf16 v[122:125], v[152:155], v[180:183], v[122:125]
	v_mfma_f32_16x16x32_bf16 v[90:93], v[138:141], v[214:217], v[90:93]
	v_mfma_f32_16x16x32_bf16 v[90:93], v[152:155], v[218:221], v[90:93]
	v_mfma_f32_16x16x32_bf16 v[74:77], v[138:141], v[236:239], v[74:77]
	v_mfma_f32_16x16x32_bf16 v[74:77], v[152:155], v[240:243], v[74:77]
	v_mfma_f32_16x16x32_bf16 v[78:81], v[130:133], v[236:239], v[78:81]
	v_mfma_f32_16x16x32_bf16 v[78:81], v[134:137], v[240:243], v[78:81]
	v_mfma_f32_16x16x32_bf16 v[94:97], v[130:133], v[214:217], v[94:97]
	v_mfma_f32_16x16x32_bf16 v[94:97], v[134:137], v[218:221], v[94:97]
	v_mfma_f32_16x16x32_bf16 v[118:121], v[156:159], v[176:179], v[118:121]
	v_mfma_f32_16x16x32_bf16 v[118:121], v[160:163], v[180:183], v[118:121]
	v_mfma_f32_16x16x32_bf16 v[102:105], v[156:159], v[206:209], v[102:105]
	v_mfma_f32_16x16x32_bf16 v[102:105], v[160:163], v[210:213], v[102:105]
	v_mfma_f32_16x16x32_bf16 v[98:101], v[168:171], v[206:209], v[98:101]
	v_mfma_f32_16x16x32_bf16 v[98:101], v[172:175], v[210:213], v[98:101]
	v_mfma_f32_16x16x32_bf16 v[114:117], v[168:171], v[176:179], v[114:117]
	v_mfma_f32_16x16x32_bf16 v[114:117], v[172:175], v[180:183], v[114:117]
	v_mfma_f32_16x16x32_bf16 v[82:85], v[168:171], v[214:217], v[82:85]
	v_mfma_f32_16x16x32_bf16 v[82:85], v[172:175], v[218:221], v[82:85]
	v_mfma_f32_16x16x32_bf16 v[66:69], v[168:171], v[236:239], v[66:69]
	v_mfma_f32_16x16x32_bf16 v[66:69], v[172:175], v[240:243], v[66:69]
	v_mfma_f32_16x16x32_bf16 v[70:73], v[156:159], v[236:239], v[70:73]
	v_mfma_f32_16x16x32_bf16 v[70:73], v[160:163], v[240:243], v[70:73]
	v_mfma_f32_16x16x32_bf16 v[86:89], v[156:159], v[214:217], v[86:89]
	v_mfma_f32_16x16x32_bf16 v[86:89], v[160:163], v[218:221], v[86:89]
	s_barrier
; #define PG8_STAGE(bufoff, gbase, voff) do { _Pragma("unroll") for (int _i = 0; _i < 2; ++_i) \
;         __builtin_amdgcn_global_load_lds((const unsigned*)((const char*)(gbase) + (voff)[_i]), (PG8_LAS unsigned*)(lds + (bufoff) + ldsw + _i * 8192), 16, 0, 0); } while (0)
; #define PG8_LDA(dst, b, h) do { _Pragma("unroll") for (int m = 0; m < 4; ++m) _Pragma("unroll") for (int k = 0; k < 2; ++k) dst[m][k] = *(const PG8_LAS bf16x8*)(lds + PG8_SA(b, h) + aoff + m * 2048 + k * 1024); } while (0)
; #define PG8_LDB(dst, b, h) do { _Pragma("unroll") for (int n = 0; n < 2; ++n) _Pragma("unroll") for (int k = 0; k < 2; ++k) dst[n][k] = *(const PG8_LAS bf16x8*)(lds + PG8_SB(b, h) + boff + n * 2048 + k * 1024); } while (0)
; template <class Epi, class Sched, bool ALIGN_EPI = false, bool SP2 = false>
; __device__ __forceinline__ void gemm_phase(PG8_LAS unsigned char* lds, const Gemm g, const Sched& S, const Epi& E) {
;     ...
;         for (int t = 0; t < nt; t += 2) {
;             const bool last = (t == nt - 2);
;             const char* a1 = cA + (size_t)(t + 1) * kstep;
;             const char* a2 = last ? nA : cA + (size_t)(t + 2) * kstep; const char* b2 = last ? nB : cB + (size_t)(t + 2) * kstep;
;             const char* a3 = a2 + kstep; const char* b3 = b2 + kstep;
;             if (last && has_next) S.a_ready(nxt);
;             if constexpr (SP2) {
;             PG8_LDB(B0, 0, 0); PG8_LDB(B1, 0, 1); PG8_SCHED; PG8_LDA(At, 0, 0); PG8_STAGE(PG8_SA(1, 1), a1 + hstep, voffA);
;             PG8_WAIT_V(8); PG8_WAIT_L(0); PG8_BAR; PG8_MMA(0, 0, At, B0); PG8_MMA(0, 1, At, B1); PG8_BAR; PG8_SCHED;
;             PG8_LDA(At, 0, 1); PG8_STAGE(PG8_SB(0, 0), b2, voffB); PG8_STAGE(PG8_SB(0, 1), b2 + hstepB, voffB); PG8_STAGE(PG8_SA(0, 0), a2, voffA);
;             PG8_WAIT_V(8); PG8_WAIT_L(0); PG8_BAR; PG8_MMA(1, 0, At, B0); PG8_MMA(1, 1, At, B1); PG8_BAR; PG8_SCHED;
;             PG8_LDB(B0, 1, 0); PG8_LDB(B1, 1, 1); PG8_SCHED; PG8_LDA(At, 1, 0); PG8_STAGE(PG8_SA(0, 1), a2 + hstep, voffA);
;             PG8_WAIT_V(8); PG8_WAIT_L(0); PG8_BAR; PG8_MMA(0, 0, At, B0); PG8_MMA(0, 1, At, B1); PG8_BAR; PG8_SCHED;
;             PG8_LDA(At, 1, 1); PG8_STAGE(PG8_SB(1, 0), b3, voffB); PG8_STAGE(PG8_SB(1, 1), b3 + hstepB, voffB); PG8_STAGE(PG8_SA(1, 0), a3, voffA);
;             PG8_WAIT_V(8); PG8_WAIT_L(0); PG8_BAR; PG8_MMA(1, 0, At, B0); PG8_MMA(1, 1, At, B1); PG8_BAR; PG8_SCHED;
	s_add_i32 s10, s12, s67
	s_mov_b32 m0, s10
	ds_read_b128 v[176:179], v166 offset:49152
	ds_read_b128 v[180:183], v166 offset:50176
	ds_read_b128 v[206:209], v166 offset:51200
	ds_read_b128 v[210:213], v166 offset:52224
	ds_read_b128 v[214:217], v166 offset:53248
	ds_read_b128 v[218:221], v166 offset:54272
	ds_read_b128 v[236:239], v166 offset:55296
	ds_read_b128 v[240:243], v166 offset:56320
	s_add_u32 s100, s46, s60
	s_addc_u32 s101, s47, s61
	global_load_lds_dwordx4 v146, s[100:101]
	s_add_i32 m0, s10, 0x2000
	s_add_u32 s10, s46, 0x80080
	s_addc_u32 s11, s47, 0
	s_add_i32 s12, s13, s67
	global_load_lds_dwordx4 v142, s[100:101]
	s_mov_b32 m0, s12
	s_nop 0
	global_load_lds_dwordx4 v146, s[10:11]
	s_add_i32 m0, s12, 0x2000
	s_nop 0
	global_load_lds_dwordx4 v142, s[10:11]
	s_mov_b32 m0, s82
	s_add_u32 s100, vcc_lo, s60
	s_addc_u32 s101, vcc_hi, s61
	global_load_lds_dwordx4 v190, s[100:101]
	s_mov_b32 m0, s42
	s_nop 0
	global_load_lds_dwordx4 v144, s[100:101]
	s_waitcnt vmcnt(8)
	s_waitcnt lgkmcnt(0)
	s_barrier
	v_mfma_f32_16x16x32_bf16 v[62:65], v[130:133], v[176:179], v[62:65]
	v_mfma_f32_16x16x32_bf16 v[62:65], v[134:137], v[180:183], v[62:65]
	v_mfma_f32_16x16x32_bf16 v[46:49], v[130:133], v[206:209], v[46:49]
	v_mfma_f32_16x16x32_bf16 v[46:49], v[134:137], v[210:213], v[46:49]
	v_mfma_f32_16x16x32_bf16 v[42:45], v[138:141], v[206:209], v[42:45]
	v_mfma_f32_16x16x32_bf16 v[42:45], v[152:155], v[210:213], v[42:45]
	v_mfma_f32_16x16x32_bf16 v[58:61], v[138:141], v[176:179], v[58:61]
	v_mfma_f32_16x16x32_bf16 v[58:61], v[152:155], v[180:183], v[58:61]
	v_mfma_f32_16x16x32_bf16 v[26:29], v[138:141], v[214:217], v[26:29]
	v_mfma_f32_16x16x32_bf16 v[26:29], v[152:155], v[218:221], v[26:29]
	v_mfma_f32_16x16x32_bf16 v[10:13], v[138:141], v[236:239], v[10:13]
	v_mfma_f32_16x16x32_bf16 v[10:13], v[152:155], v[240:243], v[10:13]
	v_mfma_f32_16x16x32_bf16 v[14:17], v[130:133], v[236:239], v[14:17]
	v_mfma_f32_16x16x32_bf16 v[14:17], v[134:137], v[240:243], v[14:17]
	v_mfma_f32_16x16x32_bf16 v[30:33], v[130:133], v[214:217], v[30:33]
	v_mfma_f32_16x16x32_bf16 v[30:33], v[134:137], v[218:221], v[30:33]
	v_mfma_f32_16x16x32_bf16 v[54:57], v[156:159], v[176:179], v[54:57]
	v_mfma_f32_16x16x32_bf16 v[54:57], v[160:163], v[180:183], v[54:57]
	v_mfma_f32_16x16x32_bf16 v[38:41], v[156:159], v[206:209], v[38:41]
	v_mfma_f32_16x16x32_bf16 v[38:41], v[160:163], v[210:213], v[38:41]
	v_mfma_f32_16x16x32_bf16 v[34:37], v[168:171], v[206:209], v[34:37]
	v_mfma_f32_16x16x32_bf16 v[34:37], v[172:175], v[210:213], v[34:37]
	v_mfma_f32_16x16x32_bf16 v[50:53], v[168:171], v[176:179], v[50:53]
	v_mfma_f32_16x16x32_bf16 v[50:53], v[172:175], v[180:183], v[50:53]
	v_mfma_f32_16x16x32_bf16 v[18:21], v[168:171], v[214:217], v[18:21]
	v_mfma_f32_16x16x32_bf16 v[18:21], v[172:175], v[218:221], v[18:21]
	v_mfma_f32_16x16x32_bf16 v[2:5], v[168:171], v[236:239], v[2:5]
	v_mfma_f32_16x16x32_bf16 v[2:5], v[172:175], v[240:243], v[2:5]
	v_mfma_f32_16x16x32_bf16 v[6:9], v[156:159], v[236:239], v[6:9]
	v_mfma_f32_16x16x32_bf16 v[6:9], v[160:163], v[240:243], v[6:9]
	v_mfma_f32_16x16x32_bf16 v[22:25], v[156:159], v[214:217], v[22:25]
	v_mfma_f32_16x16x32_bf16 v[22:25], v[160:163], v[218:221], v[22:25]
	s_barrier
	s_add_i32 s9, s9, 2
	s_add_u32 s38, s38, 0x100
	s_addc_u32 s39, s39, 0
	s_add_u32 s7, s7, 0x100
	s_addc_u32 s8, s8, 0
	s_cmpk_gt_u32 s9, 0x7d
.LBB0_1071:
	s_add_u32 s10, s38, 0xffe00080
	s_addc_u32 s11, s39, -1
	s_add_i32 s12, 0, 0x10000
	s_cmpk_eq_i32 s9, 0x7c
	s_cselect_b32 vcc_hi, s97, s11
	s_cselect_b32 vcc_lo, s4, s10
	s_cselect_b32 s47, s5, s8
	s_cselect_b32 s46, s6, s7
	s_add_i32 s13, 0, 0x14000
	ds_read_b128 v[130:133], v186
	ds_read_b128 v[134:137], v186 offset:1024
	ds_read_b128 v[138:141], v186 offset:2048
	ds_read_b128 v[152:155], v186 offset:3072
	ds_read_b128 v[156:159], v187
	ds_read_b128 v[160:163], v187 offset:1024
	ds_read_b128 v[168:171], v187 offset:2048
	ds_read_b128 v[172:175], v187 offset:3072
	s_add_i32 m0, s74, 0xc000
	ds_read_b128 v[176:179], v166
	ds_read_b128 v[180:183], v166 offset:1024
	ds_read_b128 v[206:209], v166 offset:2048
	ds_read_b128 v[210:213], v166 offset:3072
	ds_read_b128 v[214:217], v166 offset:4096
	ds_read_b128 v[218:221], v166 offset:5120
	ds_read_b128 v[236:239], v166 offset:6144
	ds_read_b128 v[240:243], v166 offset:7168
	global_load_lds_dwordx4 v148, s[38:39]
	s_add_i32 m0, s74, 0xe000
	s_nop 0
	global_load_lds_dwordx4 v150, s[38:39]
	s_nop 0
	s_waitcnt vmcnt(8)
	s_waitcnt lgkmcnt(0)
	s_barrier
	v_mfma_f32_16x16x32_bf16 v[126:129], v[130:133], v[176:179], v[126:129]
	v_mfma_f32_16x16x32_bf16 v[126:129], v[134:137], v[180:183], v[126:129]
	v_mfma_f32_16x16x32_bf16 v[110:113], v[130:133], v[206:209], v[110:113]
	v_mfma_f32_16x16x32_bf16 v[110:113], v[134:137], v[210:213], v[110:113]
	v_mfma_f32_16x16x32_bf16 v[106:109], v[138:141], v[206:209], v[106:109]
	v_mfma_f32_16x16x32_bf16 v[106:109], v[152:155], v[210:213], v[106:109]
	v_mfma_f32_16x16x32_bf16 v[122:125], v[138:141], v[176:179], v[122:125]
	v_mfma_f32_16x16x32_bf16 v[122:125], v[152:155], v[180:183], v[122:125]
	v_mfma_f32_16x16x32_bf16 v[90:93], v[138:141], v[214:217], v[90:93]
	v_mfma_f32_16x16x32_bf16 v[90:93], v[152:155], v[218:221], v[90:93]
	v_mfma_f32_16x16x32_bf16 v[74:77], v[138:141], v[236:239], v[74:77]
	v_mfma_f32_16x16x32_bf16 v[74:77], v[152:155], v[240:243], v[74:77]
	v_mfma_f32_16x16x32_bf16 v[78:81], v[130:133], v[236:239], v[78:81]
	v_mfma_f32_16x16x32_bf16 v[78:81], v[134:137], v[240:243], v[78:81]
	v_mfma_f32_16x16x32_bf16 v[94:97], v[130:133], v[214:217], v[94:97]
	v_mfma_f32_16x16x32_bf16 v[94:97], v[134:137], v[218:221], v[94:97]
	v_mfma_f32_16x16x32_bf16 v[118:121], v[156:159], v[176:179], v[118:121]
	v_mfma_f32_16x16x32_bf16 v[118:121], v[160:163], v[180:183], v[118:121]
	v_mfma_f32_16x16x32_bf16 v[102:105], v[156:159], v[206:209], v[102:105]
	v_mfma_f32_16x16x32_bf16 v[102:105], v[160:163], v[210:213], v[102:105]
	v_mfma_f32_16x16x32_bf16 v[98:101], v[168:171], v[206:209], v[98:101]
	v_mfma_f32_16x16x32_bf16 v[98:101], v[172:175], v[210:213], v[98:101]
	v_mfma_f32_16x16x32_bf16 v[114:117], v[168:171], v[176:179], v[114:117]
	v_mfma_f32_16x16x32_bf16 v[114:117], v[172:175], v[180:183], v[114:117]
	v_mfma_f32_16x16x32_bf16 v[82:85], v[168:171], v[214:217], v[82:85]
	v_mfma_f32_16x16x32_bf16 v[82:85], v[172:175], v[218:221], v[82:85]
	v_mfma_f32_16x16x32_bf16 v[66:69], v[168:171], v[236:239], v[66:69]
	v_mfma_f32_16x16x32_bf16 v[66:69], v[172:175], v[240:243], v[66:69]
	v_mfma_f32_16x16x32_bf16 v[70:73], v[156:159], v[236:239], v[70:73]
	v_mfma_f32_16x16x32_bf16 v[70:73], v[160:163], v[240:243], v[70:73]
	v_mfma_f32_16x16x32_bf16 v[86:89], v[156:159], v[214:217], v[86:89]
	v_mfma_f32_16x16x32_bf16 v[86:89], v[160:163], v[218:221], v[86:89]
	s_barrier
; #define PG8_STAGE(bufoff, gbase, voff) do { _Pragma("unroll") for (int _i = 0; _i < 2; ++_i) \
;         __builtin_amdgcn_global_load_lds((const unsigned*)((const char*)(gbase) + (voff)[_i]), (PG8_LAS unsigned*)(lds + (bufoff) + ldsw + _i * 8192), 16, 0, 0); } while (0)
; #define PG8_LDA(dst, b, h) do { _Pragma("unroll") for (int m = 0; m < 4; ++m) _Pragma("unroll") for (int k = 0; k < 2; ++k) dst[m][k] = *(const PG8_LAS bf16x8*)(lds + PG8_SA(b, h) + aoff + m * 2048 + k * 1024); } while (0)
; #define PG8_LDB(dst, b, h) do { _Pragma("unroll") for (int n = 0; n < 2; ++n) _Pragma("unroll") for (int k = 0; k < 2; ++k) dst[n][k] = *(const PG8_LAS bf16x8*)(lds + PG8_SB(b, h) + boff + n * 2048 + k * 1024); } while (0)
; #define PG8_MMA(ai, bj, At, Bt) do { __builtin_amdgcn_s_setprio(1); _Pragma("unroll") for (int m = 0; m < 4; ++m) _Pragma("unroll") for (int n = 0; n < 2; ++n) _Pragma("unroll") for (int k = 0; k < 2; ++k) \
;         acc[ai][bj][m][n] = __builtin_amdgcn_mfma_f32_16x16x32_bf16(Bt[n][k], At[m][k], acc[ai][bj][m][n], 0, 0, 0); __builtin_amdgcn_s_setprio(0); } while (0)
; #define PG8_WAIT_V(n) asm volatile("s_waitcnt vmcnt(" #n ")" ::: "memory")
; #define PG8_WAIT_L(n) asm volatile("s_waitcnt lgkmcnt(" #n ")" ::: "memory")
; #define PG8_BAR __builtin_amdgcn_s_barrier()
; #define PG8_SCHED __builtin_amdgcn_sched_barrier(0)
; template <class Epi, class Sched, bool ALIGN_EPI = false, bool SP2 = false>
; __device__ __forceinline__ void gemm_phase(PG8_LAS unsigned char* lds, const Gemm g, const Sched& S, const Epi& E) {
;     ...
;             PG8_LDA(At, 0, 1); PG8_STAGE(PG8_SB(0, 0), b2, voffB); PG8_STAGE(PG8_SB(0, 1), b2 + hstepB, voffB); PG8_STAGE(PG8_SA(0, 0), a2, voffA);
;             PG8_WAIT_V(8); PG8_WAIT_L(0); PG8_BAR; PG8_MMA(1, 0, At, B0); PG8_MMA(1, 1, At, B1); PG8_BAR; PG8_SCHED;
;             PG8_LDB(B0, 1, 0); PG8_LDB(B1, 1, 1); PG8_SCHED; PG8_LDA(At, 1, 0); PG8_STAGE(PG8_SA(0, 1), a2 + hstep, voffA);
	s_add_i32 s10, s12, s67
	s_mov_b32 m0, s10
	ds_read_b128 v[176:179], v166 offset:16384
	ds_read_b128 v[180:183], v166 offset:17408
	ds_read_b128 v[206:209], v166 offset:18432
	ds_read_b128 v[210:213], v166 offset:19456
	ds_read_b128 v[214:217], v166 offset:20480
	ds_read_b128 v[218:221], v166 offset:21504
	ds_read_b128 v[236:239], v166 offset:22528
	ds_read_b128 v[240:243], v166 offset:23552
	global_load_lds_dwordx4 v146, s[46:47]
	s_add_i32 m0, s10, 0x2000
	s_add_u32 s10, s46, 0x80000
	s_addc_u32 s11, s47, 0
	s_add_i32 s12, s13, s67
	global_load_lds_dwordx4 v142, s[46:47]
	s_mov_b32 m0, s12
	s_nop 0
	global_load_lds_dwordx4 v146, s[10:11]
	s_add_i32 m0, s12, 0x2000
	s_nop 0
	global_load_lds_dwordx4 v142, s[10:11]
	s_mov_b32 m0, s74
	s_nop 0
	global_load_lds_dwordx4 v190, vcc
	s_mov_b32 m0, s75
	s_nop 0
	global_load_lds_dwordx4 v144, vcc
	s_nop 0
	s_waitcnt vmcnt(8)
	s_waitcnt lgkmcnt(0)
	s_barrier
	v_mfma_f32_16x16x32_bf16 v[62:65], v[130:133], v[176:179], v[62:65]
	v_mfma_f32_16x16x32_bf16 v[62:65], v[134:137], v[180:183], v[62:65]
	v_mfma_f32_16x16x32_bf16 v[46:49], v[130:133], v[206:209], v[46:49]
	v_mfma_f32_16x16x32_bf16 v[46:49], v[134:137], v[210:213], v[46:49]
	v_mfma_f32_16x16x32_bf16 v[42:45], v[138:141], v[206:209], v[42:45]
	v_mfma_f32_16x16x32_bf16 v[42:45], v[152:155], v[210:213], v[42:45]
	v_mfma_f32_16x16x32_bf16 v[58:61], v[138:141], v[176:179], v[58:61]
	v_mfma_f32_16x16x32_bf16 v[58:61], v[152:155], v[180:183], v[58:61]
	v_mfma_f32_16x16x32_bf16 v[26:29], v[138:141], v[214:217], v[26:29]
	v_mfma_f32_16x16x32_bf16 v[26:29], v[152:155], v[218:221], v[26:29]
	v_mfma_f32_16x16x32_bf16 v[10:13], v[138:141], v[236:239], v[10:13]
	v_mfma_f32_16x16x32_bf16 v[10:13], v[152:155], v[240:243], v[10:13]
	v_mfma_f32_16x16x32_bf16 v[14:17], v[130:133], v[236:239], v[14:17]
	v_mfma_f32_16x16x32_bf16 v[14:17], v[134:137], v[240:243], v[14:17]
	v_mfma_f32_16x16x32_bf16 v[30:33], v[130:133], v[214:217], v[30:33]
	v_mfma_f32_16x16x32_bf16 v[30:33], v[134:137], v[218:221], v[30:33]
	v_mfma_f32_16x16x32_bf16 v[54:57], v[156:159], v[176:179], v[54:57]
	v_mfma_f32_16x16x32_bf16 v[54:57], v[160:163], v[180:183], v[54:57]
	v_mfma_f32_16x16x32_bf16 v[38:41], v[156:159], v[206:209], v[38:41]
	v_mfma_f32_16x16x32_bf16 v[38:41], v[160:163], v[210:213], v[38:41]
	v_mfma_f32_16x16x32_bf16 v[34:37], v[168:171], v[206:209], v[34:37]
	v_mfma_f32_16x16x32_bf16 v[34:37], v[172:175], v[210:213], v[34:37]
	v_mfma_f32_16x16x32_bf16 v[50:53], v[168:171], v[176:179], v[50:53]
	v_mfma_f32_16x16x32_bf16 v[50:53], v[172:175], v[180:183], v[50:53]
	v_mfma_f32_16x16x32_bf16 v[18:21], v[168:171], v[214:217], v[18:21]
	v_mfma_f32_16x16x32_bf16 v[18:21], v[172:175], v[218:221], v[18:21]
	v_mfma_f32_16x16x32_bf16 v[2:5], v[168:171], v[236:239], v[2:5]
	v_mfma_f32_16x16x32_bf16 v[2:5], v[172:175], v[240:243], v[2:5]
	v_mfma_f32_16x16x32_bf16 v[6:9], v[156:159], v[236:239], v[6:9]
	v_mfma_f32_16x16x32_bf16 v[6:9], v[160:163], v[240:243], v[6:9]
	v_mfma_f32_16x16x32_bf16 v[22:25], v[156:159], v[214:217], v[22:25]
	v_mfma_f32_16x16x32_bf16 v[22:25], v[160:163], v[218:221], v[22:25]
	s_barrier
	s_add_i32 s12, 0, 0x18000
	s_add_i32 s13, 0, 0x1c000
	ds_read_b128 v[130:133], v198
	ds_read_b128 v[134:137], v198 offset:1024
	ds_read_b128 v[138:141], v198 offset:2048
	ds_read_b128 v[152:155], v198 offset:3072
	ds_read_b128 v[156:159], v199
	ds_read_b128 v[160:163], v199 offset:1024
	ds_read_b128 v[168:171], v199 offset:2048
	ds_read_b128 v[172:175], v199 offset:3072
	s_add_u32 s10, vcc_lo, 0x200000
	s_addc_u32 s11, vcc_hi, 0
	s_mov_b32 m0, s86
	ds_read_b128 v[176:179], v166 offset:32768
	ds_read_b128 v[180:183], v166 offset:33792
	ds_read_b128 v[206:209], v166 offset:34816
	ds_read_b128 v[210:213], v166 offset:35840
	ds_read_b128 v[214:217], v166 offset:36864
	ds_read_b128 v[218:221], v166 offset:37888
	ds_read_b128 v[236:239], v166 offset:38912
	ds_read_b128 v[240:243], v166 offset:39936
	global_load_lds_dwordx4 v190, s[10:11]
	s_mov_b32 m0, s87
	s_nop 0
	global_load_lds_dwordx4 v144, s[10:11]
	s_waitcnt vmcnt(8)
	s_waitcnt lgkmcnt(0)
	s_barrier
; #define PG8_STAGE(bufoff, gbase, voff) do { _Pragma("unroll") for (int _i = 0; _i < 2; ++_i) \
;         __builtin_amdgcn_global_load_lds((const unsigned*)((const char*)(gbase) + (voff)[_i]), (PG8_LAS unsigned*)(lds + (bufoff) + ldsw + _i * 8192), 16, 0, 0); } while (0)
; #define PG8_LDA(dst, b, h) do { _Pragma("unroll") for (int m = 0; m < 4; ++m) _Pragma("unroll") for (int k = 0; k < 2; ++k) dst[m][k] = *(const PG8_LAS bf16x8*)(lds + PG8_SA(b, h) + aoff + m * 2048 + k * 1024); } while (0)
; #define PG8_LDB(dst, b, h) do { _Pragma("unroll") for (int n = 0; n < 2; ++n) _Pragma("unroll") for (int k = 0; k < 2; ++k) dst[n][k] = *(const PG8_LAS bf16x8*)(lds + PG8_SB(b, h) + boff + n * 2048 + k * 1024); } while (0)
; #define PG8_MMA(ai, bj, At, Bt) do { __builtin_amdgcn_s_setprio(1); _Pragma("unroll") for (int m = 0; m < 4; ++m) _Pragma("unroll") for (int n = 0; n < 2; ++n) _Pragma("unroll") for (int k = 0; k < 2; ++k) \
;         acc[ai][bj][m][n] = __builtin_amdgcn_mfma_f32_16x16x32_bf16(Bt[n][k], At[m][k], acc[ai][bj][m][n], 0, 0, 0); __builtin_amdgcn_s_setprio(0); } while (0)
; #define PG8_WAIT_V(n) asm volatile("s_waitcnt vmcnt(" #n ")" ::: "memory")
; #define PG8_WAIT_L(n) asm volatile("s_waitcnt lgkmcnt(" #n ")" ::: "memory")
; #define PG8_BAR __builtin_amdgcn_s_barrier()
; #define PG8_SCHED __builtin_amdgcn_sched_barrier(0)
; template <class Epi, class Sched, bool ALIGN_EPI = false, bool SP2 = false>
; __device__ __forceinline__ void gemm_phase(PG8_LAS unsigned char* lds, const Gemm g, const Sched& S, const Epi& E) {
;     ...
;             PG8_LDB(B0, 1, 0); PG8_LDB(B1, 1, 1); PG8_SCHED; PG8_LDA(At, 1, 0); PG8_STAGE(PG8_SA(0, 1), a2 + hstep, voffA);
;             PG8_WAIT_V(8); PG8_WAIT_L(0); PG8_BAR; PG8_MMA(0, 0, At, B0); PG8_MMA(0, 1, At, B1); PG8_BAR; PG8_SCHED;
;             PG8_LDA(At, 1, 1); PG8_STAGE(PG8_SB(1, 0), b3, voffB); PG8_STAGE(PG8_SB(1, 1), b3 + hstepB, voffB); PG8_STAGE(PG8_SA(1, 0), a3, voffA);
;             PG8_WAIT_V(8); PG8_WAIT_L(0); PG8_BAR; PG8_MMA(1, 0, At, B0); PG8_MMA(1, 1, At, B1); PG8_BAR; PG8_SCHED;
;     ...
;         if constexpr (ALIGN_EPI) { if (wr == 0) PG8_BAR; }
	v_mfma_f32_16x16x32_bf16 v[126:129], v[130:133], v[176:179], v[126:129]
	v_mfma_f32_16x16x32_bf16 v[126:129], v[134:137], v[180:183], v[126:129]
	v_mfma_f32_16x16x32_bf16 v[110:113], v[130:133], v[206:209], v[110:113]
	v_mfma_f32_16x16x32_bf16 v[110:113], v[134:137], v[210:213], v[110:113]
	v_mfma_f32_16x16x32_bf16 v[106:109], v[138:141], v[206:209], v[106:109]
	v_mfma_f32_16x16x32_bf16 v[106:109], v[152:155], v[210:213], v[106:109]
	v_mfma_f32_16x16x32_bf16 v[122:125], v[138:141], v[176:179], v[122:125]
	v_mfma_f32_16x16x32_bf16 v[122:125], v[152:155], v[180:183], v[122:125]
	v_mfma_f32_16x16x32_bf16 v[90:93], v[138:141], v[214:217], v[90:93]
	v_mfma_f32_16x16x32_bf16 v[90:93], v[152:155], v[218:221], v[90:93]
	v_mfma_f32_16x16x32_bf16 v[74:77], v[138:141], v[236:239], v[74:77]
	v_mfma_f32_16x16x32_bf16 v[74:77], v[152:155], v[240:243], v[74:77]
	v_mfma_f32_16x16x32_bf16 v[78:81], v[130:133], v[236:239], v[78:81]
	v_mfma_f32_16x16x32_bf16 v[78:81], v[134:137], v[240:243], v[78:81]
	v_mfma_f32_16x16x32_bf16 v[94:97], v[130:133], v[214:217], v[94:97]
	v_mfma_f32_16x16x32_bf16 v[94:97], v[134:137], v[218:221], v[94:97]
	v_mfma_f32_16x16x32_bf16 v[118:121], v[156:159], v[176:179], v[118:121]
	v_mfma_f32_16x16x32_bf16 v[118:121], v[160:163], v[180:183], v[118:121]
	v_mfma_f32_16x16x32_bf16 v[102:105], v[156:159], v[206:209], v[102:105]
	v_mfma_f32_16x16x32_bf16 v[102:105], v[160:163], v[210:213], v[102:105]
	v_mfma_f32_16x16x32_bf16 v[98:101], v[168:171], v[206:209], v[98:101]
	v_mfma_f32_16x16x32_bf16 v[98:101], v[172:175], v[210:213], v[98:101]
	v_mfma_f32_16x16x32_bf16 v[114:117], v[168:171], v[176:179], v[114:117]
	v_mfma_f32_16x16x32_bf16 v[114:117], v[172:175], v[180:183], v[114:117]
	v_mfma_f32_16x16x32_bf16 v[82:85], v[168:171], v[214:217], v[82:85]
	v_mfma_f32_16x16x32_bf16 v[82:85], v[172:175], v[218:221], v[82:85]
	v_mfma_f32_16x16x32_bf16 v[66:69], v[168:171], v[236:239], v[66:69]
	v_mfma_f32_16x16x32_bf16 v[66:69], v[172:175], v[240:243], v[66:69]
	v_mfma_f32_16x16x32_bf16 v[70:73], v[156:159], v[236:239], v[70:73]
	v_mfma_f32_16x16x32_bf16 v[70:73], v[160:163], v[240:243], v[70:73]
	v_mfma_f32_16x16x32_bf16 v[86:89], v[156:159], v[214:217], v[86:89]
	v_mfma_f32_16x16x32_bf16 v[86:89], v[160:163], v[218:221], v[86:89]
	s_barrier
	s_add_i32 s10, s12, s67
	s_mov_b32 m0, s10
	ds_read_b128 v[176:179], v166 offset:49152
	ds_read_b128 v[180:183], v166 offset:50176
	ds_read_b128 v[206:209], v166 offset:51200
	ds_read_b128 v[210:213], v166 offset:52224
	ds_read_b128 v[214:217], v166 offset:53248
	ds_read_b128 v[218:221], v166 offset:54272
	ds_read_b128 v[236:239], v166 offset:55296
	ds_read_b128 v[240:243], v166 offset:56320
	s_add_u32 s100, s46, s60
	s_addc_u32 s101, s47, s61
	global_load_lds_dwordx4 v146, s[100:101]
	s_add_i32 m0, s10, 0x2000
	s_add_u32 s10, s46, 0x80080
	s_addc_u32 s11, s47, 0
	s_add_i32 s12, s13, s67
	global_load_lds_dwordx4 v142, s[100:101]
	s_mov_b32 m0, s12
	s_nop 0
	global_load_lds_dwordx4 v146, s[10:11]
	s_add_i32 m0, s12, 0x2000
	s_nop 0
	global_load_lds_dwordx4 v142, s[10:11]
	s_mov_b32 m0, s82
	s_add_u32 s100, vcc_lo, s60
	s_addc_u32 s101, vcc_hi, s61
	global_load_lds_dwordx4 v190, s[100:101]
	s_mov_b32 m0, s42
	s_nop 0
	global_load_lds_dwordx4 v144, s[100:101]
	s_waitcnt vmcnt(8)
	s_waitcnt lgkmcnt(0)
	s_barrier
	v_mfma_f32_16x16x32_bf16 v[62:65], v[130:133], v[176:179], v[62:65]
	v_mfma_f32_16x16x32_bf16 v[62:65], v[134:137], v[180:183], v[62:65]
	v_mfma_f32_16x16x32_bf16 v[46:49], v[130:133], v[206:209], v[46:49]
	v_mfma_f32_16x16x32_bf16 v[46:49], v[134:137], v[210:213], v[46:49]
	v_mfma_f32_16x16x32_bf16 v[42:45], v[138:141], v[206:209], v[42:45]
	v_mfma_f32_16x16x32_bf16 v[42:45], v[152:155], v[210:213], v[42:45]
	v_mfma_f32_16x16x32_bf16 v[58:61], v[138:141], v[176:179], v[58:61]
	v_mfma_f32_16x16x32_bf16 v[58:61], v[152:155], v[180:183], v[58:61]
	v_mfma_f32_16x16x32_bf16 v[26:29], v[138:141], v[214:217], v[26:29]
	v_mfma_f32_16x16x32_bf16 v[26:29], v[152:155], v[218:221], v[26:29]
	v_mfma_f32_16x16x32_bf16 v[10:13], v[138:141], v[236:239], v[10:13]
	v_mfma_f32_16x16x32_bf16 v[10:13], v[152:155], v[240:243], v[10:13]
	v_mfma_f32_16x16x32_bf16 v[14:17], v[130:133], v[236:239], v[14:17]
	v_mfma_f32_16x16x32_bf16 v[14:17], v[134:137], v[240:243], v[14:17]
	v_mfma_f32_16x16x32_bf16 v[30:33], v[130:133], v[214:217], v[30:33]
	v_mfma_f32_16x16x32_bf16 v[30:33], v[134:137], v[218:221], v[30:33]
	v_mfma_f32_16x16x32_bf16 v[54:57], v[156:159], v[176:179], v[54:57]
	v_mfma_f32_16x16x32_bf16 v[54:57], v[160:163], v[180:183], v[54:57]
	v_mfma_f32_16x16x32_bf16 v[38:41], v[156:159], v[206:209], v[38:41]
	v_mfma_f32_16x16x32_bf16 v[38:41], v[160:163], v[210:213], v[38:41]
	v_mfma_f32_16x16x32_bf16 v[34:37], v[168:171], v[206:209], v[34:37]
	v_mfma_f32_16x16x32_bf16 v[34:37], v[172:175], v[210:213], v[34:37]
	v_mfma_f32_16x16x32_bf16 v[50:53], v[168:171], v[176:179], v[50:53]
	v_mfma_f32_16x16x32_bf16 v[50:53], v[172:175], v[180:183], v[50:53]
	v_mfma_f32_16x16x32_bf16 v[18:21], v[168:171], v[214:217], v[18:21]
	v_mfma_f32_16x16x32_bf16 v[18:21], v[172:175], v[218:221], v[18:21]
	v_mfma_f32_16x16x32_bf16 v[2:5], v[168:171], v[236:239], v[2:5]
	v_mfma_f32_16x16x32_bf16 v[2:5], v[172:175], v[240:243], v[2:5]
	v_mfma_f32_16x16x32_bf16 v[6:9], v[156:159], v[236:239], v[6:9]
	v_mfma_f32_16x16x32_bf16 v[6:9], v[160:163], v[240:243], v[6:9]
	v_mfma_f32_16x16x32_bf16 v[22:25], v[156:159], v[214:217], v[22:25]
	v_mfma_f32_16x16x32_bf16 v[22:25], v[160:163], v[218:221], v[22:25]
	s_barrier
	s_add_i32 s9, s9, 2
	s_add_u32 s38, s38, 0x100
	s_addc_u32 s39, s39, 0
	s_add_u32 s7, s7, 0x100
	s_addc_u32 s8, s8, 0
	s_cmpk_gt_u32 s9, 0x7d
	s_cbranch_scc0 .LBB0_1071
	s_and_b64 vcc, exec, s[72:73]
	s_cbranch_vccz .LBB0_1074
	s_barrier

; #define PG8_STAGE(bufoff, gbase, voff) do { _Pragma("unroll") for (int _i = 0; _i < 2; ++_i) \
;         __builtin_amdgcn_global_load_lds((const unsigned*)((const char*)(gbase) + (voff)[_i]), (PG8_LAS unsigned*)(lds + (bufoff) + ldsw + _i * 8192), 16, 0, 0); } while (0)
; #define PG8_LDA(dst, b, h) do { _Pragma("unroll") for (int m = 0; m < 4; ++m) _Pragma("unroll") for (int k = 0; k < 2; ++k) dst[m][k] = *(const PG8_LAS bf16x8*)(lds + PG8_SA(b, h) + aoff + m * 2048 + k * 1024); } while (0)
; #define PG8_LDB(dst, b, h) do { _Pragma("unroll") for (int n = 0; n < 2; ++n) _Pragma("unroll") for (int k = 0; k < 2; ++k) dst[n][k] = *(const PG8_LAS bf16x8*)(lds + PG8_SB(b, h) + boff + n * 2048 + k * 1024); } while (0)
; #define PG8_WAIT_V(n) asm volatile("s_waitcnt vmcnt(" #n ")" ::: "memory")
; #define PG8_WAIT_L(n) asm volatile("s_waitcnt lgkmcnt(" #n ")" ::: "memory")
; #define PG8_BAR __builtin_amdgcn_s_barrier()
; #define PG8_SCHED __builtin_amdgcn_sched_barrier(0)
; template <class Epi, class Sched, bool ALIGN_EPI = false, bool SP2 = false>
; __device__ __forceinline__ void gemm_phase(PG8_LAS unsigned char* lds, const Gemm g, const Sched& S, const Epi& E) {
;     ...
;         const bool has_next = S.next(ui + 1, nxt);
;         const char* nA = has_next ? (const char*)g.A + (size_t)nxt.pm * tstep : cA; const char* nB = has_next ? (const char*)g.Bt + (size_t)nxt.pn * tstep : cB;
;         for (int t = 0; t < nt; t += 2) {
;             const bool last = (t == nt - 2);
;             const char* a1 = cA + (size_t)(t + 1) * kstep;
;             const char* a2 = last ? nA : cA + (size_t)(t + 2) * kstep; const char* b2 = last ? nB : cB + (size_t)(t + 2) * kstep;
;             const char* a3 = a2 + kstep; const char* b3 = b2 + kstep;
;             if (last && has_next) S.a_ready(nxt);
;             if constexpr (SP2) {
;             PG8_LDB(B0, 0, 0); PG8_LDB(B1, 0, 1); PG8_SCHED; PG8_LDA(At, 0, 0); PG8_STAGE(PG8_SA(1, 1), a1 + hstep, voffA);
;             PG8_WAIT_V(8); PG8_WAIT_L(0); PG8_BAR; PG8_MMA(0, 0, At, B0); PG8_MMA(0, 1, At, B1); PG8_BAR; PG8_SCHED;
;             PG8_LDA(At, 0, 1); PG8_STAGE(PG8_SB(0, 0), b2, voffB); PG8_STAGE(PG8_SB(0, 1), b2 + hstepB, voffB); PG8_STAGE(PG8_SA(0, 0), a2, voffA);
;             PG8_WAIT_V(8); PG8_WAIT_L(0); PG8_BAR; PG8_MMA(1, 0, At, B0); PG8_MMA(1, 1, At, B1); PG8_BAR; PG8_SCHED;
.LBB0_1232:
	s_add_u32 s36, s80, 0x100
	s_addc_u32 s37, s81, 0
	s_ashr_i32 s73, s72, 31
	s_lshl_b64 s[4:5], s[72:73], 20
	s_add_u32 s78, s0, s4
	s_addc_u32 s79, s1, s5
	s_and_b64 s[4:5], s[46:47], exec
	s_cselect_b32 s4, s79, s69
	s_cselect_b32 s5, s78, s68
	s_ashr_i32 s71, s70, 31
	s_lshl_b64 s[6:7], s[70:71], 20
	s_add_u32 s76, s34, s6
	s_addc_u32 s77, s35, s7
	s_and_b64 s[6:7], s[46:47], exec
	s_cselect_b32 s6, s77, s81
	s_cselect_b32 s7, s76, s80
	s_add_u32 s8, s68, 0x80080
	s_addc_u32 s9, s69, 0
	v_lshl_add_u64 v[140:141], s[8:9], 0, v[136:137]
	v_lshl_add_u64 v[142:143], s[8:9], 0, v[138:139]
	s_mov_b32 s8, -2
	s_mov_b64 s[80:81], 0
	v_add_u32_e32 v186, 0x10000, v145
	v_add_u32_e32 v187, 0x14000, v145
	v_add_u32_e32 v198, 0x18000, v145
	v_add_u32_e32 v199, 0x1c000, v145
	s_add_u32 s9, s68, s80
	s_addc_u32 s10, s69, s81
	s_add_u32 s9, s9, 0x100
	s_addc_u32 s10, s10, 0
	s_add_u32 s100, s9, 0x7ff80
	s_addc_u32 s101, s10, 0
	s_add_u32 s11, s36, s80
	s_addc_u32 s12, s37, s81
	s_add_i32 s13, 0, 0x10000
	s_cmpk_eq_i32 s80, 0xf00
	s_cselect_b32 s93, s4, s10
	s_cselect_b32 s92, s5, s9
	s_cselect_b32 s85, s6, s12
	s_cselect_b32 s84, s7, s11
	s_add_i32 s9, 0, 0x14000
	ds_read_b128 v[152:155], v186
	ds_read_b128 v[156:159], v186 offset:1024
	ds_read_b128 v[160:163], v186 offset:2048
	ds_read_b128 v[164:167], v186 offset:3072
	ds_read_b128 v[168:171], v187
	ds_read_b128 v[172:175], v187 offset:1024
	ds_read_b128 v[176:179], v187 offset:2048
	ds_read_b128 v[180:183], v187 offset:3072
	s_add_i32 m0, s51, 0xc000
	ds_read_b128 v[206:209], v151
	ds_read_b128 v[210:213], v151 offset:1024
	ds_read_b128 v[214:217], v151 offset:2048
	ds_read_b128 v[218:221], v151 offset:3072
	ds_read_b128 v[236:239], v151 offset:4096
	ds_read_b128 v[240:243], v151 offset:5120
	ds_read_b128 v[244:247], v151 offset:6144
	ds_read_b128 v[194:197], v151 offset:7168
	global_load_lds_dwordx4 v136, s[100:101]
	s_add_i32 m0, s51, 0xe000
	s_nop 0
	global_load_lds_dwordx4 v138, s[100:101]
	s_waitcnt vmcnt(8)
	s_waitcnt lgkmcnt(0)
	s_barrier
	v_mfma_f32_16x16x32_bf16 v[126:129], v[152:155], v[206:209], 0
	v_mfma_f32_16x16x32_bf16 v[126:129], v[156:159], v[210:213], v[126:129]
	v_mfma_f32_16x16x32_bf16 v[118:121], v[152:155], v[214:217], 0
	v_mfma_f32_16x16x32_bf16 v[118:121], v[156:159], v[218:221], v[118:121]
	v_mfma_f32_16x16x32_bf16 v[114:117], v[160:163], v[214:217], 0
	v_mfma_f32_16x16x32_bf16 v[114:117], v[164:167], v[218:221], v[114:117]
	v_mfma_f32_16x16x32_bf16 v[122:125], v[160:163], v[206:209], 0
	v_mfma_f32_16x16x32_bf16 v[122:125], v[164:167], v[210:213], v[122:125]
	v_mfma_f32_16x16x32_bf16 v[106:109], v[160:163], v[236:239], 0
	v_mfma_f32_16x16x32_bf16 v[106:109], v[164:167], v[240:243], v[106:109]
	v_mfma_f32_16x16x32_bf16 v[98:101], v[160:163], v[244:247], 0
	v_mfma_f32_16x16x32_bf16 v[98:101], v[164:167], v[194:197], v[98:101]
	v_mfma_f32_16x16x32_bf16 v[102:105], v[152:155], v[244:247], 0
	v_mfma_f32_16x16x32_bf16 v[102:105], v[156:159], v[194:197], v[102:105]
	v_mfma_f32_16x16x32_bf16 v[110:113], v[152:155], v[236:239], 0
	v_mfma_f32_16x16x32_bf16 v[110:113], v[156:159], v[240:243], v[110:113]
	v_mfma_f32_16x16x32_bf16 v[94:97], v[168:171], v[206:209], 0
	v_mfma_f32_16x16x32_bf16 v[94:97], v[172:175], v[210:213], v[94:97]
	v_mfma_f32_16x16x32_bf16 v[86:89], v[168:171], v[214:217], 0
	v_mfma_f32_16x16x32_bf16 v[86:89], v[172:175], v[218:221], v[86:89]
	v_mfma_f32_16x16x32_bf16 v[82:85], v[176:179], v[214:217], 0
	v_mfma_f32_16x16x32_bf16 v[82:85], v[180:183], v[218:221], v[82:85]
	v_mfma_f32_16x16x32_bf16 v[90:93], v[176:179], v[206:209], 0
	v_mfma_f32_16x16x32_bf16 v[90:93], v[180:183], v[210:213], v[90:93]
	v_mfma_f32_16x16x32_bf16 v[74:77], v[176:179], v[236:239], 0
	v_mfma_f32_16x16x32_bf16 v[74:77], v[180:183], v[240:243], v[74:77]
	v_mfma_f32_16x16x32_bf16 v[66:69], v[176:179], v[244:247], 0
	v_mfma_f32_16x16x32_bf16 v[66:69], v[180:183], v[194:197], v[66:69]
	v_mfma_f32_16x16x32_bf16 v[70:73], v[168:171], v[244:247], 0
	v_mfma_f32_16x16x32_bf16 v[70:73], v[172:175], v[194:197], v[70:73]
	v_mfma_f32_16x16x32_bf16 v[78:81], v[168:171], v[236:239], 0
	v_mfma_f32_16x16x32_bf16 v[78:81], v[172:175], v[240:243], v[78:81]
	s_barrier
	s_add_i32 s10, s13, s42
	s_mov_b32 m0, s10
	ds_read_b128 v[194:197], v151 offset:16384
	ds_read_b128 v[206:209], v151 offset:17408
	ds_read_b128 v[210:213], v151 offset:18432
	ds_read_b128 v[214:217], v151 offset:19456
	ds_read_b128 v[218:221], v151 offset:20480
	ds_read_b128 v[236:239], v151 offset:21504
	ds_read_b128 v[240:243], v151 offset:22528
	ds_read_b128 v[244:247], v151 offset:23552
	global_load_lds_dwordx4 v130, s[84:85]
	s_add_i32 m0, s10, 0x2000
	s_add_u32 s10, s84, 0x20000
	s_addc_u32 s11, s85, 0
	s_add_i32 s9, s9, s42
	global_load_lds_dwordx4 v134, s[84:85]
	s_mov_b32 m0, s9
	s_nop 0
	global_load_lds_dwordx4 v130, s[10:11]
	s_add_i32 m0, s9, 0x2000
	s_nop 0
	global_load_lds_dwordx4 v134, s[10:11]
	s_mov_b32 m0, s51
	s_nop 0
	global_load_lds_dwordx4 v190, s[92:93]
	s_mov_b32 m0, s67
	s_nop 0
	global_load_lds_dwordx4 v132, s[92:93]
	s_nop 0
	s_waitcnt vmcnt(8)
	s_waitcnt lgkmcnt(0)
	s_barrier
; #define PG8_STAGE(bufoff, gbase, voff) do { _Pragma("unroll") for (int _i = 0; _i < 2; ++_i) \
;         __builtin_amdgcn_global_load_lds((const unsigned*)((const char*)(gbase) + (voff)[_i]), (PG8_LAS unsigned*)(lds + (bufoff) + ldsw + _i * 8192), 16, 0, 0); } while (0)
; #define PG8_LDA(dst, b, h) do { _Pragma("unroll") for (int m = 0; m < 4; ++m) _Pragma("unroll") for (int k = 0; k < 2; ++k) dst[m][k] = *(const PG8_LAS bf16x8*)(lds + PG8_SA(b, h) + aoff + m * 2048 + k * 1024); } while (0)
; #define PG8_LDB(dst, b, h) do { _Pragma("unroll") for (int n = 0; n < 2; ++n) _Pragma("unroll") for (int k = 0; k < 2; ++k) dst[n][k] = *(const PG8_LAS bf16x8*)(lds + PG8_SB(b, h) + boff + n * 2048 + k * 1024); } while (0)
; #define PG8_MMA(ai, bj, At, Bt) do { __builtin_amdgcn_s_setprio(1); _Pragma("unroll") for (int m = 0; m < 4; ++m) _Pragma("unroll") for (int n = 0; n < 2; ++n) _Pragma("unroll") for (int k = 0; k < 2; ++k) \
;         acc[ai][bj][m][n] = __builtin_amdgcn_mfma_f32_16x16x32_bf16(Bt[n][k], At[m][k], acc[ai][bj][m][n], 0, 0, 0); __builtin_amdgcn_s_setprio(0); } while (0)
; #define PG8_WAIT_V(n) asm volatile("s_waitcnt vmcnt(" #n ")" ::: "memory")
; #define PG8_WAIT_L(n) asm volatile("s_waitcnt lgkmcnt(" #n ")" ::: "memory")
; #define PG8_BAR __builtin_amdgcn_s_barrier()
; #define PG8_SCHED __builtin_amdgcn_sched_barrier(0)
; template <class Epi, class Sched, bool ALIGN_EPI = false, bool SP2 = false>
; __device__ __forceinline__ void gemm_phase(PG8_LAS unsigned char* lds, const Gemm g, const Sched& S, const Epi& E) {
;     ...
;             PG8_LDA(At, 0, 1); PG8_STAGE(PG8_SB(0, 0), b2, voffB); PG8_STAGE(PG8_SB(0, 1), b2 + hstepB, voffB); PG8_STAGE(PG8_SA(0, 0), a2, voffA);
;             PG8_WAIT_V(8); PG8_WAIT_L(0); PG8_BAR; PG8_MMA(1, 0, At, B0); PG8_MMA(1, 1, At, B1); PG8_BAR; PG8_SCHED;
;             PG8_LDB(B0, 1, 0); PG8_LDB(B1, 1, 1); PG8_SCHED; PG8_LDA(At, 1, 0); PG8_STAGE(PG8_SA(0, 1), a2 + hstep, voffA);
;             PG8_WAIT_V(8); PG8_WAIT_L(0); PG8_BAR; PG8_MMA(0, 0, At, B0); PG8_MMA(0, 1, At, B1); PG8_BAR; PG8_SCHED;
	v_mfma_f32_16x16x32_bf16 v[62:65], v[152:155], v[194:197], 0
	v_mfma_f32_16x16x32_bf16 v[62:65], v[156:159], v[206:209], v[62:65]
	v_mfma_f32_16x16x32_bf16 v[54:57], v[152:155], v[210:213], 0
	v_mfma_f32_16x16x32_bf16 v[54:57], v[156:159], v[214:217], v[54:57]
	v_mfma_f32_16x16x32_bf16 v[50:53], v[160:163], v[210:213], 0
	v_mfma_f32_16x16x32_bf16 v[50:53], v[164:167], v[214:217], v[50:53]
	v_mfma_f32_16x16x32_bf16 v[58:61], v[160:163], v[194:197], 0
	v_mfma_f32_16x16x32_bf16 v[58:61], v[164:167], v[206:209], v[58:61]
	v_mfma_f32_16x16x32_bf16 v[42:45], v[160:163], v[218:221], 0
	v_mfma_f32_16x16x32_bf16 v[42:45], v[164:167], v[236:239], v[42:45]
	v_mfma_f32_16x16x32_bf16 v[34:37], v[160:163], v[240:243], 0
	v_mfma_f32_16x16x32_bf16 v[34:37], v[164:167], v[244:247], v[34:37]
	v_mfma_f32_16x16x32_bf16 v[38:41], v[152:155], v[240:243], 0
	v_mfma_f32_16x16x32_bf16 v[38:41], v[156:159], v[244:247], v[38:41]
	v_mfma_f32_16x16x32_bf16 v[46:49], v[152:155], v[218:221], 0
	v_mfma_f32_16x16x32_bf16 v[46:49], v[156:159], v[236:239], v[46:49]
	v_mfma_f32_16x16x32_bf16 v[30:33], v[168:171], v[194:197], 0
	v_mfma_f32_16x16x32_bf16 v[30:33], v[172:175], v[206:209], v[30:33]
	v_mfma_f32_16x16x32_bf16 v[22:25], v[168:171], v[210:213], 0
	v_mfma_f32_16x16x32_bf16 v[22:25], v[172:175], v[214:217], v[22:25]
	v_mfma_f32_16x16x32_bf16 v[18:21], v[176:179], v[210:213], 0
	v_mfma_f32_16x16x32_bf16 v[18:21], v[180:183], v[214:217], v[18:21]
	v_mfma_f32_16x16x32_bf16 v[26:29], v[176:179], v[194:197], 0
	v_mfma_f32_16x16x32_bf16 v[26:29], v[180:183], v[206:209], v[26:29]
	v_mfma_f32_16x16x32_bf16 v[10:13], v[176:179], v[218:221], 0
	v_mfma_f32_16x16x32_bf16 v[10:13], v[180:183], v[236:239], v[10:13]
	v_mfma_f32_16x16x32_bf16 v[2:5], v[176:179], v[240:243], 0
	v_mfma_f32_16x16x32_bf16 v[2:5], v[180:183], v[244:247], v[2:5]
	v_mfma_f32_16x16x32_bf16 v[6:9], v[168:171], v[240:243], 0
	v_mfma_f32_16x16x32_bf16 v[6:9], v[172:175], v[244:247], v[6:9]
	v_mfma_f32_16x16x32_bf16 v[14:17], v[168:171], v[218:221], 0
	v_mfma_f32_16x16x32_bf16 v[14:17], v[172:175], v[236:239], v[14:17]
	s_barrier
	s_add_i32 s9, 0, 0x18000
	s_add_i32 s12, 0, 0x1c000
	ds_read_b128 v[152:155], v198
	ds_read_b128 v[156:159], v198 offset:1024
	ds_read_b128 v[160:163], v198 offset:2048
	ds_read_b128 v[164:167], v198 offset:3072
	ds_read_b128 v[168:171], v199
	ds_read_b128 v[172:175], v199 offset:1024
	ds_read_b128 v[176:179], v199 offset:2048
	ds_read_b128 v[180:183], v199 offset:3072
	s_add_u32 s10, s92, 0x80000
	s_addc_u32 s11, s93, 0
	s_mov_b32 m0, s74
	ds_read_b128 v[194:197], v151 offset:32768
	ds_read_b128 v[206:209], v151 offset:33792
	ds_read_b128 v[210:213], v151 offset:34816
	ds_read_b128 v[214:217], v151 offset:35840
	ds_read_b128 v[218:221], v151 offset:36864
	ds_read_b128 v[236:239], v151 offset:37888
	ds_read_b128 v[240:243], v151 offset:38912
	ds_read_b128 v[244:247], v151 offset:39936
	global_load_lds_dwordx4 v190, s[10:11]
	s_mov_b32 m0, s75
	s_nop 0
	global_load_lds_dwordx4 v132, s[10:11]
	s_waitcnt vmcnt(8)
	s_waitcnt lgkmcnt(0)
	s_barrier
	v_mfma_f32_16x16x32_bf16 v[126:129], v[152:155], v[194:197], v[126:129]
	v_mfma_f32_16x16x32_bf16 v[126:129], v[156:159], v[206:209], v[126:129]
	v_mfma_f32_16x16x32_bf16 v[118:121], v[152:155], v[210:213], v[118:121]
	v_mfma_f32_16x16x32_bf16 v[118:121], v[156:159], v[214:217], v[118:121]
	v_mfma_f32_16x16x32_bf16 v[114:117], v[160:163], v[210:213], v[114:117]
	v_mfma_f32_16x16x32_bf16 v[114:117], v[164:167], v[214:217], v[114:117]
	v_mfma_f32_16x16x32_bf16 v[122:125], v[160:163], v[194:197], v[122:125]
	v_mfma_f32_16x16x32_bf16 v[122:125], v[164:167], v[206:209], v[122:125]
	v_mfma_f32_16x16x32_bf16 v[106:109], v[160:163], v[218:221], v[106:109]
	v_mfma_f32_16x16x32_bf16 v[106:109], v[164:167], v[236:239], v[106:109]
	v_mfma_f32_16x16x32_bf16 v[98:101], v[160:163], v[240:243], v[98:101]
	v_mfma_f32_16x16x32_bf16 v[98:101], v[164:167], v[244:247], v[98:101]
	v_mfma_f32_16x16x32_bf16 v[102:105], v[152:155], v[240:243], v[102:105]
	v_mfma_f32_16x16x32_bf16 v[102:105], v[156:159], v[244:247], v[102:105]
	v_mfma_f32_16x16x32_bf16 v[110:113], v[152:155], v[218:221], v[110:113]
	v_mfma_f32_16x16x32_bf16 v[110:113], v[156:159], v[236:239], v[110:113]
	v_mfma_f32_16x16x32_bf16 v[94:97], v[168:171], v[194:197], v[94:97]
	v_mfma_f32_16x16x32_bf16 v[94:97], v[172:175], v[206:209], v[94:97]
	v_mfma_f32_16x16x32_bf16 v[86:89], v[168:171], v[210:213], v[86:89]
	v_mfma_f32_16x16x32_bf16 v[86:89], v[172:175], v[214:217], v[86:89]
	v_mfma_f32_16x16x32_bf16 v[82:85], v[176:179], v[210:213], v[82:85]
	v_mfma_f32_16x16x32_bf16 v[82:85], v[180:183], v[214:217], v[82:85]
	v_mfma_f32_16x16x32_bf16 v[90:93], v[176:179], v[194:197], v[90:93]
	v_mfma_f32_16x16x32_bf16 v[90:93], v[180:183], v[206:209], v[90:93]
	v_mfma_f32_16x16x32_bf16 v[74:77], v[176:179], v[218:221], v[74:77]
	v_mfma_f32_16x16x32_bf16 v[74:77], v[180:183], v[236:239], v[74:77]
	v_mfma_f32_16x16x32_bf16 v[66:69], v[176:179], v[240:243], v[66:69]
	v_mfma_f32_16x16x32_bf16 v[66:69], v[180:183], v[244:247], v[66:69]
	v_mfma_f32_16x16x32_bf16 v[70:73], v[168:171], v[240:243], v[70:73]
	v_mfma_f32_16x16x32_bf16 v[70:73], v[172:175], v[244:247], v[70:73]
	v_mfma_f32_16x16x32_bf16 v[78:81], v[168:171], v[218:221], v[78:81]
	v_mfma_f32_16x16x32_bf16 v[78:81], v[172:175], v[236:239], v[78:81]
	s_barrier
; #define PG8_STAGE(bufoff, gbase, voff) do { _Pragma("unroll") for (int _i = 0; _i < 2; ++_i) \
;         __builtin_amdgcn_global_load_lds((const unsigned*)((const char*)(gbase) + (voff)[_i]), (PG8_LAS unsigned*)(lds + (bufoff) + ldsw + _i * 8192), 16, 0, 0); } while (0)
; #define PG8_LDA(dst, b, h) do { _Pragma("unroll") for (int m = 0; m < 4; ++m) _Pragma("unroll") for (int k = 0; k < 2; ++k) dst[m][k] = *(const PG8_LAS bf16x8*)(lds + PG8_SA(b, h) + aoff + m * 2048 + k * 1024); } while (0)
; #define PG8_LDB(dst, b, h) do { _Pragma("unroll") for (int n = 0; n < 2; ++n) _Pragma("unroll") for (int k = 0; k < 2; ++k) dst[n][k] = *(const PG8_LAS bf16x8*)(lds + PG8_SB(b, h) + boff + n * 2048 + k * 1024); } while (0)
; template <class Epi, class Sched, bool ALIGN_EPI = false, bool SP2 = false>
; __device__ __forceinline__ void gemm_phase(PG8_LAS unsigned char* lds, const Gemm g, const Sched& S, const Epi& E) {
;     ...
;         for (int t = 0; t < nt; t += 2) {
;             const bool last = (t == nt - 2);
;             const char* a1 = cA + (size_t)(t + 1) * kstep;
;             const char* a2 = last ? nA : cA + (size_t)(t + 2) * kstep; const char* b2 = last ? nB : cB + (size_t)(t + 2) * kstep;
;             const char* a3 = a2 + kstep; const char* b3 = b2 + kstep;
;             if (last && has_next) S.a_ready(nxt);
;             if constexpr (SP2) {
;             PG8_LDB(B0, 0, 0); PG8_LDB(B1, 0, 1); PG8_SCHED; PG8_LDA(At, 0, 0); PG8_STAGE(PG8_SA(1, 1), a1 + hstep, voffA);
;             PG8_WAIT_V(8); PG8_WAIT_L(0); PG8_BAR; PG8_MMA(0, 0, At, B0); PG8_MMA(0, 1, At, B1); PG8_BAR; PG8_SCHED;
;             PG8_LDA(At, 0, 1); PG8_STAGE(PG8_SB(0, 0), b2, voffB); PG8_STAGE(PG8_SB(0, 1), b2 + hstepB, voffB); PG8_STAGE(PG8_SA(0, 0), a2, voffA);
;             PG8_WAIT_V(8); PG8_WAIT_L(0); PG8_BAR; PG8_MMA(1, 0, At, B0); PG8_MMA(1, 1, At, B1); PG8_BAR; PG8_SCHED;
;             PG8_LDB(B0, 1, 0); PG8_LDB(B1, 1, 1); PG8_SCHED; PG8_LDA(At, 1, 0); PG8_STAGE(PG8_SA(0, 1), a2 + hstep, voffA);
;             PG8_WAIT_V(8); PG8_WAIT_L(0); PG8_BAR; PG8_MMA(0, 0, At, B0); PG8_MMA(0, 1, At, B1); PG8_BAR; PG8_SCHED;
;             PG8_LDA(At, 1, 1); PG8_STAGE(PG8_SB(1, 0), b3, voffB); PG8_STAGE(PG8_SB(1, 1), b3 + hstepB, voffB); PG8_STAGE(PG8_SA(1, 0), a3, voffA);
;             PG8_WAIT_V(8); PG8_WAIT_L(0); PG8_BAR; PG8_MMA(1, 0, At, B0); PG8_MMA(1, 1, At, B1); PG8_BAR; PG8_SCHED;
	s_add_i32 s9, s9, s42
	s_mov_b32 m0, s9
	ds_read_b128 v[194:197], v151 offset:49152
	ds_read_b128 v[206:209], v151 offset:50176
	ds_read_b128 v[210:213], v151 offset:51200
	ds_read_b128 v[214:217], v151 offset:52224
	ds_read_b128 v[218:221], v151 offset:53248
	ds_read_b128 v[236:239], v151 offset:54272
	ds_read_b128 v[240:243], v151 offset:55296
	ds_read_b128 v[244:247], v151 offset:56320
	s_add_u32 s100, s84, s60
	s_addc_u32 s101, s85, s61
	global_load_lds_dwordx4 v130, s[100:101]
	s_add_i32 m0, s9, 0x2000
	s_add_u32 s10, s84, 0x20080
	s_addc_u32 s11, s85, 0
	s_add_i32 s9, s12, s42
	global_load_lds_dwordx4 v134, s[100:101]
	s_mov_b32 m0, s9
	s_nop 0
	global_load_lds_dwordx4 v130, s[10:11]
	s_add_i32 m0, s9, 0x2000
	s_nop 0
	global_load_lds_dwordx4 v134, s[10:11]
	s_mov_b32 m0, s82
	s_add_u32 s100, s92, s60
	s_addc_u32 s101, s93, s61
	global_load_lds_dwordx4 v190, s[100:101]
	s_mov_b32 m0, s86
	s_nop 0
	global_load_lds_dwordx4 v132, s[100:101]
	s_waitcnt vmcnt(8)
	s_waitcnt lgkmcnt(0)
	s_barrier
	v_mfma_f32_16x16x32_bf16 v[62:65], v[152:155], v[194:197], v[62:65]
	v_mfma_f32_16x16x32_bf16 v[62:65], v[156:159], v[206:209], v[62:65]
	v_mfma_f32_16x16x32_bf16 v[54:57], v[152:155], v[210:213], v[54:57]
	v_mfma_f32_16x16x32_bf16 v[54:57], v[156:159], v[214:217], v[54:57]
	v_mfma_f32_16x16x32_bf16 v[50:53], v[160:163], v[210:213], v[50:53]
	v_mfma_f32_16x16x32_bf16 v[50:53], v[164:167], v[214:217], v[50:53]
	v_mfma_f32_16x16x32_bf16 v[58:61], v[160:163], v[194:197], v[58:61]
	v_mfma_f32_16x16x32_bf16 v[58:61], v[164:167], v[206:209], v[58:61]
	v_mfma_f32_16x16x32_bf16 v[42:45], v[160:163], v[218:221], v[42:45]
	v_mfma_f32_16x16x32_bf16 v[42:45], v[164:167], v[236:239], v[42:45]
	v_mfma_f32_16x16x32_bf16 v[34:37], v[160:163], v[240:243], v[34:37]
	v_mfma_f32_16x16x32_bf16 v[34:37], v[164:167], v[244:247], v[34:37]
	v_mfma_f32_16x16x32_bf16 v[38:41], v[152:155], v[240:243], v[38:41]
	v_mfma_f32_16x16x32_bf16 v[38:41], v[156:159], v[244:247], v[38:41]
	v_mfma_f32_16x16x32_bf16 v[46:49], v[152:155], v[218:221], v[46:49]
	v_mfma_f32_16x16x32_bf16 v[46:49], v[156:159], v[236:239], v[46:49]
	v_mfma_f32_16x16x32_bf16 v[30:33], v[168:171], v[194:197], v[30:33]
	v_mfma_f32_16x16x32_bf16 v[30:33], v[172:175], v[206:209], v[30:33]
	v_mfma_f32_16x16x32_bf16 v[22:25], v[168:171], v[210:213], v[22:25]
	v_mfma_f32_16x16x32_bf16 v[22:25], v[172:175], v[214:217], v[22:25]
	v_mfma_f32_16x16x32_bf16 v[18:21], v[176:179], v[210:213], v[18:21]
	v_mfma_f32_16x16x32_bf16 v[18:21], v[180:183], v[214:217], v[18:21]
	v_mfma_f32_16x16x32_bf16 v[26:29], v[176:179], v[194:197], v[26:29]
	v_mfma_f32_16x16x32_bf16 v[26:29], v[180:183], v[206:209], v[26:29]
	v_mfma_f32_16x16x32_bf16 v[10:13], v[176:179], v[218:221], v[10:13]
	v_mfma_f32_16x16x32_bf16 v[10:13], v[180:183], v[236:239], v[10:13]
	v_mfma_f32_16x16x32_bf16 v[2:5], v[176:179], v[240:243], v[2:5]
	v_mfma_f32_16x16x32_bf16 v[2:5], v[180:183], v[244:247], v[2:5]
	v_mfma_f32_16x16x32_bf16 v[6:9], v[168:171], v[240:243], v[6:9]
	v_mfma_f32_16x16x32_bf16 v[6:9], v[172:175], v[244:247], v[6:9]
	v_mfma_f32_16x16x32_bf16 v[14:17], v[168:171], v[218:221], v[14:17]
	v_mfma_f32_16x16x32_bf16 v[14:17], v[172:175], v[236:239], v[14:17]
	s_barrier
	s_add_i32 s8, s8, 2
	s_add_u32 s80, s80, 0x100
	s_addc_u32 s81, s81, 0
	s_cmp_gt_u32 s8, 29
.LBB0_1233:
	s_add_u32 s9, s68, s80
	s_addc_u32 s10, s69, s81
	s_add_u32 s9, s9, 0x100
	s_addc_u32 s10, s10, 0
	s_add_u32 s100, s9, 0x7ff80
	s_addc_u32 s101, s10, 0
	s_add_u32 s11, s36, s80
	s_addc_u32 s12, s37, s81
	s_add_i32 s13, 0, 0x10000
	s_cmpk_eq_i32 s80, 0xf00
	s_cselect_b32 s93, s4, s10
	s_cselect_b32 s92, s5, s9
	s_cselect_b32 s85, s6, s12
	s_cselect_b32 s84, s7, s11
	s_add_i32 s9, 0, 0x14000
	ds_read_b128 v[152:155], v186
	ds_read_b128 v[156:159], v186 offset:1024
	ds_read_b128 v[160:163], v186 offset:2048
	ds_read_b128 v[164:167], v186 offset:3072
	ds_read_b128 v[168:171], v187
	ds_read_b128 v[172:175], v187 offset:1024
	ds_read_b128 v[176:179], v187 offset:2048
	ds_read_b128 v[180:183], v187 offset:3072
	s_add_i32 m0, s51, 0xc000
	ds_read_b128 v[206:209], v151
	ds_read_b128 v[210:213], v151 offset:1024
	ds_read_b128 v[214:217], v151 offset:2048
	ds_read_b128 v[218:221], v151 offset:3072
	ds_read_b128 v[236:239], v151 offset:4096
	ds_read_b128 v[240:243], v151 offset:5120
	ds_read_b128 v[244:247], v151 offset:6144
	ds_read_b128 v[194:197], v151 offset:7168
	global_load_lds_dwordx4 v136, s[100:101]
	s_add_i32 m0, s51, 0xe000
	s_nop 0
	global_load_lds_dwordx4 v138, s[100:101]
	s_nop 0
	s_waitcnt vmcnt(8)
	s_waitcnt lgkmcnt(0)
	s_barrier
; #define PG8_STAGE(bufoff, gbase, voff) do { _Pragma("unroll") for (int _i = 0; _i < 2; ++_i) \
;         __builtin_amdgcn_global_load_lds((const unsigned*)((const char*)(gbase) + (voff)[_i]), (PG8_LAS unsigned*)(lds + (bufoff) + ldsw + _i * 8192), 16, 0, 0); } while (0)
; #define PG8_LDA(dst, b, h) do { _Pragma("unroll") for (int m = 0; m < 4; ++m) _Pragma("unroll") for (int k = 0; k < 2; ++k) dst[m][k] = *(const PG8_LAS bf16x8*)(lds + PG8_SA(b, h) + aoff + m * 2048 + k * 1024); } while (0)
; #define PG8_LDB(dst, b, h) do { _Pragma("unroll") for (int n = 0; n < 2; ++n) _Pragma("unroll") for (int k = 0; k < 2; ++k) dst[n][k] = *(const PG8_LAS bf16x8*)(lds + PG8_SB(b, h) + boff + n * 2048 + k * 1024); } while (0)
; #define PG8_MMA(ai, bj, At, Bt) do { __builtin_amdgcn_s_setprio(1); _Pragma("unroll") for (int m = 0; m < 4; ++m) _Pragma("unroll") for (int n = 0; n < 2; ++n) _Pragma("unroll") for (int k = 0; k < 2; ++k) \
;         acc[ai][bj][m][n] = __builtin_amdgcn_mfma_f32_16x16x32_bf16(Bt[n][k], At[m][k], acc[ai][bj][m][n], 0, 0, 0); __builtin_amdgcn_s_setprio(0); } while (0)
; #define PG8_WAIT_V(n) asm volatile("s_waitcnt vmcnt(" #n ")" ::: "memory")
; #define PG8_WAIT_L(n) asm volatile("s_waitcnt lgkmcnt(" #n ")" ::: "memory")
; #define PG8_BAR __builtin_amdgcn_s_barrier()
; #define PG8_SCHED __builtin_amdgcn_sched_barrier(0)
; template <class Epi, class Sched, bool ALIGN_EPI = false, bool SP2 = false>
; __device__ __forceinline__ void gemm_phase(PG8_LAS unsigned char* lds, const Gemm g, const Sched& S, const Epi& E) {
;     ...
;             PG8_LDB(B0, 0, 0); PG8_LDB(B1, 0, 1); PG8_SCHED; PG8_LDA(At, 0, 0); PG8_STAGE(PG8_SA(1, 1), a1 + hstep, voffA);
;             PG8_WAIT_V(8); PG8_WAIT_L(0); PG8_BAR; PG8_MMA(0, 0, At, B0); PG8_MMA(0, 1, At, B1); PG8_BAR; PG8_SCHED;
;             PG8_LDA(At, 0, 1); PG8_STAGE(PG8_SB(0, 0), b2, voffB); PG8_STAGE(PG8_SB(0, 1), b2 + hstepB, voffB); PG8_STAGE(PG8_SA(0, 0), a2, voffA);
;             PG8_WAIT_V(8); PG8_WAIT_L(0); PG8_BAR; PG8_MMA(1, 0, At, B0); PG8_MMA(1, 1, At, B1); PG8_BAR; PG8_SCHED;
	v_mfma_f32_16x16x32_bf16 v[126:129], v[152:155], v[206:209], v[126:129]
	v_mfma_f32_16x16x32_bf16 v[126:129], v[156:159], v[210:213], v[126:129]
	v_mfma_f32_16x16x32_bf16 v[118:121], v[152:155], v[214:217], v[118:121]
	v_mfma_f32_16x16x32_bf16 v[118:121], v[156:159], v[218:221], v[118:121]
	v_mfma_f32_16x16x32_bf16 v[114:117], v[160:163], v[214:217], v[114:117]
	v_mfma_f32_16x16x32_bf16 v[114:117], v[164:167], v[218:221], v[114:117]
	v_mfma_f32_16x16x32_bf16 v[122:125], v[160:163], v[206:209], v[122:125]
	v_mfma_f32_16x16x32_bf16 v[122:125], v[164:167], v[210:213], v[122:125]
	v_mfma_f32_16x16x32_bf16 v[106:109], v[160:163], v[236:239], v[106:109]
	v_mfma_f32_16x16x32_bf16 v[106:109], v[164:167], v[240:243], v[106:109]
	v_mfma_f32_16x16x32_bf16 v[98:101], v[160:163], v[244:247], v[98:101]
	v_mfma_f32_16x16x32_bf16 v[98:101], v[164:167], v[194:197], v[98:101]
	v_mfma_f32_16x16x32_bf16 v[102:105], v[152:155], v[244:247], v[102:105]
	v_mfma_f32_16x16x32_bf16 v[102:105], v[156:159], v[194:197], v[102:105]
	v_mfma_f32_16x16x32_bf16 v[110:113], v[152:155], v[236:239], v[110:113]
	v_mfma_f32_16x16x32_bf16 v[110:113], v[156:159], v[240:243], v[110:113]
	v_mfma_f32_16x16x32_bf16 v[94:97], v[168:171], v[206:209], v[94:97]
	v_mfma_f32_16x16x32_bf16 v[94:97], v[172:175], v[210:213], v[94:97]
	v_mfma_f32_16x16x32_bf16 v[86:89], v[168:171], v[214:217], v[86:89]
	v_mfma_f32_16x16x32_bf16 v[86:89], v[172:175], v[218:221], v[86:89]
	v_mfma_f32_16x16x32_bf16 v[82:85], v[176:179], v[214:217], v[82:85]
	v_mfma_f32_16x16x32_bf16 v[82:85], v[180:183], v[218:221], v[82:85]
	v_mfma_f32_16x16x32_bf16 v[90:93], v[176:179], v[206:209], v[90:93]
	v_mfma_f32_16x16x32_bf16 v[90:93], v[180:183], v[210:213], v[90:93]
	v_mfma_f32_16x16x32_bf16 v[74:77], v[176:179], v[236:239], v[74:77]
	v_mfma_f32_16x16x32_bf16 v[74:77], v[180:183], v[240:243], v[74:77]
	v_mfma_f32_16x16x32_bf16 v[66:69], v[176:179], v[244:247], v[66:69]
	v_mfma_f32_16x16x32_bf16 v[66:69], v[180:183], v[194:197], v[66:69]
	v_mfma_f32_16x16x32_bf16 v[70:73], v[168:171], v[244:247], v[70:73]
	v_mfma_f32_16x16x32_bf16 v[70:73], v[172:175], v[194:197], v[70:73]
	v_mfma_f32_16x16x32_bf16 v[78:81], v[168:171], v[236:239], v[78:81]
	v_mfma_f32_16x16x32_bf16 v[78:81], v[172:175], v[240:243], v[78:81]
	s_barrier
	s_add_i32 s10, s13, s42
	s_mov_b32 m0, s10
	ds_read_b128 v[194:197], v151 offset:16384
	ds_read_b128 v[206:209], v151 offset:17408
	ds_read_b128 v[210:213], v151 offset:18432
	ds_read_b128 v[214:217], v151 offset:19456
	ds_read_b128 v[218:221], v151 offset:20480
	ds_read_b128 v[236:239], v151 offset:21504
	ds_read_b128 v[240:243], v151 offset:22528
	ds_read_b128 v[244:247], v151 offset:23552
	global_load_lds_dwordx4 v130, s[84:85]
	s_add_i32 m0, s10, 0x2000
	s_add_u32 s10, s84, 0x20000
	s_addc_u32 s11, s85, 0
	s_add_i32 s9, s9, s42
	global_load_lds_dwordx4 v134, s[84:85]
	s_mov_b32 m0, s9
	s_nop 0
	global_load_lds_dwordx4 v130, s[10:11]
	s_add_i32 m0, s9, 0x2000
	s_nop 0
	global_load_lds_dwordx4 v134, s[10:11]
	s_mov_b32 m0, s51
	s_nop 0
	global_load_lds_dwordx4 v190, s[92:93]
	s_mov_b32 m0, s67
	s_nop 0
	global_load_lds_dwordx4 v132, s[92:93]
	s_nop 0
	s_waitcnt vmcnt(8)
	s_waitcnt lgkmcnt(0)
	s_barrier
	v_mfma_f32_16x16x32_bf16 v[62:65], v[152:155], v[194:197], v[62:65]
	v_mfma_f32_16x16x32_bf16 v[62:65], v[156:159], v[206:209], v[62:65]
	v_mfma_f32_16x16x32_bf16 v[54:57], v[152:155], v[210:213], v[54:57]
	v_mfma_f32_16x16x32_bf16 v[54:57], v[156:159], v[214:217], v[54:57]
	v_mfma_f32_16x16x32_bf16 v[50:53], v[160:163], v[210:213], v[50:53]
	v_mfma_f32_16x16x32_bf16 v[50:53], v[164:167], v[214:217], v[50:53]
	v_mfma_f32_16x16x32_bf16 v[58:61], v[160:163], v[194:197], v[58:61]
	v_mfma_f32_16x16x32_bf16 v[58:61], v[164:167], v[206:209], v[58:61]
	v_mfma_f32_16x16x32_bf16 v[42:45], v[160:163], v[218:221], v[42:45]
	v_mfma_f32_16x16x32_bf16 v[42:45], v[164:167], v[236:239], v[42:45]
	v_mfma_f32_16x16x32_bf16 v[34:37], v[160:163], v[240:243], v[34:37]
	v_mfma_f32_16x16x32_bf16 v[34:37], v[164:167], v[244:247], v[34:37]
	v_mfma_f32_16x16x32_bf16 v[38:41], v[152:155], v[240:243], v[38:41]
	v_mfma_f32_16x16x32_bf16 v[38:41], v[156:159], v[244:247], v[38:41]
	v_mfma_f32_16x16x32_bf16 v[46:49], v[152:155], v[218:221], v[46:49]
	v_mfma_f32_16x16x32_bf16 v[46:49], v[156:159], v[236:239], v[46:49]
	v_mfma_f32_16x16x32_bf16 v[30:33], v[168:171], v[194:197], v[30:33]
	v_mfma_f32_16x16x32_bf16 v[30:33], v[172:175], v[206:209], v[30:33]
	v_mfma_f32_16x16x32_bf16 v[22:25], v[168:171], v[210:213], v[22:25]
	v_mfma_f32_16x16x32_bf16 v[22:25], v[172:175], v[214:217], v[22:25]
	v_mfma_f32_16x16x32_bf16 v[18:21], v[176:179], v[210:213], v[18:21]
	v_mfma_f32_16x16x32_bf16 v[18:21], v[180:183], v[214:217], v[18:21]
	v_mfma_f32_16x16x32_bf16 v[26:29], v[176:179], v[194:197], v[26:29]
	v_mfma_f32_16x16x32_bf16 v[26:29], v[180:183], v[206:209], v[26:29]
	v_mfma_f32_16x16x32_bf16 v[10:13], v[176:179], v[218:221], v[10:13]
	v_mfma_f32_16x16x32_bf16 v[10:13], v[180:183], v[236:239], v[10:13]
	v_mfma_f32_16x16x32_bf16 v[2:5], v[176:179], v[240:243], v[2:5]
	v_mfma_f32_16x16x32_bf16 v[2:5], v[180:183], v[244:247], v[2:5]
	v_mfma_f32_16x16x32_bf16 v[6:9], v[168:171], v[240:243], v[6:9]
	v_mfma_f32_16x16x32_bf16 v[6:9], v[172:175], v[244:247], v[6:9]
	v_mfma_f32_16x16x32_bf16 v[14:17], v[168:171], v[218:221], v[14:17]
	v_mfma_f32_16x16x32_bf16 v[14:17], v[172:175], v[236:239], v[14:17]
	s_barrier
; #define PG8_STAGE(bufoff, gbase, voff) do { _Pragma("unroll") for (int _i = 0; _i < 2; ++_i) \
;         __builtin_amdgcn_global_load_lds((const unsigned*)((const char*)(gbase) + (voff)[_i]), (PG8_LAS unsigned*)(lds + (bufoff) + ldsw + _i * 8192), 16, 0, 0); } while (0)
; #define PG8_LDA(dst, b, h) do { _Pragma("unroll") for (int m = 0; m < 4; ++m) _Pragma("unroll") for (int k = 0; k < 2; ++k) dst[m][k] = *(const PG8_LAS bf16x8*)(lds + PG8_SA(b, h) + aoff + m * 2048 + k * 1024); } while (0)
; #define PG8_LDB(dst, b, h) do { _Pragma("unroll") for (int n = 0; n < 2; ++n) _Pragma("unroll") for (int k = 0; k < 2; ++k) dst[n][k] = *(const PG8_LAS bf16x8*)(lds + PG8_SB(b, h) + boff + n * 2048 + k * 1024); } while (0)
; #define PG8_MMA(ai, bj, At, Bt) do { __builtin_amdgcn_s_setprio(1); _Pragma("unroll") for (int m = 0; m < 4; ++m) _Pragma("unroll") for (int n = 0; n < 2; ++n) _Pragma("unroll") for (int k = 0; k < 2; ++k) \
;         acc[ai][bj][m][n] = __builtin_amdgcn_mfma_f32_16x16x32_bf16(Bt[n][k], At[m][k], acc[ai][bj][m][n], 0, 0, 0); __builtin_amdgcn_s_setprio(0); } while (0)
; #define PG8_WAIT_V(n) asm volatile("s_waitcnt vmcnt(" #n ")" ::: "memory")
; #define PG8_WAIT_L(n) asm volatile("s_waitcnt lgkmcnt(" #n ")" ::: "memory")
; #define PG8_BAR __builtin_amdgcn_s_barrier()
; #define PG8_SCHED __builtin_amdgcn_sched_barrier(0)
; template <class Epi, class Sched, bool ALIGN_EPI = false, bool SP2 = false>
; __device__ __forceinline__ void gemm_phase(PG8_LAS unsigned char* lds, const Gemm g, const Sched& S, const Epi& E) {
;     ...
;             PG8_LDB(B0, 1, 0); PG8_LDB(B1, 1, 1); PG8_SCHED; PG8_LDA(At, 1, 0); PG8_STAGE(PG8_SA(0, 1), a2 + hstep, voffA);
;             PG8_WAIT_V(8); PG8_WAIT_L(0); PG8_BAR; PG8_MMA(0, 0, At, B0); PG8_MMA(0, 1, At, B1); PG8_BAR; PG8_SCHED;
;             PG8_LDA(At, 1, 1); PG8_STAGE(PG8_SB(1, 0), b3, voffB); PG8_STAGE(PG8_SB(1, 1), b3 + hstepB, voffB); PG8_STAGE(PG8_SA(1, 0), a3, voffA);
;             PG8_WAIT_V(8); PG8_WAIT_L(0); PG8_BAR; PG8_MMA(1, 0, At, B0); PG8_MMA(1, 1, At, B1); PG8_BAR; PG8_SCHED;
;     ...
;         if constexpr (ALIGN_EPI) { if (wr == 0) PG8_BAR; }
	s_add_i32 s9, 0, 0x18000
	s_add_i32 s12, 0, 0x1c000
	ds_read_b128 v[152:155], v198
	ds_read_b128 v[156:159], v198 offset:1024
	ds_read_b128 v[160:163], v198 offset:2048
	ds_read_b128 v[164:167], v198 offset:3072
	ds_read_b128 v[168:171], v199
	ds_read_b128 v[172:175], v199 offset:1024
	ds_read_b128 v[176:179], v199 offset:2048
	ds_read_b128 v[180:183], v199 offset:3072
	s_add_u32 s10, s92, 0x80000
	s_addc_u32 s11, s93, 0
	s_mov_b32 m0, s74
	ds_read_b128 v[194:197], v151 offset:32768
	ds_read_b128 v[206:209], v151 offset:33792
	ds_read_b128 v[210:213], v151 offset:34816
	ds_read_b128 v[214:217], v151 offset:35840
	ds_read_b128 v[218:221], v151 offset:36864
	ds_read_b128 v[236:239], v151 offset:37888
	ds_read_b128 v[240:243], v151 offset:38912
	ds_read_b128 v[244:247], v151 offset:39936
	global_load_lds_dwordx4 v190, s[10:11]
	s_mov_b32 m0, s75
	s_nop 0
	global_load_lds_dwordx4 v132, s[10:11]
	s_waitcnt vmcnt(8)
	s_waitcnt lgkmcnt(0)
	s_barrier
	v_mfma_f32_16x16x32_bf16 v[126:129], v[152:155], v[194:197], v[126:129]
	v_mfma_f32_16x16x32_bf16 v[126:129], v[156:159], v[206:209], v[126:129]
	v_mfma_f32_16x16x32_bf16 v[118:121], v[152:155], v[210:213], v[118:121]
	v_mfma_f32_16x16x32_bf16 v[118:121], v[156:159], v[214:217], v[118:121]
	v_mfma_f32_16x16x32_bf16 v[114:117], v[160:163], v[210:213], v[114:117]
	v_mfma_f32_16x16x32_bf16 v[114:117], v[164:167], v[214:217], v[114:117]
	v_mfma_f32_16x16x32_bf16 v[122:125], v[160:163], v[194:197], v[122:125]
	v_mfma_f32_16x16x32_bf16 v[122:125], v[164:167], v[206:209], v[122:125]
	v_mfma_f32_16x16x32_bf16 v[106:109], v[160:163], v[218:221], v[106:109]
	v_mfma_f32_16x16x32_bf16 v[106:109], v[164:167], v[236:239], v[106:109]
	v_mfma_f32_16x16x32_bf16 v[98:101], v[160:163], v[240:243], v[98:101]
	v_mfma_f32_16x16x32_bf16 v[98:101], v[164:167], v[244:247], v[98:101]
	v_mfma_f32_16x16x32_bf16 v[102:105], v[152:155], v[240:243], v[102:105]
	v_mfma_f32_16x16x32_bf16 v[102:105], v[156:159], v[244:247], v[102:105]
	v_mfma_f32_16x16x32_bf16 v[110:113], v[152:155], v[218:221], v[110:113]
	v_mfma_f32_16x16x32_bf16 v[110:113], v[156:159], v[236:239], v[110:113]
	v_mfma_f32_16x16x32_bf16 v[94:97], v[168:171], v[194:197], v[94:97]
	v_mfma_f32_16x16x32_bf16 v[94:97], v[172:175], v[206:209], v[94:97]
	v_mfma_f32_16x16x32_bf16 v[86:89], v[168:171], v[210:213], v[86:89]
	v_mfma_f32_16x16x32_bf16 v[86:89], v[172:175], v[214:217], v[86:89]
	v_mfma_f32_16x16x32_bf16 v[82:85], v[176:179], v[210:213], v[82:85]
	v_mfma_f32_16x16x32_bf16 v[82:85], v[180:183], v[214:217], v[82:85]
	v_mfma_f32_16x16x32_bf16 v[90:93], v[176:179], v[194:197], v[90:93]
	v_mfma_f32_16x16x32_bf16 v[90:93], v[180:183], v[206:209], v[90:93]
	v_mfma_f32_16x16x32_bf16 v[74:77], v[176:179], v[218:221], v[74:77]
	v_mfma_f32_16x16x32_bf16 v[74:77], v[180:183], v[236:239], v[74:77]
	v_mfma_f32_16x16x32_bf16 v[66:69], v[176:179], v[240:243], v[66:69]
	v_mfma_f32_16x16x32_bf16 v[66:69], v[180:183], v[244:247], v[66:69]
	v_mfma_f32_16x16x32_bf16 v[70:73], v[168:171], v[240:243], v[70:73]
	v_mfma_f32_16x16x32_bf16 v[70:73], v[172:175], v[244:247], v[70:73]
	v_mfma_f32_16x16x32_bf16 v[78:81], v[168:171], v[218:221], v[78:81]
	v_mfma_f32_16x16x32_bf16 v[78:81], v[172:175], v[236:239], v[78:81]
	s_barrier
	s_add_i32 s9, s9, s42
	s_mov_b32 m0, s9
	ds_read_b128 v[194:197], v151 offset:49152
	ds_read_b128 v[206:209], v151 offset:50176
	ds_read_b128 v[210:213], v151 offset:51200
	ds_read_b128 v[214:217], v151 offset:52224
	ds_read_b128 v[218:221], v151 offset:53248
	ds_read_b128 v[236:239], v151 offset:54272
	ds_read_b128 v[240:243], v151 offset:55296
	ds_read_b128 v[244:247], v151 offset:56320
	s_add_u32 s100, s84, s60
	s_addc_u32 s101, s85, s61
	global_load_lds_dwordx4 v130, s[100:101]
	s_add_i32 m0, s9, 0x2000
	s_add_u32 s10, s84, 0x20080
	s_addc_u32 s11, s85, 0
	s_add_i32 s9, s12, s42
	global_load_lds_dwordx4 v134, s[100:101]
	s_mov_b32 m0, s9
	s_nop 0
	global_load_lds_dwordx4 v130, s[10:11]
	s_add_i32 m0, s9, 0x2000
	s_nop 0
	global_load_lds_dwordx4 v134, s[10:11]
	s_mov_b32 m0, s82
	s_add_u32 s100, s92, s60
	s_addc_u32 s101, s93, s61
	global_load_lds_dwordx4 v190, s[100:101]
	s_mov_b32 m0, s86
	s_nop 0
	global_load_lds_dwordx4 v132, s[100:101]
	s_waitcnt vmcnt(8)
	s_waitcnt lgkmcnt(0)
	s_barrier
	v_mfma_f32_16x16x32_bf16 v[62:65], v[152:155], v[194:197], v[62:65]
	v_mfma_f32_16x16x32_bf16 v[62:65], v[156:159], v[206:209], v[62:65]
	v_mfma_f32_16x16x32_bf16 v[54:57], v[152:155], v[210:213], v[54:57]
	v_mfma_f32_16x16x32_bf16 v[54:57], v[156:159], v[214:217], v[54:57]
	v_mfma_f32_16x16x32_bf16 v[50:53], v[160:163], v[210:213], v[50:53]
	v_mfma_f32_16x16x32_bf16 v[50:53], v[164:167], v[214:217], v[50:53]
	v_mfma_f32_16x16x32_bf16 v[58:61], v[160:163], v[194:197], v[58:61]
	v_mfma_f32_16x16x32_bf16 v[58:61], v[164:167], v[206:209], v[58:61]
	v_mfma_f32_16x16x32_bf16 v[42:45], v[160:163], v[218:221], v[42:45]
	v_mfma_f32_16x16x32_bf16 v[42:45], v[164:167], v[236:239], v[42:45]
	v_mfma_f32_16x16x32_bf16 v[34:37], v[160:163], v[240:243], v[34:37]
	v_mfma_f32_16x16x32_bf16 v[34:37], v[164:167], v[244:247], v[34:37]
	v_mfma_f32_16x16x32_bf16 v[38:41], v[152:155], v[240:243], v[38:41]
	v_mfma_f32_16x16x32_bf16 v[38:41], v[156:159], v[244:247], v[38:41]
	v_mfma_f32_16x16x32_bf16 v[46:49], v[152:155], v[218:221], v[46:49]
	v_mfma_f32_16x16x32_bf16 v[46:49], v[156:159], v[236:239], v[46:49]
	v_mfma_f32_16x16x32_bf16 v[30:33], v[168:171], v[194:197], v[30:33]
	v_mfma_f32_16x16x32_bf16 v[30:33], v[172:175], v[206:209], v[30:33]
	v_mfma_f32_16x16x32_bf16 v[22:25], v[168:171], v[210:213], v[22:25]
	v_mfma_f32_16x16x32_bf16 v[22:25], v[172:175], v[214:217], v[22:25]
	v_mfma_f32_16x16x32_bf16 v[18:21], v[176:179], v[210:213], v[18:21]
	v_mfma_f32_16x16x32_bf16 v[18:21], v[180:183], v[214:217], v[18:21]
	v_mfma_f32_16x16x32_bf16 v[26:29], v[176:179], v[194:197], v[26:29]
	v_mfma_f32_16x16x32_bf16 v[26:29], v[180:183], v[206:209], v[26:29]
	v_mfma_f32_16x16x32_bf16 v[10:13], v[176:179], v[218:221], v[10:13]
	v_mfma_f32_16x16x32_bf16 v[10:13], v[180:183], v[236:239], v[10:13]
	v_mfma_f32_16x16x32_bf16 v[2:5], v[176:179], v[240:243], v[2:5]
	v_mfma_f32_16x16x32_bf16 v[2:5], v[180:183], v[244:247], v[2:5]
	v_mfma_f32_16x16x32_bf16 v[6:9], v[168:171], v[240:243], v[6:9]
	v_mfma_f32_16x16x32_bf16 v[6:9], v[172:175], v[244:247], v[6:9]
	v_mfma_f32_16x16x32_bf16 v[14:17], v[168:171], v[218:221], v[14:17]
	v_mfma_f32_16x16x32_bf16 v[14:17], v[172:175], v[236:239], v[14:17]
	s_barrier
	s_add_i32 s8, s8, 2
	s_add_u32 s80, s80, 0x100
	s_addc_u32 s81, s81, 0
	s_cmp_gt_u32 s8, 29
	s_cbranch_scc0 .LBB0_1233
	s_and_b64 vcc, exec, s[62:63]
	s_cbranch_vccz .LBB0_1236
	s_barrier
